# static priority: per-phase s_setprio flips deleted in all GEMM K-loops, waves 4-7 get s_setprio 1 for each GEMM phase; on top of v4
# speedup vs baseline: 1.0123x; 1.0123x over previous
.LBB0_147:
	s_or_b64 exec, exec, s[0:1]
	v_readfirstlane_b32 s98, v202
	s_nop 3
	s_lshr_b32 s98, s98, 8
	s_cmp_eq_u32 s98, 1
	s_cbranch_scc0 .Lprio_skip_0
	s_setprio 1
.Lprio_skip_0:
	v_readlane_b32 s0, v248, 10
	s_ashr_i32 s0, s0, 31
	v_readlane_b32 s1, v248, 11
	v_writelane_b32 v247, s0, 11
	s_ashr_i32 s0, s42, 31
	v_writelane_b32 v247, s0, 8
	s_add_u32 s0, s58, 0x12900000
	s_addc_u32 s1, s59, 0
	v_writelane_b32 v247, s0, 9
	v_mov_b32_e32 v8, v202
	s_waitcnt lgkmcnt(0)
	v_writelane_b32 v247, s1, 10
	s_add_u32 s0, s58, 0x17100000
	s_addc_u32 s1, s59, 0
	s_barrier
	s_cmpk_lt_i32 s42, 0x360
	v_writelane_b32 v248, s0, 63
	v_readfirstlane_b32 s22, v8
	s_nop 0
	v_writelane_b32 v247, s1, 0
	s_cbranch_scc0 .LBB0_159
	v_lshlrev_b32_e32 v0, 4, v8
	v_add_u32_e32 v1, 0x2000, v0
	v_readlane_b32 s1, v247, 8
	v_ashrrev_i32_e32 v2, 31, v1
	s_lshr_b32 s1, s1, 29
	v_lshrrev_b32_e32 v2, 22, v2
	s_add_i32 s1, s42, s1
	v_add_u32_e32 v2, v1, v2
	s_ashr_i32 s0, s22, 6
	s_ashr_i32 s2, s1, 3
	s_and_b32 s1, s1, -8
	v_ashrrev_i32_e32 v9, 10, v2
	s_ashr_i32 s3, s22, 8
	s_lshl_b32 s23, s0, 10
	s_sub_i32 s1, s42, s1
	v_mul_i32_i24_e32 v2, 0x400, v9
	s_cmp_lt_i32 s1, 0
	s_movk_i32 s24, 0x6d
	v_sub_u32_e32 v1, v1, v2
	s_cselect_b32 s6, s24, 0x6c
	v_lshrrev_b32_e32 v2, 4, v1
	s_mul_i32 s1, s6, s1
	v_bitop3_b32 v1, v2, v1, 32 bitop3:0x6c
	s_add_i32 s1, s1, s2
	v_ashrrev_i32_e32 v2, 31, v1
	s_mul_hi_i32 s2, s1, 0x2aaaaaab
	v_lshrrev_b32_e32 v2, 26, v2
	s_lshr_b32 s6, s2, 31
	s_ashr_i32 s2, s2, 5
	v_add_u32_e32 v2, v1, v2
	v_lshlrev_b32_e32 v3, 3, v9
	s_add_i32 s2, s2, s6
	v_ashrrev_i32_e32 v10, 6, v2
	v_and_b32_e32 v3, -16, v3
	s_lshl_b32 s8, s2, 3
	s_mulk_i32 s2, 0xc0
	v_add_u32_e32 v3, v10, v3
	s_sub_i32 s1, s1, s2
	v_and_b32_e32 v4, 3, v10
	s_mov_b32 s2, 0xfffe0
	v_lshrrev_b32_e32 v5, 2, v3
	v_lshlrev_b32_e32 v6, 1, v3
	v_and_b32_e32 v2, 0xc0, v2
	v_and_or_b32 v4, v3, s2, v4
	v_and_b32_e32 v5, 4, v5
	v_and_b32_e32 v6, 24, v6
	v_sub_u32_e32 v1, v1, v2
	v_mov_b32_e32 v2, 1
	v_or3_b32 v4, v4, v5, v6
	v_lshlrev_b32_e32 v5, 5, v9
	v_ashrrev_i16_sdwa v1, v2, sext(v1) dst_sel:DWORD dst_unused:UNUSED_PAD src0_sel:DWORD src1_sel:BYTE_0
	v_and_b32_e32 v5, 32, v5
	v_bfe_i32 v11, v1, 0, 16
	v_add_lshl_u32 v1, v5, v11, 1
	v_lshl_add_u32 v128, v4, 12, v1
	v_lshl_add_u32 v130, v3, 12, v1
	v_bfe_i32 v1, v8, 27, 1
	v_lshrrev_b32_e32 v1, 22, v1
	v_add_u32_e32 v1, v0, v1
	v_and_b32_e32 v1, 0xfffffc00, v1
	v_sub_u32_e32 v0, v0, v1
	v_lshrrev_b32_e32 v1, 4, v0
	v_ashrrev_i32_e32 v3, 31, v8
	v_bitop3_b32 v0, v1, v0, 32 bitop3:0x6c
	v_lshrrev_b32_e32 v3, 26, v3
	v_ashrrev_i32_e32 v1, 31, v0
	v_add_u32_e32 v3, v8, v3
	v_lshrrev_b32_e32 v1, 26, v1
	v_ashrrev_i32_e32 v13, 6, v3
	v_add_u32_e32 v1, v0, v1
	v_lshlrev_b32_e32 v3, 3, v13
	v_ashrrev_i32_e32 v12, 6, v1
	v_and_b32_e32 v3, -16, v3
	v_add_u32_e32 v3, v12, v3
	v_and_b32_e32 v4, 3, v12
	v_lshrrev_b32_e32 v5, 2, v3
	v_lshlrev_b32_e32 v6, 1, v3
	v_and_b32_e32 v1, 0xc0, v1
	v_and_or_b32 v4, v3, s2, v4
	v_and_b32_e32 v5, 4, v5
	v_and_b32_e32 v6, 24, v6
	v_sub_u32_e32 v0, v0, v1
	s_sub_i32 s6, 36, s8
	v_or3_b32 v4, v4, v5, v6
	v_lshlrev_b32_e32 v5, 5, v13
	v_ashrrev_i16_sdwa v0, v2, sext(v0) dst_sel:DWORD dst_unused:UNUSED_PAD src0_sel:DWORD src1_sel:BYTE_0
	s_min_u32 s9, s6, 8
	v_and_b32_e32 v5, 32, v5
	v_bfe_i32 v14, v0, 0, 16
	v_add_lshl_u32 v0, v5, v14, 1
	v_cvt_f32_ubyte0_e32 v2, s9
	v_lshl_add_u32 v132, v4, 12, v0
	v_cvt_f32_i32_e32 v1, s1
	v_rcp_iflag_f32_e32 v4, v2
	v_lshl_add_u32 v134, v3, 12, v0
	s_ashr_i32 s2, s1, 30
	s_or_b32 s2, s2, 1
	v_mul_f32_e32 v0, v1, v4
	v_trunc_f32_e32 v0, v0
	v_fma_f32 v1, -v0, v2, v1
	v_cvt_i32_f32_e32 v0, v0
	v_cmp_ge_f32_e64 s[6:7], |v1|, v2
	s_and_b64 s[6:7], s[6:7], exec
	s_cselect_b32 s2, s2, 0
	v_readfirstlane_b32 s6, v0
	s_add_i32 s2, s6, s2
	s_mul_i32 s6, s2, s9
	s_sub_i32 s1, s1, s6
	s_sext_i32_i16 s1, s1
	s_add_i32 s6, s8, s1
	s_ashr_i32 s7, s6, 31
	s_bfe_i64 s[10:11], s[2:3], 0x100000
	s_lshl_b64 s[8:9], s[6:7], 20
	s_lshl_b64 s[10:11], s[10:11], 20
	s_add_u32 s18, s58, s10
	s_addc_u32 s19, s59, s11
	s_add_i32 s7, s23, 0
	s_add_i32 m0, s7, 0x10000
	v_readlane_b32 s10, v247, 9
	v_mov_b32_e32 v230, s3
	v_lshlrev_b32_e32 v230, 17, v230
	v_add_u32_e32 v132, v132, v230
	v_add_u32_e32 v230, 0x40000, v230
	v_add_u32_e32 v128, v128, v230
	global_load_lds_dwordx4 v132, s[18:19]
	s_add_i32 m0, s7, 0x12000
	v_readlane_b32 s11, v247, 10
	s_add_u32 s16, s10, s8
	global_load_lds_dwordx4 v128, s[18:19]
	s_addc_u32 s17, s11, s9
	s_mov_b32 m0, s7
	s_add_i32 s25, s7, 0x2000
	global_load_lds_dwordx4 v134, s[16:17]
	s_mov_b32 m0, s25
	s_add_u32 s8, s18, 0x20000
	global_load_lds_dwordx4 v130, s[16:17]
	s_addc_u32 s9, s19, 0
	s_add_i32 m0, s7, 0x14000
	v_mov_b32_e32 v133, 0
	global_load_lds_dwordx4 v132, s[8:9]
	s_add_i32 m0, s7, 0x16000
	v_mov_b32_e32 v129, v133
	global_load_lds_dwordx4 v128, s[8:9]
	s_add_u32 s8, s16, 0x80000
	s_addc_u32 s9, s17, 0
	s_add_i32 s26, s7, 0x4000
	s_mov_b32 m0, s26
	s_add_i32 s27, s7, 0x6000
	global_load_lds_dwordx4 v134, s[8:9]
	s_mov_b32 m0, s27
	v_mov_b32_e32 v135, v133
	global_load_lds_dwordx4 v130, s[8:9]
	v_mov_b32_e32 v131, v133
	s_mov_b32 s28, 0
	v_lshl_add_u64 v[6:7], s[18:19], 0, v[132:133]
	v_lshl_add_u64 v[4:5], s[18:19], 0, v[128:129]
	v_lshl_add_u64 v[2:3], s[16:17], 0, v[134:135]
	s_cmp_lg_u32 s3, 1
	v_lshl_add_u64 v[0:1], s[16:17], 0, v[130:131]
	s_cbranch_scc1 .LBB0_150
	s_barrier

.LBB0_154:
	ds_read_b128 v[150:153], v147
	ds_read_b128 v[154:157], v147 offset:1024
	ds_read_b128 v[158:161], v147 offset:2048
	ds_read_b128 v[162:165], v147 offset:3072
	s_add_u32 s18, s16, 0xfff80080
	s_addc_u32 s19, s17, -1
	s_cmp_eq_u32 s40, 28
	s_cselect_b32 s21, s11, s19
	s_cselect_b32 s20, s36, s18
	s_cselect_b32 s19, s9, s39
	s_cselect_b32 s18, s37, s38
	v_lshl_add_u64 v[198:199], s[16:17], 0, v[136:137]
	s_add_i32 m0, s7, 0xc000
	ds_read_b128 v[166:169], v148
	ds_read_b128 v[170:173], v148 offset:1024
	ds_read_b128 v[174:177], v148 offset:2048
	ds_read_b128 v[178:181], v148 offset:3072
	ds_read_b128 v[182:185], v148 offset:4096
	ds_read_b128 v[186:189], v148 offset:5120
	ds_read_b128 v[190:193], v148 offset:6144
	ds_read_b128 v[194:197], v148 offset:7168
	global_load_lds_dwordx4 v[198:199], off
	v_lshl_add_u64 v[198:199], s[16:17], 0, v[138:139]
	s_add_i32 m0, s7, 0xe000
	s_nop 0
	global_load_lds_dwordx4 v[198:199], off
	s_waitcnt lgkmcnt(8)
	s_barrier
	s_waitcnt lgkmcnt(0)
	s_waitcnt lgkmcnt(0)
	v_mfma_f32_16x16x32_bf16 v[124:127], v[150:153], v[166:169], v[124:127]
	v_mfma_f32_16x16x32_bf16 v[120:123], v[158:161], v[166:169], v[120:123]
	v_mfma_f32_16x16x32_bf16 v[116:119], v[150:153], v[174:177], v[116:119]
	v_mfma_f32_16x16x32_bf16 v[112:115], v[158:161], v[174:177], v[112:115]
	v_mfma_f32_16x16x32_bf16 v[100:103], v[150:153], v[182:185], v[100:103]
	v_mfma_f32_16x16x32_bf16 v[96:99], v[158:161], v[182:185], v[96:99]
	v_mfma_f32_16x16x32_bf16 v[84:87], v[150:153], v[190:193], v[84:87]
	v_mfma_f32_16x16x32_bf16 v[80:83], v[158:161], v[190:193], v[80:83]
	v_mfma_f32_16x16x32_bf16 v[124:127], v[154:157], v[170:173], v[124:127]
	v_mfma_f32_16x16x32_bf16 v[120:123], v[162:165], v[170:173], v[120:123]
	v_mfma_f32_16x16x32_bf16 v[116:119], v[154:157], v[178:181], v[116:119]
	v_mfma_f32_16x16x32_bf16 v[112:115], v[162:165], v[178:181], v[112:115]
	v_mfma_f32_16x16x32_bf16 v[100:103], v[154:157], v[186:189], v[100:103]
	v_mfma_f32_16x16x32_bf16 v[96:99], v[162:165], v[186:189], v[96:99]
	v_mfma_f32_16x16x32_bf16 v[84:87], v[154:157], v[194:197], v[84:87]
	v_mfma_f32_16x16x32_bf16 v[80:83], v[162:165], v[194:197], v[80:83]
	s_barrier
	s_add_i32 s41, s31, s23
	v_lshl_add_u64 v[216:217], s[18:19], 0, v[132:133]
	s_mov_b32 m0, s41
	ds_read_b128 v[198:201], v149
	ds_read_b128 v[204:207], v149 offset:1024
	ds_read_b128 v[208:211], v149 offset:2048
	ds_read_b128 v[212:215], v149 offset:3072
	global_load_lds_dwordx4 v[216:217], off
	v_lshl_add_u64 v[218:219], s[18:19], 0, v[128:129]
	s_add_i32 m0, s41, 0x2000
	s_nop 0
	global_load_lds_dwordx4 v[218:219], off
	s_barrier
	s_waitcnt lgkmcnt(0)
	s_waitcnt lgkmcnt(0)
	v_mfma_f32_16x16x32_bf16 v[108:111], v[198:201], v[166:169], v[108:111]
	v_mfma_f32_16x16x32_bf16 v[104:107], v[208:211], v[166:169], v[104:107]
	v_mfma_f32_16x16x32_bf16 v[92:95], v[198:201], v[174:177], v[92:95]
	v_mfma_f32_16x16x32_bf16 v[88:91], v[208:211], v[174:177], v[88:91]
	v_mfma_f32_16x16x32_bf16 v[76:79], v[198:201], v[182:185], v[76:79]
	v_mfma_f32_16x16x32_bf16 v[72:75], v[208:211], v[182:185], v[72:75]
	v_mfma_f32_16x16x32_bf16 v[68:71], v[198:201], v[190:193], v[68:71]
	v_mfma_f32_16x16x32_bf16 v[64:67], v[208:211], v[190:193], v[64:67]
	v_mfma_f32_16x16x32_bf16 v[108:111], v[204:207], v[170:173], v[108:111]
	v_mfma_f32_16x16x32_bf16 v[104:107], v[212:215], v[170:173], v[104:107]
	v_mfma_f32_16x16x32_bf16 v[92:95], v[204:207], v[178:181], v[92:95]
	v_mfma_f32_16x16x32_bf16 v[88:91], v[212:215], v[178:181], v[88:91]
	v_mfma_f32_16x16x32_bf16 v[76:79], v[204:207], v[186:189], v[76:79]
	v_mfma_f32_16x16x32_bf16 v[72:75], v[212:215], v[186:189], v[72:75]
	v_mfma_f32_16x16x32_bf16 v[68:71], v[204:207], v[194:197], v[68:71]
	v_mfma_f32_16x16x32_bf16 v[64:67], v[212:215], v[194:197], v[64:67]
	s_mov_b32 m0, s7
	v_lshl_add_u64 v[220:221], s[20:21], 0, v[134:135]
	s_barrier
	ds_read_b128 v[166:169], v148 offset:16384
	ds_read_b128 v[170:173], v148 offset:17408
	ds_read_b128 v[174:177], v148 offset:18432
	ds_read_b128 v[178:181], v148 offset:19456
	ds_read_b128 v[182:185], v148 offset:20480
	ds_read_b128 v[186:189], v148 offset:21504
	ds_read_b128 v[190:193], v148 offset:22528
	ds_read_b128 v[194:197], v148 offset:23552
	global_load_lds_dwordx4 v[220:221], off
	v_lshl_add_u64 v[222:223], s[20:21], 0, v[130:131]
	s_mov_b32 m0, s25
	s_nop 0
	global_load_lds_dwordx4 v[222:223], off
	s_barrier
	s_waitcnt lgkmcnt(0)
	s_waitcnt lgkmcnt(0)
	v_mfma_f32_16x16x32_bf16 v[60:63], v[150:153], v[166:169], v[60:63]
	v_mfma_f32_16x16x32_bf16 v[56:59], v[158:161], v[166:169], v[56:59]
	v_mfma_f32_16x16x32_bf16 v[52:55], v[150:153], v[174:177], v[52:55]
	v_mfma_f32_16x16x32_bf16 v[48:51], v[158:161], v[174:177], v[48:51]
	v_mfma_f32_16x16x32_bf16 v[36:39], v[150:153], v[182:185], v[36:39]
	v_mfma_f32_16x16x32_bf16 v[32:35], v[158:161], v[182:185], v[32:35]
	v_mfma_f32_16x16x32_bf16 v[20:23], v[150:153], v[190:193], v[20:23]
	v_mfma_f32_16x16x32_bf16 v[16:19], v[158:161], v[190:193], v[16:19]
	v_mfma_f32_16x16x32_bf16 v[60:63], v[154:157], v[170:173], v[60:63]
	v_mfma_f32_16x16x32_bf16 v[56:59], v[162:165], v[170:173], v[56:59]
	v_mfma_f32_16x16x32_bf16 v[52:55], v[154:157], v[178:181], v[52:55]
	v_mfma_f32_16x16x32_bf16 v[48:51], v[162:165], v[178:181], v[48:51]
	v_mfma_f32_16x16x32_bf16 v[36:39], v[154:157], v[186:189], v[36:39]
	v_mfma_f32_16x16x32_bf16 v[32:35], v[162:165], v[186:189], v[32:35]
	v_mfma_f32_16x16x32_bf16 v[20:23], v[154:157], v[194:197], v[20:23]
	v_mfma_f32_16x16x32_bf16 v[16:19], v[162:165], v[194:197], v[16:19]
	s_barrier
	s_add_u32 s42, s18, 0x20000
	s_addc_u32 s43, s19, 0
	s_add_i32 s41, s33, s23
	v_lshl_add_u64 v[150:151], s[42:43], 0, v[132:133]
	s_mov_b32 m0, s41
	s_nop 0
	global_load_lds_dwordx4 v[150:151], off
	v_lshl_add_u64 v[150:151], s[42:43], 0, v[128:129]
	s_add_i32 m0, s41, 0x2000
	s_nop 0
	global_load_lds_dwordx4 v[150:151], off
	s_waitcnt vmcnt(6)
	s_barrier
	v_mfma_f32_16x16x32_bf16 v[44:47], v[198:201], v[166:169], v[44:47]
	v_mfma_f32_16x16x32_bf16 v[40:43], v[208:211], v[166:169], v[40:43]
	v_mfma_f32_16x16x32_bf16 v[28:31], v[198:201], v[174:177], v[28:31]
	v_mfma_f32_16x16x32_bf16 v[24:27], v[208:211], v[174:177], v[24:27]
	v_mfma_f32_16x16x32_bf16 v[12:15], v[198:201], v[182:185], v[12:15]
	v_mfma_f32_16x16x32_bf16 v[8:11], v[208:211], v[182:185], v[8:11]
	v_mfma_f32_16x16x32_bf16 v[4:7], v[198:201], v[190:193], v[4:7]
	v_mfma_f32_16x16x32_bf16 v[0:3], v[208:211], v[190:193], v[0:3]
	v_mfma_f32_16x16x32_bf16 v[44:47], v[204:207], v[170:173], v[44:47]
	v_mfma_f32_16x16x32_bf16 v[40:43], v[212:215], v[170:173], v[40:43]
	v_mfma_f32_16x16x32_bf16 v[28:31], v[204:207], v[178:181], v[28:31]
	v_mfma_f32_16x16x32_bf16 v[24:27], v[212:215], v[178:181], v[24:27]
	v_mfma_f32_16x16x32_bf16 v[12:15], v[204:207], v[186:189], v[12:15]
	v_mfma_f32_16x16x32_bf16 v[8:11], v[212:215], v[186:189], v[8:11]
	v_mfma_f32_16x16x32_bf16 v[4:7], v[204:207], v[194:197], v[4:7]
	v_mfma_f32_16x16x32_bf16 v[0:3], v[212:215], v[194:197], v[0:3]
	s_add_i32 s41, 0, 0x18000
	v_add_u32_e32 v162, s41, v145
	s_barrier
	ds_read_b128 v[150:153], v162
	ds_read_b128 v[154:157], v162 offset:1024
	ds_read_b128 v[158:161], v162 offset:2048
	ds_read_b128 v[162:165], v162 offset:3072
	s_add_u32 s20, s20, 0x80000
	s_addc_u32 s21, s21, 0
	s_mov_b32 m0, s26
	v_lshl_add_u64 v[198:199], s[20:21], 0, v[134:135]
	ds_read_b128 v[166:169], v148 offset:32768
	ds_read_b128 v[170:173], v148 offset:33792
	ds_read_b128 v[174:177], v148 offset:34816
	ds_read_b128 v[178:181], v148 offset:35840
	ds_read_b128 v[182:185], v148 offset:36864
	ds_read_b128 v[186:189], v148 offset:37888
	ds_read_b128 v[190:193], v148 offset:38912
	ds_read_b128 v[194:197], v148 offset:39936
	global_load_lds_dwordx4 v[198:199], off
	v_lshl_add_u64 v[198:199], s[20:21], 0, v[130:131]
	s_mov_b32 m0, s27
	s_nop 0
	global_load_lds_dwordx4 v[198:199], off
	s_waitcnt lgkmcnt(8)
	s_barrier
	s_waitcnt lgkmcnt(0)
	s_waitcnt lgkmcnt(0)
	v_mfma_f32_16x16x32_bf16 v[124:127], v[150:153], v[166:169], v[124:127]
	v_mfma_f32_16x16x32_bf16 v[120:123], v[158:161], v[166:169], v[120:123]
	v_mfma_f32_16x16x32_bf16 v[116:119], v[150:153], v[174:177], v[116:119]
	v_mfma_f32_16x16x32_bf16 v[112:115], v[158:161], v[174:177], v[112:115]
	v_mfma_f32_16x16x32_bf16 v[100:103], v[150:153], v[182:185], v[100:103]
	v_mfma_f32_16x16x32_bf16 v[96:99], v[158:161], v[182:185], v[96:99]
	v_mfma_f32_16x16x32_bf16 v[84:87], v[150:153], v[190:193], v[84:87]
	v_mfma_f32_16x16x32_bf16 v[80:83], v[158:161], v[190:193], v[80:83]
	v_mfma_f32_16x16x32_bf16 v[124:127], v[154:157], v[170:173], v[124:127]
	v_mfma_f32_16x16x32_bf16 v[120:123], v[162:165], v[170:173], v[120:123]
	v_mfma_f32_16x16x32_bf16 v[116:119], v[154:157], v[178:181], v[116:119]
	v_mfma_f32_16x16x32_bf16 v[112:115], v[162:165], v[178:181], v[112:115]
	v_mfma_f32_16x16x32_bf16 v[100:103], v[154:157], v[186:189], v[100:103]
	v_mfma_f32_16x16x32_bf16 v[96:99], v[162:165], v[186:189], v[96:99]
	v_mfma_f32_16x16x32_bf16 v[84:87], v[154:157], v[194:197], v[84:87]
	v_mfma_f32_16x16x32_bf16 v[80:83], v[162:165], v[194:197], v[80:83]
	s_barrier
	s_add_i32 s20, 0, 0x1c000
	s_add_i32 s21, s41, s23
	v_add_u32_e32 v212, s20, v145
	v_lshl_add_u64 v[216:217], v[216:217], 0, s[0:1]
	s_mov_b32 m0, s21
	ds_read_b128 v[198:201], v212
	ds_read_b128 v[204:207], v212 offset:1024
	ds_read_b128 v[208:211], v212 offset:2048
	ds_read_b128 v[212:215], v212 offset:3072
	global_load_lds_dwordx4 v[216:217], off
	v_lshl_add_u64 v[216:217], v[218:219], 0, s[0:1]
	s_add_i32 m0, s21, 0x2000
	s_nop 0
	global_load_lds_dwordx4 v[216:217], off
	s_barrier
	s_waitcnt lgkmcnt(0)
	s_waitcnt lgkmcnt(0)
	v_mfma_f32_16x16x32_bf16 v[108:111], v[198:201], v[166:169], v[108:111]
	v_mfma_f32_16x16x32_bf16 v[104:107], v[208:211], v[166:169], v[104:107]
	v_mfma_f32_16x16x32_bf16 v[92:95], v[198:201], v[174:177], v[92:95]
	v_mfma_f32_16x16x32_bf16 v[88:91], v[208:211], v[174:177], v[88:91]
	v_mfma_f32_16x16x32_bf16 v[76:79], v[198:201], v[182:185], v[76:79]
	v_mfma_f32_16x16x32_bf16 v[72:75], v[208:211], v[182:185], v[72:75]
	v_mfma_f32_16x16x32_bf16 v[68:71], v[198:201], v[190:193], v[68:71]
	v_mfma_f32_16x16x32_bf16 v[64:67], v[208:211], v[190:193], v[64:67]
	v_mfma_f32_16x16x32_bf16 v[108:111], v[204:207], v[170:173], v[108:111]
	v_mfma_f32_16x16x32_bf16 v[104:107], v[212:215], v[170:173], v[104:107]
	v_mfma_f32_16x16x32_bf16 v[92:95], v[204:207], v[178:181], v[92:95]
	v_mfma_f32_16x16x32_bf16 v[88:91], v[212:215], v[178:181], v[88:91]
	v_mfma_f32_16x16x32_bf16 v[76:79], v[204:207], v[186:189], v[76:79]
	v_mfma_f32_16x16x32_bf16 v[72:75], v[212:215], v[186:189], v[72:75]
	v_mfma_f32_16x16x32_bf16 v[68:71], v[204:207], v[194:197], v[68:71]
	v_mfma_f32_16x16x32_bf16 v[64:67], v[212:215], v[194:197], v[64:67]
	s_mov_b32 m0, s29
	v_lshl_add_u64 v[216:217], v[220:221], 0, s[0:1]
	s_barrier
	ds_read_b128 v[166:169], v148 offset:49152
	ds_read_b128 v[170:173], v148 offset:50176
	ds_read_b128 v[174:177], v148 offset:51200
	ds_read_b128 v[178:181], v148 offset:52224
	ds_read_b128 v[182:185], v148 offset:53248
	ds_read_b128 v[186:189], v148 offset:54272
	ds_read_b128 v[190:193], v148 offset:55296
	ds_read_b128 v[194:197], v148 offset:56320
	global_load_lds_dwordx4 v[216:217], off
	v_lshl_add_u64 v[216:217], v[222:223], 0, s[0:1]
	s_mov_b32 m0, s30
	s_nop 0
	global_load_lds_dwordx4 v[216:217], off
	s_barrier
	s_waitcnt lgkmcnt(0)
	s_waitcnt lgkmcnt(0)
	v_mfma_f32_16x16x32_bf16 v[60:63], v[150:153], v[166:169], v[60:63]
	v_mfma_f32_16x16x32_bf16 v[56:59], v[158:161], v[166:169], v[56:59]
	v_mfma_f32_16x16x32_bf16 v[52:55], v[150:153], v[174:177], v[52:55]
	v_mfma_f32_16x16x32_bf16 v[48:51], v[158:161], v[174:177], v[48:51]
	v_mfma_f32_16x16x32_bf16 v[36:39], v[150:153], v[182:185], v[36:39]
	v_mfma_f32_16x16x32_bf16 v[32:35], v[158:161], v[182:185], v[32:35]
	v_mfma_f32_16x16x32_bf16 v[20:23], v[150:153], v[190:193], v[20:23]
	v_mfma_f32_16x16x32_bf16 v[16:19], v[158:161], v[190:193], v[16:19]
	v_mfma_f32_16x16x32_bf16 v[60:63], v[154:157], v[170:173], v[60:63]
	v_mfma_f32_16x16x32_bf16 v[56:59], v[162:165], v[170:173], v[56:59]
	v_mfma_f32_16x16x32_bf16 v[52:55], v[154:157], v[178:181], v[52:55]
	v_mfma_f32_16x16x32_bf16 v[48:51], v[162:165], v[178:181], v[48:51]
	v_mfma_f32_16x16x32_bf16 v[36:39], v[154:157], v[186:189], v[36:39]
	v_mfma_f32_16x16x32_bf16 v[32:35], v[162:165], v[186:189], v[32:35]
	v_mfma_f32_16x16x32_bf16 v[20:23], v[154:157], v[194:197], v[20:23]
	v_mfma_f32_16x16x32_bf16 v[16:19], v[162:165], v[194:197], v[16:19]
	s_barrier
	s_add_u32 s18, s18, 0x20080
	s_addc_u32 s19, s19, 0
	s_add_i32 s20, s20, s23
	v_lshl_add_u64 v[150:151], s[18:19], 0, v[132:133]
	s_mov_b32 m0, s20
	s_nop 0
	global_load_lds_dwordx4 v[150:151], off
	v_lshl_add_u64 v[150:151], s[18:19], 0, v[128:129]
	s_add_i32 m0, s20, 0x2000
	s_nop 0
	global_load_lds_dwordx4 v[150:151], off
	s_waitcnt vmcnt(6)
	s_barrier
	v_mfma_f32_16x16x32_bf16 v[44:47], v[198:201], v[166:169], v[44:47]
	v_mfma_f32_16x16x32_bf16 v[40:43], v[208:211], v[166:169], v[40:43]
	v_mfma_f32_16x16x32_bf16 v[28:31], v[198:201], v[174:177], v[28:31]
	v_mfma_f32_16x16x32_bf16 v[24:27], v[208:211], v[174:177], v[24:27]
	v_mfma_f32_16x16x32_bf16 v[12:15], v[198:201], v[182:185], v[12:15]
	v_mfma_f32_16x16x32_bf16 v[8:11], v[208:211], v[182:185], v[8:11]
	v_mfma_f32_16x16x32_bf16 v[4:7], v[198:201], v[190:193], v[4:7]
	v_mfma_f32_16x16x32_bf16 v[0:3], v[208:211], v[190:193], v[0:3]
	v_mfma_f32_16x16x32_bf16 v[44:47], v[204:207], v[170:173], v[44:47]
	v_mfma_f32_16x16x32_bf16 v[40:43], v[212:215], v[170:173], v[40:43]
	v_mfma_f32_16x16x32_bf16 v[28:31], v[204:207], v[178:181], v[28:31]
	v_mfma_f32_16x16x32_bf16 v[24:27], v[212:215], v[178:181], v[24:27]
	v_mfma_f32_16x16x32_bf16 v[12:15], v[204:207], v[186:189], v[12:15]
	v_mfma_f32_16x16x32_bf16 v[8:11], v[212:215], v[186:189], v[8:11]
	v_mfma_f32_16x16x32_bf16 v[4:7], v[204:207], v[194:197], v[4:7]
	v_mfma_f32_16x16x32_bf16 v[0:3], v[212:215], v[194:197], v[0:3]
	s_add_i32 s40, s40, 2
	s_add_u32 s16, s16, 0x100
	s_addc_u32 s17, s17, 0
	s_add_u32 s38, s38, 0x100
	s_addc_u32 s39, s39, 0
	s_cmp_gt_u32 s40, 29
	s_barrier
	s_cbranch_scc0 .LBB0_154
	v_readlane_b32 s100, v248, 63
	v_readlane_b32 s101, v247, 0
	v_and_b32_e32 v242, 15, v202
	v_bfe_u32 v243, v202, 4, 2
	v_bfe_u32 v244, v202, 6, 2
	v_lshrrev_b32_e32 v245, 8, v202
	v_and_b32_e32 v240, 7, v242
	v_lshl_add_u32 v240, v245, 6, v240
	v_lshl_add_u32 v240, s6, 8, v240
	v_mul_u32_u24_e32 v240, 0x3000, v240
	v_lshrrev_b32_e32 v241, 3, v242
	v_lshlrev_b32_e32 v241, 6, v241
	v_lshl_add_u32 v241, v244, 7, v241
	v_lshl_add_u32 v241, v243, 4, v241
	v_add_u32_e32 v240, v240, v241
	s_lshl_b32 s98, s35, 9
	v_add_u32_e32 v240, s98, v240
	v_cvt_pk_bf16_f32 v228, v124, v125
	v_cvt_pk_bf16_f32 v229, v126, v127
	v_cvt_pk_bf16_f32 v230, v120, v121
	v_cvt_pk_bf16_f32 v231, v122, v123
	v_cvt_pk_bf16_f32 v232, v108, v109
	v_cvt_pk_bf16_f32 v233, v110, v111
	v_cvt_pk_bf16_f32 v234, v104, v105
	v_cvt_pk_bf16_f32 v235, v106, v107
	v_mov_b32_e32 v236, v228
	v_mov_b32_e32 v237, v229
	v_mov_b32_e32 v238, v230
	v_mov_b32_e32 v239, v231
	v_mov_b32_dpp v228, v232 row_ror:8 row_mask:0xf bank_mask:0xc
	v_mov_b32_dpp v229, v233 row_ror:8 row_mask:0xf bank_mask:0xc
	v_mov_b32_dpp v230, v234 row_ror:8 row_mask:0xf bank_mask:0xc
	v_mov_b32_dpp v231, v235 row_ror:8 row_mask:0xf bank_mask:0xc
	v_mov_b32_dpp v232, v236 row_ror:8 row_mask:0xf bank_mask:0x3
	v_mov_b32_dpp v233, v237 row_ror:8 row_mask:0xf bank_mask:0x3
	v_mov_b32_dpp v234, v238 row_ror:8 row_mask:0xf bank_mask:0x3
	v_mov_b32_dpp v235, v239 row_ror:8 row_mask:0xf bank_mask:0x3
	global_store_dwordx4 v240, v[228:231], s[100:101]
	s_add_u32 s100, s100, 0x18000
	s_addc_u32 s101, s101, 0
	global_store_dwordx4 v240, v[232:235], s[100:101]
	v_cvt_pk_bf16_f32 v228, v116, v117
	v_cvt_pk_bf16_f32 v229, v118, v119
	v_cvt_pk_bf16_f32 v230, v112, v113
	v_cvt_pk_bf16_f32 v231, v114, v115
	v_cvt_pk_bf16_f32 v232, v92, v93
	v_cvt_pk_bf16_f32 v233, v94, v95
	v_cvt_pk_bf16_f32 v234, v88, v89
	v_cvt_pk_bf16_f32 v235, v90, v91
	v_mov_b32_e32 v236, v228
	v_mov_b32_e32 v237, v229
	v_mov_b32_e32 v238, v230
	v_mov_b32_e32 v239, v231
	v_mov_b32_dpp v228, v232 row_ror:8 row_mask:0xf bank_mask:0xc
	v_mov_b32_dpp v229, v233 row_ror:8 row_mask:0xf bank_mask:0xc
	v_mov_b32_dpp v230, v234 row_ror:8 row_mask:0xf bank_mask:0xc
	v_mov_b32_dpp v231, v235 row_ror:8 row_mask:0xf bank_mask:0xc
	v_mov_b32_dpp v232, v236 row_ror:8 row_mask:0xf bank_mask:0x3
	v_mov_b32_dpp v233, v237 row_ror:8 row_mask:0xf bank_mask:0x3
	v_mov_b32_dpp v234, v238 row_ror:8 row_mask:0xf bank_mask:0x3
	v_mov_b32_dpp v235, v239 row_ror:8 row_mask:0xf bank_mask:0x3
	s_add_u32 s100, s100, 0x18000
	s_addc_u32 s101, s101, 0
	global_store_dwordx4 v240, v[228:231], s[100:101]
	s_add_u32 s100, s100, 0x18000
	s_addc_u32 s101, s101, 0
	global_store_dwordx4 v240, v[232:235], s[100:101]
	v_cvt_pk_bf16_f32 v228, v100, v101
	v_cvt_pk_bf16_f32 v229, v102, v103
	v_cvt_pk_bf16_f32 v230, v96, v97
	v_cvt_pk_bf16_f32 v231, v98, v99
	v_cvt_pk_bf16_f32 v232, v76, v77
	v_cvt_pk_bf16_f32 v233, v78, v79
	v_cvt_pk_bf16_f32 v234, v72, v73
	v_cvt_pk_bf16_f32 v235, v74, v75
	v_mov_b32_e32 v236, v228
	v_mov_b32_e32 v237, v229
	v_mov_b32_e32 v238, v230
	v_mov_b32_e32 v239, v231
	v_mov_b32_dpp v228, v232 row_ror:8 row_mask:0xf bank_mask:0xc
	v_mov_b32_dpp v229, v233 row_ror:8 row_mask:0xf bank_mask:0xc
	v_mov_b32_dpp v230, v234 row_ror:8 row_mask:0xf bank_mask:0xc
	v_mov_b32_dpp v231, v235 row_ror:8 row_mask:0xf bank_mask:0xc
	v_mov_b32_dpp v232, v236 row_ror:8 row_mask:0xf bank_mask:0x3
	v_mov_b32_dpp v233, v237 row_ror:8 row_mask:0xf bank_mask:0x3
	v_mov_b32_dpp v234, v238 row_ror:8 row_mask:0xf bank_mask:0x3
	v_mov_b32_dpp v235, v239 row_ror:8 row_mask:0xf bank_mask:0x3
	s_add_u32 s100, s100, 0x18000
	s_addc_u32 s101, s101, 0
	global_store_dwordx4 v240, v[228:231], s[100:101]
	s_add_u32 s100, s100, 0x18000
	s_addc_u32 s101, s101, 0
	global_store_dwordx4 v240, v[232:235], s[100:101]
	v_cvt_pk_bf16_f32 v228, v84, v85
	v_cvt_pk_bf16_f32 v229, v86, v87
	v_cvt_pk_bf16_f32 v230, v80, v81
	v_cvt_pk_bf16_f32 v231, v82, v83
	v_cvt_pk_bf16_f32 v232, v68, v69
	v_cvt_pk_bf16_f32 v233, v70, v71
	v_cvt_pk_bf16_f32 v234, v64, v65
	v_cvt_pk_bf16_f32 v235, v66, v67
	v_mov_b32_e32 v236, v228
	v_mov_b32_e32 v237, v229
	v_mov_b32_e32 v238, v230
	v_mov_b32_e32 v239, v231
	v_mov_b32_dpp v228, v232 row_ror:8 row_mask:0xf bank_mask:0xc
	v_mov_b32_dpp v229, v233 row_ror:8 row_mask:0xf bank_mask:0xc
	v_mov_b32_dpp v230, v234 row_ror:8 row_mask:0xf bank_mask:0xc
	v_mov_b32_dpp v231, v235 row_ror:8 row_mask:0xf bank_mask:0xc
	v_mov_b32_dpp v232, v236 row_ror:8 row_mask:0xf bank_mask:0x3
	v_mov_b32_dpp v233, v237 row_ror:8 row_mask:0xf bank_mask:0x3
	v_mov_b32_dpp v234, v238 row_ror:8 row_mask:0xf bank_mask:0x3
	v_mov_b32_dpp v235, v239 row_ror:8 row_mask:0xf bank_mask:0x3
	s_add_u32 s100, s100, 0x18000
	s_addc_u32 s101, s101, 0
	global_store_dwordx4 v240, v[228:231], s[100:101]
	s_add_u32 s100, s100, 0x18000
	s_addc_u32 s101, s101, 0
	global_store_dwordx4 v240, v[232:235], s[100:101]
	v_cvt_pk_bf16_f32 v228, v60, v61
	v_cvt_pk_bf16_f32 v229, v62, v63
	v_cvt_pk_bf16_f32 v230, v56, v57
	v_cvt_pk_bf16_f32 v231, v58, v59
	v_cvt_pk_bf16_f32 v232, v44, v45
	v_cvt_pk_bf16_f32 v233, v46, v47
	v_cvt_pk_bf16_f32 v234, v40, v41
	v_cvt_pk_bf16_f32 v235, v42, v43
	v_mov_b32_e32 v236, v228
	v_mov_b32_e32 v237, v229
	v_mov_b32_e32 v238, v230
	v_mov_b32_e32 v239, v231
	v_mov_b32_dpp v228, v232 row_ror:8 row_mask:0xf bank_mask:0xc
	v_mov_b32_dpp v229, v233 row_ror:8 row_mask:0xf bank_mask:0xc
	v_mov_b32_dpp v230, v234 row_ror:8 row_mask:0xf bank_mask:0xc
	v_mov_b32_dpp v231, v235 row_ror:8 row_mask:0xf bank_mask:0xc
	v_mov_b32_dpp v232, v236 row_ror:8 row_mask:0xf bank_mask:0x3
	v_mov_b32_dpp v233, v237 row_ror:8 row_mask:0xf bank_mask:0x3
	v_mov_b32_dpp v234, v238 row_ror:8 row_mask:0xf bank_mask:0x3
	v_mov_b32_dpp v235, v239 row_ror:8 row_mask:0xf bank_mask:0x3
	s_add_u32 s100, s100, 0xd8000
	s_addc_u32 s101, s101, 0
	global_store_dwordx4 v240, v[228:231], s[100:101]
	s_add_u32 s100, s100, 0x18000
	s_addc_u32 s101, s101, 0
	global_store_dwordx4 v240, v[232:235], s[100:101]
	v_cvt_pk_bf16_f32 v228, v52, v53
	v_cvt_pk_bf16_f32 v229, v54, v55
	v_cvt_pk_bf16_f32 v230, v48, v49
	v_cvt_pk_bf16_f32 v231, v50, v51
	v_cvt_pk_bf16_f32 v232, v28, v29
	v_cvt_pk_bf16_f32 v233, v30, v31
	v_cvt_pk_bf16_f32 v234, v24, v25
	v_cvt_pk_bf16_f32 v235, v26, v27
	v_mov_b32_e32 v236, v228
	v_mov_b32_e32 v237, v229
	v_mov_b32_e32 v238, v230
	v_mov_b32_e32 v239, v231
	v_mov_b32_dpp v228, v232 row_ror:8 row_mask:0xf bank_mask:0xc
	v_mov_b32_dpp v229, v233 row_ror:8 row_mask:0xf bank_mask:0xc
	v_mov_b32_dpp v230, v234 row_ror:8 row_mask:0xf bank_mask:0xc
	v_mov_b32_dpp v231, v235 row_ror:8 row_mask:0xf bank_mask:0xc
	v_mov_b32_dpp v232, v236 row_ror:8 row_mask:0xf bank_mask:0x3
	v_mov_b32_dpp v233, v237 row_ror:8 row_mask:0xf bank_mask:0x3
	v_mov_b32_dpp v234, v238 row_ror:8 row_mask:0xf bank_mask:0x3
	v_mov_b32_dpp v235, v239 row_ror:8 row_mask:0xf bank_mask:0x3
	s_add_u32 s100, s100, 0x18000
	s_addc_u32 s101, s101, 0
	global_store_dwordx4 v240, v[228:231], s[100:101]
	s_add_u32 s100, s100, 0x18000
	s_addc_u32 s101, s101, 0
	global_store_dwordx4 v240, v[232:235], s[100:101]
	v_cvt_pk_bf16_f32 v228, v36, v37
	v_cvt_pk_bf16_f32 v229, v38, v39
	v_cvt_pk_bf16_f32 v230, v32, v33
	v_cvt_pk_bf16_f32 v231, v34, v35
	v_cvt_pk_bf16_f32 v232, v12, v13
	v_cvt_pk_bf16_f32 v233, v14, v15
	v_cvt_pk_bf16_f32 v234, v8, v9
	v_cvt_pk_bf16_f32 v235, v10, v11
	v_mov_b32_e32 v236, v228
	v_mov_b32_e32 v237, v229
	v_mov_b32_e32 v238, v230
	v_mov_b32_e32 v239, v231
	v_mov_b32_dpp v228, v232 row_ror:8 row_mask:0xf bank_mask:0xc
	v_mov_b32_dpp v229, v233 row_ror:8 row_mask:0xf bank_mask:0xc
	v_mov_b32_dpp v230, v234 row_ror:8 row_mask:0xf bank_mask:0xc
	v_mov_b32_dpp v231, v235 row_ror:8 row_mask:0xf bank_mask:0xc
	v_mov_b32_dpp v232, v236 row_ror:8 row_mask:0xf bank_mask:0x3
	v_mov_b32_dpp v233, v237 row_ror:8 row_mask:0xf bank_mask:0x3
	v_mov_b32_dpp v234, v238 row_ror:8 row_mask:0xf bank_mask:0x3
	v_mov_b32_dpp v235, v239 row_ror:8 row_mask:0xf bank_mask:0x3
	s_add_u32 s100, s100, 0x18000
	s_addc_u32 s101, s101, 0
	global_store_dwordx4 v240, v[228:231], s[100:101]
	s_add_u32 s100, s100, 0x18000
	s_addc_u32 s101, s101, 0
	global_store_dwordx4 v240, v[232:235], s[100:101]
	v_cvt_pk_bf16_f32 v228, v20, v21
	v_cvt_pk_bf16_f32 v229, v22, v23
	v_cvt_pk_bf16_f32 v230, v16, v17
	v_cvt_pk_bf16_f32 v231, v18, v19
	v_cvt_pk_bf16_f32 v232, v4, v5
	v_cvt_pk_bf16_f32 v233, v6, v7
	v_cvt_pk_bf16_f32 v234, v0, v1
	v_cvt_pk_bf16_f32 v235, v2, v3
	v_mov_b32_e32 v236, v228
	v_mov_b32_e32 v237, v229
	v_mov_b32_e32 v238, v230
	v_mov_b32_e32 v239, v231
	v_mov_b32_dpp v228, v232 row_ror:8 row_mask:0xf bank_mask:0xc
	v_mov_b32_dpp v229, v233 row_ror:8 row_mask:0xf bank_mask:0xc
	v_mov_b32_dpp v230, v234 row_ror:8 row_mask:0xf bank_mask:0xc
	v_mov_b32_dpp v231, v235 row_ror:8 row_mask:0xf bank_mask:0xc
	v_mov_b32_dpp v232, v236 row_ror:8 row_mask:0xf bank_mask:0x3
	v_mov_b32_dpp v233, v237 row_ror:8 row_mask:0xf bank_mask:0x3
	v_mov_b32_dpp v234, v238 row_ror:8 row_mask:0xf bank_mask:0x3
	v_mov_b32_dpp v235, v239 row_ror:8 row_mask:0xf bank_mask:0x3
	s_add_u32 s100, s100, 0x18000
	s_addc_u32 s101, s101, 0
	global_store_dwordx4 v240, v[228:231], s[100:101]
	s_add_u32 s100, s100, 0x18000
	s_addc_u32 s101, s101, 0
	global_store_dwordx4 v240, v[232:235], s[100:101]
	s_and_b64 vcc, exec, s[2:3]
	s_mov_b32 s35, s8
	s_mov_b32 s6, s10
	s_mov_b64 s[18:19], s[14:15]
	s_mov_b64 s[16:17], s[12:13]
	s_cbranch_vccz .LBB0_151
	s_waitcnt vmcnt(0)
	s_cmpk_gt_u32 s22, 0xff
	s_cbranch_scc1 .LBB0_158
	s_barrier

.LBB0_253:
	s_or_b64 exec, exec, s[0:1]
	s_setprio 0
	v_readlane_b32 s0, v248, 10
	s_lshl_b32 s11, s42, 9
	s_lshl_b32 s10, s0, 9
	s_waitcnt lgkmcnt(0)
	v_mov_b32_e32 v0, v202
	s_barrier
	s_add_u32 s14, s58, 0x14d00000
	s_mov_b32 s26, 0x240000
	v_add_u32_e32 v106, s11, v0
	s_addc_u32 s15, s59, 0
	v_cmp_gt_i32_e32 vcc, s26, v106
	v_readlane_b32 s1, v248, 11
	s_and_saveexec_b64 s[0:1], vcc
	s_xor_b64 s[16:17], exec, s[0:1]
	s_cbranch_execz .LBB0_306
	v_lshlrev_b32_e32 v0, 3, v0
	v_and_b32_e32 v80, 0x7f8, v0
	v_readlane_b32 s64, v248, 13
	v_mov_b32_e32 v83, 0
	v_lshlrev_b32_e32 v82, 2, v80
	v_readlane_b32 s78, v248, 27
	v_readlane_b32 s79, v248, 28
	s_mov_b64 s[0:1], 0x2000
	s_nop 3
	global_load_dwordx4 v[0:3], v82, s[78:79] offset:16
	global_load_dwordx4 v[4:7], v82, s[78:79]
	v_lshl_add_u64 v[16:17], s[78:79], 0, v[82:83]
	v_add_co_u32_e32 v8, vcc, 0x2000, v16
	v_lshl_add_u64 v[12:13], v[16:17], 0, s[0:1]
	s_nop 0
	v_addc_co_u32_e32 v9, vcc, 0, v17, vcc
	s_mov_b64 s[0:1], 0x4000
	v_lshl_add_u64 v[20:21], v[16:17], 0, s[0:1]
	v_add_co_u32_e32 v16, vcc, 0x4000, v16
	global_load_dwordx4 v[8:11], v[8:9], off
	s_nop 0
	global_load_dwordx4 v[12:15], v[12:13], off offset:16
	v_addc_co_u32_e32 v17, vcc, 0, v17, vcc
	global_load_dwordx4 v[16:19], v[16:17], off
	s_nop 0
	global_load_dwordx4 v[20:23], v[20:21], off offset:16
	v_readlane_b32 s0, v248, 63
	v_readlane_b32 s68, v248, 17
	v_readlane_b32 s69, v248, 18
	v_lshlrev_b32_e32 v24, 1, v80
	v_mov_b32_e32 v25, v83
	v_readlane_b32 s1, v247, 0
	v_readlane_b32 s65, v248, 14
	v_readlane_b32 s66, v248, 15
	v_readlane_b32 s67, v248, 16
	v_readlane_b32 s70, v248, 19
	v_readlane_b32 s71, v248, 20
	v_readlane_b32 s72, v248, 21
	v_readlane_b32 s73, v248, 22
	v_readlane_b32 s74, v248, 23
	v_readlane_b32 s75, v248, 24
	v_readlane_b32 s76, v248, 25
	v_readlane_b32 s77, v248, 26
	s_movk_i32 s27, 0x2000
	v_lshl_add_u64 v[84:85], s[0:1], 0, v[24:25]
	v_lshl_add_u64 v[86:87], s[68:69], 0, v[82:83]
	v_lshl_add_u64 v[88:89], s[14:15], 0, v[24:25]
	s_mov_b64 s[18:19], 0
	s_movk_i32 s28, 0x1fff
	s_mov_b32 s29, 0x23ffff
	v_mov_b32_e32 v81, 0x7ff
	v_mov_b32_e32 v102, 0x7fe
	v_mov_b32_e32 v103, 0xfffff802
	v_mov_b32_e32 v104, 0x4800000
	v_mov_b32_e32 v105, 0x5070000
	v_mov_b32_e32 v48, v83
	v_mov_b32_e32 v49, v83
	v_mov_b32_e32 v50, v83
	v_mov_b32_e32 v51, v83
	v_mov_b32_e32 v44, v83
	v_mov_b32_e32 v45, v83
	v_mov_b32_e32 v46, v83
	v_mov_b32_e32 v47, v83
	v_mov_b32_e32 v40, v83
	v_mov_b32_e32 v41, v83
	v_mov_b32_e32 v42, v83
	v_mov_b32_e32 v43, v83
	v_mov_b32_e32 v36, v83
	v_mov_b32_e32 v37, v83
	v_mov_b32_e32 v38, v83
	v_mov_b32_e32 v39, v83
	s_branch .LBB0_256

.Lprio_skip_2:
	v_readlane_b32 s0, v248, 10
	s_abs_i32 s4, s0
	s_waitcnt lgkmcnt(0)
	v_cvt_f32_u32_e32 v0, s4
	v_readlane_b32 s1, v248, 11
	s_sub_i32 s0, 0, s4
	v_mov_b32_e32 v8, v202
	v_rcp_iflag_f32_e32 v0, v0
	s_barrier
	v_mul_f32_e32 v0, 0x4f7ffffe, v0
	v_cvt_u32_f32_e32 v0, v0
	s_nop 0
	v_readfirstlane_b32 s30, v8
	v_readfirstlane_b32 s1, v0
	s_mul_i32 s0, s0, s1
	s_mul_hi_u32 s0, s1, s0
	s_add_i32 s0, s1, s0
	v_writelane_b32 v247, s0, 17
	s_mul_hi_u32 s0, s0, 0x2400
	s_mul_i32 s1, s0, s4
	s_sub_i32 s1, 0x2400, s1
	s_add_i32 s2, s0, 1
	s_sub_i32 s3, s1, s4
	s_cmp_ge_u32 s1, s4
	s_cselect_b32 s0, s2, s0
	s_cselect_b32 s1, s3, s1
	s_add_i32 s2, s0, 1
	v_writelane_b32 v247, s4, 18
	s_cmp_ge_u32 s1, s4
	s_cselect_b32 s0, s2, s0
	v_readlane_b32 s1, v247, 11
	s_xor_b32 s0, s0, s1
	s_sub_i32 s3, s0, s1
	s_add_u32 s4, s58, 0x1800000
	s_addc_u32 s5, s59, 0
	s_cmp_gt_i32 s3, 0
	s_cbranch_scc0 .LBB0_372
	v_lshlrev_b32_e32 v0, 4, v8
	v_add_u32_e32 v1, 0x2000, v0
	v_ashrrev_i32_e32 v2, 31, v1
	v_lshrrev_b32_e32 v2, 22, v2
	v_add_u32_e32 v2, v1, v2
	v_ashrrev_i32_e32 v9, 10, v2
	s_mul_i32 s7, s3, s42
	v_mul_i32_i24_e32 v2, 0x400, v9
	s_ashr_i32 s0, s7, 31
	s_mul_hi_i32 s1, s7, 0x38e38e39
	v_sub_u32_e32 v1, v1, v2
	s_lshr_b32 s0, s0, 27
	s_lshr_b32 s2, s1, 31
	s_ashr_i32 s1, s1, 6
	v_lshrrev_b32_e32 v2, 4, v1
	s_add_i32 s8, s7, s0
	s_add_i32 s1, s1, s2
	v_bitop3_b32 v1, v2, v1, 32 bitop3:0x6c
	s_ashr_i32 s0, s8, 5
	s_mul_i32 s2, s1, -9
	v_ashrrev_i32_e32 v2, 31, v1
	s_add_i32 s2, s2, s0
	v_lshrrev_b32_e32 v2, 26, v2
	s_and_b32 s39, s1, 7
	s_lshl_b32 s0, s2, 2
	s_ashr_i32 s1, s1, 3
	v_add_u32_e32 v2, v1, v2
	v_lshlrev_b32_e32 v3, 3, v9
	s_add_i32 s0, s0, s1
	v_ashrrev_i32_e32 v10, 6, v2
	v_and_b32_e32 v3, -16, v3
	s_ashr_i32 s1, s0, 31
	v_add_u32_e32 v3, v10, v3
	s_lshl_b64 s[18:19], s[0:1], 20
	v_and_b32_e32 v4, 3, v10
	s_mov_b32 s1, 0xfffe0
	v_lshrrev_b32_e32 v5, 2, v3
	v_lshlrev_b32_e32 v6, 1, v3
	v_and_b32_e32 v2, 0xc0, v2
	v_and_or_b32 v4, v3, s1, v4
	v_and_b32_e32 v5, 4, v5
	v_and_b32_e32 v6, 24, v6
	v_sub_u32_e32 v1, v1, v2
	v_mov_b32_e32 v2, 1
	v_or3_b32 v4, v4, v5, v6
	v_lshlrev_b32_e32 v5, 5, v9
	v_ashrrev_i16_sdwa v1, v2, sext(v1) dst_sel:DWORD dst_unused:UNUSED_PAD src0_sel:DWORD src1_sel:BYTE_0
	v_and_b32_e32 v5, 32, v5
	v_bfe_i32 v11, v1, 0, 16
	v_add_lshl_u32 v1, v5, v11, 1
	v_lshl_add_u32 v128, v4, 12, v1
	v_lshl_add_u32 v130, v3, 12, v1
	v_bfe_i32 v1, v8, 27, 1
	v_lshrrev_b32_e32 v1, 22, v1
	v_add_u32_e32 v1, v0, v1
	v_and_b32_e32 v1, 0xfffffc00, v1
	v_sub_u32_e32 v0, v0, v1
	v_lshrrev_b32_e32 v1, 4, v0
	v_ashrrev_i32_e32 v3, 31, v8
	v_bitop3_b32 v0, v1, v0, 32 bitop3:0x6c
	v_lshrrev_b32_e32 v3, 26, v3
	v_ashrrev_i32_e32 v1, 31, v0
	v_add_u32_e32 v3, v8, v3
	v_lshrrev_b32_e32 v1, 26, v1
	v_ashrrev_i32_e32 v13, 6, v3
	s_andn2_b32 s8, s8, 31
	v_add_u32_e32 v1, v0, v1
	v_lshlrev_b32_e32 v3, 3, v13
	s_sub_i32 s16, s7, s8
	v_ashrrev_i32_e32 v12, 6, v1
	v_and_b32_e32 v3, -16, v3
	s_ashr_i32 s2, s30, 6
	s_ashr_i32 s17, s16, 31
	v_add_u32_e32 v3, v12, v3
	s_ashr_i32 s6, s30, 8
	s_lshl_b32 s31, s2, 10
	s_lshl_b32 s9, s39, 20
	s_lshl_b64 s[16:17], s[16:17], 7
	v_and_b32_e32 v4, 3, v12
	v_lshrrev_b32_e32 v5, 2, v3
	v_lshlrev_b32_e32 v6, 1, v3
	v_and_b32_e32 v1, 0xc0, v1
	v_and_or_b32 v4, v3, s1, v4
	v_and_b32_e32 v5, 4, v5
	v_and_b32_e32 v6, 24, v6
	v_sub_u32_e32 v0, v0, v1
	s_add_u32 s1, s4, s9
	v_or3_b32 v4, v4, v5, v6
	v_lshlrev_b32_e32 v5, 5, v13
	v_ashrrev_i16_sdwa v0, v2, sext(v0) dst_sel:DWORD dst_unused:UNUSED_PAD src0_sel:DWORD src1_sel:BYTE_0
	s_addc_u32 s9, s5, 0
	v_and_b32_e32 v5, 32, v5
	v_bfe_i32 v14, v0, 0, 16
	s_add_u32 s26, s1, s16
	v_add_lshl_u32 v0, v5, v14, 1
	s_addc_u32 s27, s9, s17
	s_add_i32 s1, s31, 0
	v_lshl_add_u32 v132, v4, 12, v0
	s_add_i32 m0, s1, 0x10000
	v_lshl_add_u32 v134, v3, 12, v0
	v_mov_b32_e32 v230, s6
	v_lshlrev_b32_e32 v230, 17, v230
	v_add_u32_e32 v132, v132, v230
	v_add_u32_e32 v230, 0x40000, v230
	v_add_u32_e32 v128, v128, v230
	global_load_lds_dwordx4 v132, s[26:27]
	s_add_i32 m0, s1, 0x12000
	s_add_u32 s9, s14, s18
	s_addc_u32 s18, s15, s19
	s_add_u32 s24, s9, s16
	global_load_lds_dwordx4 v128, s[26:27]
	s_addc_u32 s25, s18, s17
	s_mov_b32 m0, s1
	s_add_i32 s33, s1, 0x2000
	global_load_lds_dwordx4 v134, s[24:25]
	s_mov_b32 m0, s33
	s_add_u32 s16, s26, 0x20000
	global_load_lds_dwordx4 v130, s[24:25]
	s_addc_u32 s17, s27, 0
	s_add_i32 m0, s1, 0x14000
	v_mov_b32_e32 v133, 0
	global_load_lds_dwordx4 v132, s[16:17]
	s_add_i32 m0, s1, 0x16000
	v_mov_b32_e32 v129, v133
	global_load_lds_dwordx4 v128, s[16:17]
	s_add_u32 s16, s24, 0x80000
	s_addc_u32 s17, s25, 0
	s_add_i32 s34, s1, 0x4000
	s_mov_b32 m0, s34
	s_add_i32 s35, s1, 0x6000
	global_load_lds_dwordx4 v134, s[16:17]
	s_mov_b32 m0, s35
	v_mov_b32_e32 v135, v133
	global_load_lds_dwordx4 v130, s[16:17]
	v_mov_b32_e32 v131, v133
	v_lshl_add_u64 v[6:7], s[26:27], 0, v[132:133]
	v_lshl_add_u64 v[4:5], s[26:27], 0, v[128:129]
	v_lshl_add_u64 v[0:1], s[24:25], 0, v[134:135]
	s_cmp_lg_u32 s6, 1
	v_lshl_add_u64 v[2:3], s[24:25], 0, v[130:131]
	s_cbranch_scc1 .LBB0_361
	s_barrier

.LBB0_368:
	ds_read_b128 v[146:149], v143
	ds_read_b128 v[150:153], v143 offset:1024
	ds_read_b128 v[154:157], v143 offset:2048
	ds_read_b128 v[158:161], v143 offset:3072
	s_add_i32 s52, s26, 2
	s_add_u32 s27, s24, 0xfff80080
	s_addc_u32 s28, s25, -1
	s_cmp_eq_u32 s49, s26
	s_cselect_b32 s26, s48, s50
	s_cselect_b32 s29, s7, s28
	s_cselect_b32 s28, s9, s27
	s_cselect_b32 s27, s47, s51
	v_lshl_add_u64 v[194:195], s[24:25], 0, v[136:137]
	s_add_i32 m0, s1, 0xc000
	ds_read_b128 v[162:165], v144
	ds_read_b128 v[166:169], v144 offset:1024
	ds_read_b128 v[170:173], v144 offset:2048
	ds_read_b128 v[174:177], v144 offset:3072
	ds_read_b128 v[178:181], v144 offset:4096
	ds_read_b128 v[182:185], v144 offset:5120
	ds_read_b128 v[186:189], v144 offset:6144
	ds_read_b128 v[190:193], v144 offset:7168
	global_load_lds_dwordx4 v[194:195], off
	v_lshl_add_u64 v[194:195], s[24:25], 0, v[138:139]
	s_add_i32 m0, s1, 0xe000
	s_nop 0
	global_load_lds_dwordx4 v[194:195], off
	s_waitcnt lgkmcnt(8)
	s_barrier
	s_waitcnt lgkmcnt(0)
	s_waitcnt lgkmcnt(0)
	v_mfma_f32_16x16x32_bf16 v[124:127], v[146:149], v[162:165], v[124:127]
	v_mfma_f32_16x16x32_bf16 v[120:123], v[154:157], v[162:165], v[120:123]
	v_mfma_f32_16x16x32_bf16 v[108:111], v[146:149], v[170:173], v[108:111]
	v_mfma_f32_16x16x32_bf16 v[104:107], v[154:157], v[170:173], v[104:107]
	v_mfma_f32_16x16x32_bf16 v[92:95], v[146:149], v[178:181], v[92:95]
	v_mfma_f32_16x16x32_bf16 v[88:91], v[154:157], v[178:181], v[88:91]
	v_mfma_f32_16x16x32_bf16 v[76:79], v[146:149], v[186:189], v[76:79]
	v_mfma_f32_16x16x32_bf16 v[72:75], v[154:157], v[186:189], v[72:75]
	v_mfma_f32_16x16x32_bf16 v[124:127], v[150:153], v[166:169], v[124:127]
	v_mfma_f32_16x16x32_bf16 v[120:123], v[158:161], v[166:169], v[120:123]
	v_mfma_f32_16x16x32_bf16 v[108:111], v[150:153], v[174:177], v[108:111]
	v_mfma_f32_16x16x32_bf16 v[104:107], v[158:161], v[174:177], v[104:107]
	v_mfma_f32_16x16x32_bf16 v[92:95], v[150:153], v[182:185], v[92:95]
	v_mfma_f32_16x16x32_bf16 v[88:91], v[158:161], v[182:185], v[88:91]
	v_mfma_f32_16x16x32_bf16 v[76:79], v[150:153], v[190:193], v[76:79]
	v_mfma_f32_16x16x32_bf16 v[72:75], v[158:161], v[190:193], v[72:75]
	s_barrier
	s_add_i32 s53, s42, s31
	v_lshl_add_u64 v[212:213], s[26:27], 0, v[132:133]
	s_mov_b32 m0, s53
	ds_read_b128 v[194:197], v145
	ds_read_b128 v[198:201], v145 offset:1024
	ds_read_b128 v[204:207], v145 offset:2048
	ds_read_b128 v[208:211], v145 offset:3072
	global_load_lds_dwordx4 v[212:213], off
	v_lshl_add_u64 v[214:215], s[26:27], 0, v[128:129]
	s_add_i32 m0, s53, 0x2000
	s_nop 0
	global_load_lds_dwordx4 v[214:215], off
	s_barrier
	s_waitcnt lgkmcnt(0)
	s_waitcnt lgkmcnt(0)
	v_mfma_f32_16x16x32_bf16 v[116:119], v[194:197], v[162:165], v[116:119]
	v_mfma_f32_16x16x32_bf16 v[112:115], v[204:207], v[162:165], v[112:115]
	v_mfma_f32_16x16x32_bf16 v[100:103], v[194:197], v[170:173], v[100:103]
	v_mfma_f32_16x16x32_bf16 v[96:99], v[204:207], v[170:173], v[96:99]
	v_mfma_f32_16x16x32_bf16 v[84:87], v[194:197], v[178:181], v[84:87]
	v_mfma_f32_16x16x32_bf16 v[80:83], v[204:207], v[178:181], v[80:83]
	v_mfma_f32_16x16x32_bf16 v[68:71], v[194:197], v[186:189], v[68:71]
	v_mfma_f32_16x16x32_bf16 v[64:67], v[204:207], v[186:189], v[64:67]
	v_mfma_f32_16x16x32_bf16 v[116:119], v[198:201], v[166:169], v[116:119]
	v_mfma_f32_16x16x32_bf16 v[112:115], v[208:211], v[166:169], v[112:115]
	v_mfma_f32_16x16x32_bf16 v[100:103], v[198:201], v[174:177], v[100:103]
	v_mfma_f32_16x16x32_bf16 v[96:99], v[208:211], v[174:177], v[96:99]
	v_mfma_f32_16x16x32_bf16 v[84:87], v[198:201], v[182:185], v[84:87]
	v_mfma_f32_16x16x32_bf16 v[80:83], v[208:211], v[182:185], v[80:83]
	v_mfma_f32_16x16x32_bf16 v[68:71], v[198:201], v[190:193], v[68:71]
	v_mfma_f32_16x16x32_bf16 v[64:67], v[208:211], v[190:193], v[64:67]
	s_mov_b32 m0, s1
	v_lshl_add_u64 v[216:217], s[28:29], 0, v[134:135]
	s_barrier
	ds_read_b128 v[162:165], v144 offset:16384
	ds_read_b128 v[166:169], v144 offset:17408
	ds_read_b128 v[170:173], v144 offset:18432
	ds_read_b128 v[174:177], v144 offset:19456
	ds_read_b128 v[178:181], v144 offset:20480
	ds_read_b128 v[182:185], v144 offset:21504
	ds_read_b128 v[186:189], v144 offset:22528
	ds_read_b128 v[190:193], v144 offset:23552
	global_load_lds_dwordx4 v[216:217], off
	v_lshl_add_u64 v[218:219], s[28:29], 0, v[130:131]
	s_mov_b32 m0, s33
	s_nop 0
	global_load_lds_dwordx4 v[218:219], off
	s_barrier
	s_waitcnt lgkmcnt(0)
	s_waitcnt lgkmcnt(0)
	v_mfma_f32_16x16x32_bf16 v[60:63], v[146:149], v[162:165], v[60:63]
	v_mfma_f32_16x16x32_bf16 v[56:59], v[154:157], v[162:165], v[56:59]
	v_mfma_f32_16x16x32_bf16 v[44:47], v[146:149], v[170:173], v[44:47]
	v_mfma_f32_16x16x32_bf16 v[40:43], v[154:157], v[170:173], v[40:43]
	v_mfma_f32_16x16x32_bf16 v[28:31], v[146:149], v[178:181], v[28:31]
	v_mfma_f32_16x16x32_bf16 v[24:27], v[154:157], v[178:181], v[24:27]
	v_mfma_f32_16x16x32_bf16 v[12:15], v[146:149], v[186:189], v[12:15]
	v_mfma_f32_16x16x32_bf16 v[8:11], v[154:157], v[186:189], v[8:11]
	v_mfma_f32_16x16x32_bf16 v[60:63], v[150:153], v[166:169], v[60:63]
	v_mfma_f32_16x16x32_bf16 v[56:59], v[158:161], v[166:169], v[56:59]
	v_mfma_f32_16x16x32_bf16 v[44:47], v[150:153], v[174:177], v[44:47]
	v_mfma_f32_16x16x32_bf16 v[40:43], v[158:161], v[174:177], v[40:43]
	v_mfma_f32_16x16x32_bf16 v[28:31], v[150:153], v[182:185], v[28:31]
	v_mfma_f32_16x16x32_bf16 v[24:27], v[158:161], v[182:185], v[24:27]
	v_mfma_f32_16x16x32_bf16 v[12:15], v[150:153], v[190:193], v[12:15]
	v_mfma_f32_16x16x32_bf16 v[8:11], v[158:161], v[190:193], v[8:11]
	s_barrier
	s_add_u32 s54, s26, 0x20000
	s_addc_u32 s55, s27, 0
	s_add_i32 s53, s43, s31
	v_lshl_add_u64 v[146:147], s[54:55], 0, v[132:133]
	s_mov_b32 m0, s53
	s_nop 0
	global_load_lds_dwordx4 v[146:147], off
	v_lshl_add_u64 v[146:147], s[54:55], 0, v[128:129]
	s_add_i32 m0, s53, 0x2000
	s_nop 0
	global_load_lds_dwordx4 v[146:147], off
	s_waitcnt vmcnt(6)
	s_barrier
	v_mfma_f32_16x16x32_bf16 v[52:55], v[194:197], v[162:165], v[52:55]
	v_mfma_f32_16x16x32_bf16 v[48:51], v[204:207], v[162:165], v[48:51]
	v_mfma_f32_16x16x32_bf16 v[36:39], v[194:197], v[170:173], v[36:39]
	v_mfma_f32_16x16x32_bf16 v[32:35], v[204:207], v[170:173], v[32:35]
	v_mfma_f32_16x16x32_bf16 v[20:23], v[194:197], v[178:181], v[20:23]
	v_mfma_f32_16x16x32_bf16 v[16:19], v[204:207], v[178:181], v[16:19]
	v_mfma_f32_16x16x32_bf16 v[4:7], v[194:197], v[186:189], v[4:7]
	v_mfma_f32_16x16x32_bf16 v[0:3], v[204:207], v[186:189], v[0:3]
	v_mfma_f32_16x16x32_bf16 v[52:55], v[198:201], v[166:169], v[52:55]
	v_mfma_f32_16x16x32_bf16 v[48:51], v[208:211], v[166:169], v[48:51]
	v_mfma_f32_16x16x32_bf16 v[36:39], v[198:201], v[174:177], v[36:39]
	v_mfma_f32_16x16x32_bf16 v[32:35], v[208:211], v[174:177], v[32:35]
	v_mfma_f32_16x16x32_bf16 v[20:23], v[198:201], v[182:185], v[20:23]
	v_mfma_f32_16x16x32_bf16 v[16:19], v[208:211], v[182:185], v[16:19]
	v_mfma_f32_16x16x32_bf16 v[4:7], v[198:201], v[190:193], v[4:7]
	v_mfma_f32_16x16x32_bf16 v[0:3], v[208:211], v[190:193], v[0:3]
	s_add_i32 s53, 0, 0x18000
	v_add_u32_e32 v158, s53, v141
	s_barrier
	ds_read_b128 v[146:149], v158
	ds_read_b128 v[150:153], v158 offset:1024
	ds_read_b128 v[154:157], v158 offset:2048
	ds_read_b128 v[158:161], v158 offset:3072
	s_add_u32 s28, s28, 0x80000
	s_addc_u32 s29, s29, 0
	s_mov_b32 m0, s34
	v_lshl_add_u64 v[194:195], s[28:29], 0, v[134:135]
	ds_read_b128 v[162:165], v144 offset:32768
	ds_read_b128 v[166:169], v144 offset:33792
	ds_read_b128 v[170:173], v144 offset:34816
	ds_read_b128 v[174:177], v144 offset:35840
	ds_read_b128 v[178:181], v144 offset:36864
	ds_read_b128 v[182:185], v144 offset:37888
	ds_read_b128 v[186:189], v144 offset:38912
	ds_read_b128 v[190:193], v144 offset:39936
	global_load_lds_dwordx4 v[194:195], off
	v_lshl_add_u64 v[194:195], s[28:29], 0, v[130:131]
	s_mov_b32 m0, s35
	s_nop 0
	global_load_lds_dwordx4 v[194:195], off
	s_waitcnt lgkmcnt(8)
	s_barrier
	s_waitcnt lgkmcnt(0)
	s_waitcnt lgkmcnt(0)
	v_mfma_f32_16x16x32_bf16 v[124:127], v[146:149], v[162:165], v[124:127]
	v_mfma_f32_16x16x32_bf16 v[120:123], v[154:157], v[162:165], v[120:123]
	v_mfma_f32_16x16x32_bf16 v[108:111], v[146:149], v[170:173], v[108:111]
	v_mfma_f32_16x16x32_bf16 v[104:107], v[154:157], v[170:173], v[104:107]
	v_mfma_f32_16x16x32_bf16 v[92:95], v[146:149], v[178:181], v[92:95]
	v_mfma_f32_16x16x32_bf16 v[88:91], v[154:157], v[178:181], v[88:91]
	v_mfma_f32_16x16x32_bf16 v[76:79], v[146:149], v[186:189], v[76:79]
	v_mfma_f32_16x16x32_bf16 v[72:75], v[154:157], v[186:189], v[72:75]
	v_mfma_f32_16x16x32_bf16 v[124:127], v[150:153], v[166:169], v[124:127]
	v_mfma_f32_16x16x32_bf16 v[120:123], v[158:161], v[166:169], v[120:123]
	v_mfma_f32_16x16x32_bf16 v[108:111], v[150:153], v[174:177], v[108:111]
	v_mfma_f32_16x16x32_bf16 v[104:107], v[158:161], v[174:177], v[104:107]
	v_mfma_f32_16x16x32_bf16 v[92:95], v[150:153], v[182:185], v[92:95]
	v_mfma_f32_16x16x32_bf16 v[88:91], v[158:161], v[182:185], v[88:91]
	v_mfma_f32_16x16x32_bf16 v[76:79], v[150:153], v[190:193], v[76:79]
	v_mfma_f32_16x16x32_bf16 v[72:75], v[158:161], v[190:193], v[72:75]
	s_barrier
	s_add_i32 s28, 0, 0x1c000
	s_add_i32 s29, s53, s31
	v_add_u32_e32 v208, s28, v141
	v_lshl_add_u64 v[212:213], v[212:213], 0, s[2:3]
	s_mov_b32 m0, s29
	ds_read_b128 v[194:197], v208
	ds_read_b128 v[198:201], v208 offset:1024
	ds_read_b128 v[204:207], v208 offset:2048
	ds_read_b128 v[208:211], v208 offset:3072
	global_load_lds_dwordx4 v[212:213], off
	v_lshl_add_u64 v[212:213], v[214:215], 0, s[2:3]
	s_add_i32 m0, s29, 0x2000
	s_nop 0
	global_load_lds_dwordx4 v[212:213], off
	s_barrier
	s_waitcnt lgkmcnt(0)
	s_waitcnt lgkmcnt(0)
	v_mfma_f32_16x16x32_bf16 v[116:119], v[194:197], v[162:165], v[116:119]
	v_mfma_f32_16x16x32_bf16 v[112:115], v[204:207], v[162:165], v[112:115]
	v_mfma_f32_16x16x32_bf16 v[100:103], v[194:197], v[170:173], v[100:103]
	v_mfma_f32_16x16x32_bf16 v[96:99], v[204:207], v[170:173], v[96:99]
	v_mfma_f32_16x16x32_bf16 v[84:87], v[194:197], v[178:181], v[84:87]
	v_mfma_f32_16x16x32_bf16 v[80:83], v[204:207], v[178:181], v[80:83]
	v_mfma_f32_16x16x32_bf16 v[68:71], v[194:197], v[186:189], v[68:71]
	v_mfma_f32_16x16x32_bf16 v[64:67], v[204:207], v[186:189], v[64:67]
	v_mfma_f32_16x16x32_bf16 v[116:119], v[198:201], v[166:169], v[116:119]
	v_mfma_f32_16x16x32_bf16 v[112:115], v[208:211], v[166:169], v[112:115]
	v_mfma_f32_16x16x32_bf16 v[100:103], v[198:201], v[174:177], v[100:103]
	v_mfma_f32_16x16x32_bf16 v[96:99], v[208:211], v[174:177], v[96:99]
	v_mfma_f32_16x16x32_bf16 v[84:87], v[198:201], v[182:185], v[84:87]
	v_mfma_f32_16x16x32_bf16 v[80:83], v[208:211], v[182:185], v[80:83]
	v_mfma_f32_16x16x32_bf16 v[68:71], v[198:201], v[190:193], v[68:71]
	v_mfma_f32_16x16x32_bf16 v[64:67], v[208:211], v[190:193], v[64:67]
	s_mov_b32 m0, s40
	v_lshl_add_u64 v[212:213], v[216:217], 0, s[2:3]
	s_barrier
	ds_read_b128 v[162:165], v144 offset:49152
	ds_read_b128 v[166:169], v144 offset:50176
	ds_read_b128 v[170:173], v144 offset:51200
	ds_read_b128 v[174:177], v144 offset:52224
	ds_read_b128 v[178:181], v144 offset:53248
	ds_read_b128 v[182:185], v144 offset:54272
	ds_read_b128 v[186:189], v144 offset:55296
	ds_read_b128 v[190:193], v144 offset:56320
	global_load_lds_dwordx4 v[212:213], off
	v_lshl_add_u64 v[212:213], v[218:219], 0, s[2:3]
	s_mov_b32 m0, s41
	s_nop 0
	global_load_lds_dwordx4 v[212:213], off
	s_barrier
	s_waitcnt lgkmcnt(0)
	s_waitcnt lgkmcnt(0)
	v_mfma_f32_16x16x32_bf16 v[60:63], v[146:149], v[162:165], v[60:63]
	v_mfma_f32_16x16x32_bf16 v[56:59], v[154:157], v[162:165], v[56:59]
	v_mfma_f32_16x16x32_bf16 v[44:47], v[146:149], v[170:173], v[44:47]
	v_mfma_f32_16x16x32_bf16 v[40:43], v[154:157], v[170:173], v[40:43]
	v_mfma_f32_16x16x32_bf16 v[28:31], v[146:149], v[178:181], v[28:31]
	v_mfma_f32_16x16x32_bf16 v[24:27], v[154:157], v[178:181], v[24:27]
	v_mfma_f32_16x16x32_bf16 v[12:15], v[146:149], v[186:189], v[12:15]
	v_mfma_f32_16x16x32_bf16 v[8:11], v[154:157], v[186:189], v[8:11]
	v_mfma_f32_16x16x32_bf16 v[60:63], v[150:153], v[166:169], v[60:63]
	v_mfma_f32_16x16x32_bf16 v[56:59], v[158:161], v[166:169], v[56:59]
	v_mfma_f32_16x16x32_bf16 v[44:47], v[150:153], v[174:177], v[44:47]
	v_mfma_f32_16x16x32_bf16 v[40:43], v[158:161], v[174:177], v[40:43]
	v_mfma_f32_16x16x32_bf16 v[28:31], v[150:153], v[182:185], v[28:31]
	v_mfma_f32_16x16x32_bf16 v[24:27], v[158:161], v[182:185], v[24:27]
	v_mfma_f32_16x16x32_bf16 v[12:15], v[150:153], v[190:193], v[12:15]
	v_mfma_f32_16x16x32_bf16 v[8:11], v[158:161], v[190:193], v[8:11]
	s_barrier
	s_add_u32 s26, s26, 0x20080
	s_addc_u32 s27, s27, 0
	s_add_i32 s28, s28, s31
	v_lshl_add_u64 v[146:147], s[26:27], 0, v[132:133]
	s_mov_b32 m0, s28
	s_nop 0
	global_load_lds_dwordx4 v[146:147], off
	v_lshl_add_u64 v[146:147], s[26:27], 0, v[128:129]
	s_add_i32 m0, s28, 0x2000
	s_nop 0
	global_load_lds_dwordx4 v[146:147], off
	s_waitcnt vmcnt(6)
	s_barrier
	v_mfma_f32_16x16x32_bf16 v[52:55], v[194:197], v[162:165], v[52:55]
	v_mfma_f32_16x16x32_bf16 v[48:51], v[204:207], v[162:165], v[48:51]
	v_mfma_f32_16x16x32_bf16 v[36:39], v[194:197], v[170:173], v[36:39]
	v_mfma_f32_16x16x32_bf16 v[32:35], v[204:207], v[170:173], v[32:35]
	v_mfma_f32_16x16x32_bf16 v[20:23], v[194:197], v[178:181], v[20:23]
	v_mfma_f32_16x16x32_bf16 v[16:19], v[204:207], v[178:181], v[16:19]
	v_mfma_f32_16x16x32_bf16 v[4:7], v[194:197], v[186:189], v[4:7]
	v_mfma_f32_16x16x32_bf16 v[0:3], v[204:207], v[186:189], v[0:3]
	v_mfma_f32_16x16x32_bf16 v[52:55], v[198:201], v[166:169], v[52:55]
	v_mfma_f32_16x16x32_bf16 v[48:51], v[208:211], v[166:169], v[48:51]
	v_mfma_f32_16x16x32_bf16 v[36:39], v[198:201], v[174:177], v[36:39]
	v_mfma_f32_16x16x32_bf16 v[32:35], v[208:211], v[174:177], v[32:35]
	v_mfma_f32_16x16x32_bf16 v[20:23], v[198:201], v[182:185], v[20:23]
	v_mfma_f32_16x16x32_bf16 v[16:19], v[208:211], v[182:185], v[16:19]
	v_mfma_f32_16x16x32_bf16 v[4:7], v[198:201], v[190:193], v[4:7]
	v_mfma_f32_16x16x32_bf16 v[0:3], v[208:211], v[190:193], v[0:3]
	s_add_u32 s24, s24, 0x100
	s_addc_u32 s25, s25, 0
	s_add_u32 s50, s50, 0x100
	s_addc_u32 s51, s51, 0
	s_cmp_ge_i32 s52, s46
	s_mov_b32 s26, s52
	s_barrier
	s_cbranch_scc0 .LBB0_368
	s_branch .LBB0_363

.LBB0_424:
	s_or_b64 exec, exec, s[0:1]
	s_setprio 0
	v_readlane_b32 s0, v248, 10
	v_readlane_b32 s1, v248, 11
	s_lshl_b32 s0, s0, 4
	v_writelane_b32 v248, s0, 52
	s_waitcnt lgkmcnt(0)
	v_mov_b32_e32 v0, v202
	v_mov_b32_e32 v1, v202
	v_writelane_b32 v248, s1, 53
	s_add_u32 s0, s58, 0xe100000
	s_addc_u32 s1, s59, 0
	v_writelane_b32 v248, s0, 54
	s_barrier
	s_nop 0
	v_writelane_b32 v248, s1, 55
	s_add_u32 s0, s58, 0x3c280000
	s_addc_u32 s1, s59, 0
	v_writelane_b32 v248, s0, 50
	s_movk_i32 s24, 0x2400
	s_nop 0
	v_writelane_b32 v248, s1, 51
	s_add_u32 s0, s58, 0x39e80000
	s_addc_u32 s1, s59, 0
	v_writelane_b32 v248, s0, 56
	v_ashrrev_i32_e32 v32, 6, v1
	s_nop 0
	v_writelane_b32 v248, s1, 57
	v_readlane_b32 s0, v247, 6
	v_readlane_b32 s1, v247, 7
	s_nop 0
	v_add_u32_e32 v1, s0, v32
	v_cmp_gt_i32_e32 vcc, s24, v1
	s_and_saveexec_b64 s[0:1], vcc
	s_xor_b64 s[2:3], exec, s[0:1]
	s_cbranch_execz .LBB0_472
	v_and_b32_e32 v96, 63, v0
	v_or_b32_e32 v34, 0x100, v96
	v_or_b32_e32 v36, 0x140, v96
	v_or_b32_e32 v38, 0x180, v96
	v_or_b32_e32 v40, 0x1c0, v96
	v_readlane_b32 s16, v248, 0
	v_lshlrev_b32_e32 v0, 4, v40
	v_lshlrev_b32_e32 v4, 4, v38
	v_readlane_b32 s17, v248, 1
	v_lshlrev_b32_e32 v8, 4, v36
	v_lshlrev_b32_e32 v12, 4, v34
	v_lshlrev_b32_e32 v28, 4, v96
	s_nop 1
	global_load_dwordx4 v[0:3], v0, s[16:17]
	s_nop 0
	global_load_dwordx4 v[4:7], v4, s[16:17]
	s_nop 0
	global_load_dwordx4 v[8:11], v8, s[16:17]
	s_nop 0
	global_load_dwordx4 v[12:15], v12, s[16:17]
	s_nop 0
	global_load_dwordx4 v[16:19], v28, s[16:17] offset:3072
	global_load_dwordx4 v[20:23], v28, s[16:17] offset:2048
	global_load_dwordx4 v[24:27], v28, s[16:17] offset:1024
	s_nop 0
	global_load_dwordx4 v[28:31], v28, s[16:17]
	v_mbcnt_hi_u32_b32 v33, -1, v203
	v_and_b32_e32 v35, 64, v33
	v_add_u32_e32 v35, 64, v35
	v_xor_b32_e32 v37, 1, v33
	v_cmp_lt_i32_e32 vcc, v37, v35
	v_readlane_b32 s0, v248, 50
	v_mov_b32_e32 v99, 0
	v_cndmask_b32_e32 v37, v33, v37, vcc
	v_lshlrev_b32_e32 v97, 2, v37
	v_xor_b32_e32 v37, 2, v33
	v_cmp_lt_i32_e32 vcc, v37, v35
	v_lshlrev_b32_e32 v98, 3, v96
	v_readlane_b32 s1, v248, 51
	v_cndmask_b32_e32 v37, v33, v37, vcc
	v_lshlrev_b32_e32 v188, 2, v37
	v_xor_b32_e32 v37, 4, v33
	v_cmp_lt_i32_e32 vcc, v37, v35
	v_lshl_add_u64 v[100:101], s[0:1], 0, v[98:99]
	v_readlane_b32 s0, v247, 9
	v_cndmask_b32_e32 v37, v33, v37, vcc
	v_lshlrev_b32_e32 v189, 2, v37
	v_xor_b32_e32 v37, 8, v33
	v_cmp_lt_i32_e32 vcc, v37, v35
	v_readlane_b32 s1, v247, 10
	v_readlane_b32 s64, v248, 13
	v_cndmask_b32_e32 v37, v33, v37, vcc
	v_lshlrev_b32_e32 v190, 2, v37
	v_xor_b32_e32 v37, 16, v33
	v_cmp_lt_i32_e32 vcc, v37, v35
	v_lshl_add_u64 v[102:103], s[0:1], 0, v[98:99]
	v_readlane_b32 s0, v247, 6
	v_cndmask_b32_e32 v37, v33, v37, vcc
	v_lshlrev_b32_e32 v191, 2, v37
	v_xor_b32_e32 v37, 32, v33
	v_cmp_lt_i32_e32 vcc, v37, v35
	v_readlane_b32 s1, v247, 7
	s_mov_b32 s6, s0
	v_cndmask_b32_e32 v33, v33, v37, vcc
	s_ashr_i32 s7, s0, 31
	v_writelane_b32 v247, s0, 6
	v_lshlrev_b32_e32 v192, 2, v33
	v_ashrrev_i32_e32 v33, 31, v32
	v_writelane_b32 v247, s1, 7
	v_readlane_b32 s0, v248, 52
	v_lshl_add_u64 v[104:105], v[32:33], 0, s[6:7]
	v_readlane_b32 s1, v248, 53
	s_mov_b32 s29, s61
	v_readlane_b32 s18, v248, 2
	v_readlane_b32 s19, v248, 3
	s_mov_b32 s61, 0
	s_ashr_i32 s1, s0, 31
	v_lshlrev_b64 v[32:33], 13, v[104:105]
	v_readlane_b32 s65, v248, 14
	v_readlane_b32 s20, v248, 4
	v_readlane_b32 s21, v248, 5
	v_readlane_b32 s22, v248, 6
	v_readlane_b32 s23, v248, 7
	v_readlane_b32 s66, v248, 15
	v_readlane_b32 s67, v248, 16
	v_readlane_b32 s68, v248, 17
	v_readlane_b32 s69, v248, 18
	v_readlane_b32 s70, v248, 19
	v_readlane_b32 s71, v248, 20
	v_readlane_b32 s72, v248, 21
	v_readlane_b32 s73, v248, 22
	v_readlane_b32 s74, v248, 23
	v_readlane_b32 s75, v248, 24
	v_readlane_b32 s76, v248, 25
	v_readlane_b32 s77, v248, 26
	v_readlane_b32 s78, v248, 27
	v_readlane_b32 s79, v248, 28
	v_lshl_add_u64 v[106:107], s[64:65], 0, v[32:33]
	v_writelane_b32 v248, s0, 52
	s_lshl_b64 s[6:7], s[0:1], 13
	s_mov_b64 s[8:9], 0
	s_movk_i32 s25, 0x1fff
	s_mov_b32 s26, 0x38e38e39
	v_mov_b32_e32 v193, 0x358637bd
	s_mov_b32 s27, 0x800000
	v_lshlrev_b32_e32 v108, 4, v34
	v_lshlrev_b32_e32 v110, 4, v36
	v_lshlrev_b32_e32 v112, 4, v38
	v_lshlrev_b32_e32 v114, 4, v40
	s_movk_i32 s28, 0x23ff
	s_mov_b64 s[14:15], s[60:61]
	s_mov_b64 s[16:17], 0
	s_mov_b64 s[18:19], 0
	v_writelane_b32 v248, s1, 53
	s_branch .LBB0_427

.Lprio_skip_4:
	s_cmpk_lt_i32 s42, 0x480
	s_cselect_b64 s[2:3], -1, 0
	s_add_u32 s0, s58, 0x2000000
	v_mov_b32_e32 v10, v202
	s_waitcnt lgkmcnt(0)
	s_barrier
	s_addc_u32 s1, s59, 0
	v_writelane_b32 v247, s2, 14
	v_readfirstlane_b32 s28, v10
	s_and_b64 vcc, exec, s[2:3]
	v_writelane_b32 v247, s3, 15
	s_cbranch_vccz .LBB0_536
	v_lshlrev_b32_e32 v0, 4, v10
	v_readlane_b32 s2, v247, 8
	v_add_u32_e32 v1, 0x2000, v0
	s_lshr_b32 s2, s2, 29
	v_ashrrev_i32_e32 v2, 31, v1
	s_add_i32 s2, s42, s2
	v_lshrrev_b32_e32 v2, 22, v2
	s_ashr_i32 s6, s28, 6
	s_and_b32 s7, s2, -8
	v_add_u32_e32 v2, v1, v2
	s_ashr_i32 s3, s28, 8
	s_lshl_b32 s29, s6, 10
	s_sub_i32 s7, s42, s7
	v_ashrrev_i32_e32 v8, 10, v2
	s_cmp_lt_i32 s7, 0
	s_movk_i32 s30, 0x91
	v_mul_i32_i24_e32 v2, 0x400, v8
	s_cselect_b32 s8, s30, 0x90
	v_sub_u32_e32 v1, v1, v2
	s_mul_i32 s7, s8, s7
	s_ashr_i32 s2, s2, 3
	v_lshrrev_b32_e32 v2, 4, v1
	s_add_i32 s2, s7, s2
	v_bitop3_b32 v1, v2, v1, 32 bitop3:0x6c
	s_ashr_i32 s7, s2, 31
	v_ashrrev_i32_e32 v2, 31, v1
	s_lshr_b32 s7, s7, 24
	v_lshrrev_b32_e32 v2, 26, v2
	s_add_i32 s7, s2, s7
	v_add_u32_e32 v2, v1, v2
	v_lshlrev_b32_e32 v3, 3, v8
	s_ashr_i32 s7, s7, 8
	v_ashrrev_i32_e32 v9, 6, v2
	v_and_b32_e32 v3, -16, v3
	s_lshl_b32 s14, s7, 3
	s_lshl_b32 s7, s7, 8
	v_add_u32_e32 v3, v9, v3
	s_sub_i32 s7, s2, s7
	v_and_b32_e32 v4, 3, v9
	s_mov_b32 s2, 0xfffe0
	v_lshrrev_b32_e32 v5, 2, v3
	v_lshlrev_b32_e32 v6, 1, v3
	v_and_b32_e32 v2, 0xc0, v2
	v_and_or_b32 v4, v3, s2, v4
	v_and_b32_e32 v5, 4, v5
	v_and_b32_e32 v6, 24, v6
	v_sub_u32_e32 v1, v1, v2
	v_mov_b32_e32 v2, 1
	v_or3_b32 v4, v4, v5, v6
	v_lshlrev_b32_e32 v5, 5, v8
	v_ashrrev_i16_sdwa v1, v2, sext(v1) dst_sel:DWORD dst_unused:UNUSED_PAD src0_sel:DWORD src1_sel:BYTE_0
	v_and_b32_e32 v5, 32, v5
	v_bfe_i32 v11, v1, 0, 16
	v_add_lshl_u32 v1, v5, v11, 1
	v_lshl_add_u32 v128, v4, 12, v1
	v_lshl_add_u32 v130, v3, 12, v1
	v_bfe_i32 v1, v10, 27, 1
	v_lshrrev_b32_e32 v1, 22, v1
	v_add_u32_e32 v1, v0, v1
	v_and_b32_e32 v1, 0xfffffc00, v1
	v_sub_u32_e32 v0, v0, v1
	v_lshrrev_b32_e32 v1, 4, v0
	v_ashrrev_i32_e32 v3, 31, v10
	v_bitop3_b32 v0, v1, v0, 32 bitop3:0x6c
	v_lshrrev_b32_e32 v3, 26, v3
	v_ashrrev_i32_e32 v1, 31, v0
	v_add_u32_e32 v3, v10, v3
	v_lshrrev_b32_e32 v1, 26, v1
	v_ashrrev_i32_e32 v13, 6, v3
	v_add_u32_e32 v1, v0, v1
	v_lshlrev_b32_e32 v3, 3, v13
	v_ashrrev_i32_e32 v12, 6, v1
	v_and_b32_e32 v3, -16, v3
	v_add_u32_e32 v3, v12, v3
	v_and_b32_e32 v4, 3, v12
	v_lshrrev_b32_e32 v5, 2, v3
	v_lshlrev_b32_e32 v6, 1, v3
	v_and_b32_e32 v1, 0xc0, v1
	v_and_or_b32 v4, v3, s2, v4
	v_and_b32_e32 v5, 4, v5
	v_and_b32_e32 v6, 24, v6
	v_sub_u32_e32 v0, v0, v1
	s_sub_i32 s8, 36, s14
	v_or3_b32 v4, v4, v5, v6
	v_lshlrev_b32_e32 v5, 5, v13
	v_ashrrev_i16_sdwa v0, v2, sext(v0) dst_sel:DWORD dst_unused:UNUSED_PAD src0_sel:DWORD src1_sel:BYTE_0
	s_min_u32 s15, s8, 8
	v_and_b32_e32 v5, 32, v5
	v_bfe_i32 v14, v0, 0, 16
	v_add_lshl_u32 v0, v5, v14, 1
	s_sext_i32_i16 s2, s7
	v_cvt_f32_ubyte0_e32 v2, s15
	v_lshl_add_u32 v132, v4, 12, v0
	v_cvt_f32_i32_e32 v1, s2
	v_rcp_iflag_f32_e32 v4, v2
	v_lshl_add_u32 v134, v3, 12, v0
	s_ashr_i32 s2, s2, 30
	s_or_b32 s2, s2, 1
	v_mul_f32_e32 v0, v1, v4
	v_trunc_f32_e32 v0, v0
	v_fma_f32 v1, -v0, v2, v1
	v_cvt_i32_f32_e32 v0, v0
	v_cmp_ge_f32_e64 s[8:9], |v1|, v2
	s_and_b64 s[8:9], s[8:9], exec
	s_cselect_b32 s2, s2, 0
	v_readfirstlane_b32 s8, v0
	s_add_i32 s2, s8, s2
	s_mul_i32 s8, s2, s15
	s_sub_i32 s7, s7, s8
	s_sext_i32_i16 s7, s7
	s_add_i32 s20, s14, s7
	s_ashr_i32 s21, s20, 31
	s_bfe_i64 s[14:15], s[2:3], 0x100000
	s_lshl_b64 s[8:9], s[20:21], 20
	s_lshl_b64 s[14:15], s[14:15], 20
	s_add_u32 s24, s0, s14
	s_addc_u32 s25, s1, s15
	s_add_i32 s21, s29, 0
	s_add_i32 m0, s21, 0x10000
	v_readlane_b32 s14, v247, 9
	v_mov_b32_e32 v230, s3
	v_lshlrev_b32_e32 v230, 17, v230
	v_add_u32_e32 v132, v132, v230
	v_add_u32_e32 v230, 0x40000, v230
	v_add_u32_e32 v128, v128, v230
	global_load_lds_dwordx4 v132, s[24:25]
	s_add_i32 m0, s21, 0x12000
	v_readlane_b32 s15, v247, 10
	s_add_u32 s22, s14, s8
	global_load_lds_dwordx4 v128, s[24:25]
	s_addc_u32 s23, s15, s9
	s_mov_b32 m0, s21
	s_add_i32 s31, s21, 0x2000
	global_load_lds_dwordx4 v134, s[22:23]
	s_mov_b32 m0, s31
	s_add_u32 s8, s24, 0x20000
	global_load_lds_dwordx4 v130, s[22:23]
	s_addc_u32 s9, s25, 0
	s_add_i32 m0, s21, 0x14000
	v_mov_b32_e32 v133, 0
	global_load_lds_dwordx4 v132, s[8:9]
	s_add_i32 m0, s21, 0x16000
	v_mov_b32_e32 v129, v133
	global_load_lds_dwordx4 v128, s[8:9]
	s_add_u32 s8, s22, 0x80000
	s_addc_u32 s9, s23, 0
	s_add_i32 s33, s21, 0x4000
	s_mov_b32 m0, s33
	s_add_i32 s34, s21, 0x6000
	global_load_lds_dwordx4 v134, s[8:9]
	s_mov_b32 m0, s34
	v_mov_b32_e32 v135, v133
	global_load_lds_dwordx4 v130, s[8:9]
	v_mov_b32_e32 v131, v133
	s_mov_b32 s35, 0
	v_lshl_add_u64 v[6:7], s[24:25], 0, v[132:133]
	v_lshl_add_u64 v[4:5], s[24:25], 0, v[128:129]
	v_lshl_add_u64 v[2:3], s[22:23], 0, v[134:135]
	s_cmp_lg_u32 s3, 1
	v_lshl_add_u64 v[0:1], s[22:23], 0, v[130:131]
	s_cbranch_scc1 .LBB0_527
	s_barrier

.LBB0_531:
	ds_read_b128 v[152:155], v149
	ds_read_b128 v[156:159], v149 offset:1024
	ds_read_b128 v[160:163], v149 offset:2048
	ds_read_b128 v[164:167], v149 offset:3072
	s_add_u32 s24, s22, 0xfff80080
	s_addc_u32 s25, s23, -1
	s_cmp_eq_u32 s45, 28
	s_cselect_b32 s27, s15, s25
	s_cselect_b32 s26, s41, s24
	s_cselect_b32 s25, s9, s44
	s_cselect_b32 s24, s42, s43
	v_lshl_add_u64 v[144:145], s[22:23], 0, v[136:137]
	s_add_i32 m0, s21, 0xc000
	ds_read_b128 v[168:171], v150
	ds_read_b128 v[172:175], v150 offset:1024
	ds_read_b128 v[176:179], v150 offset:2048
	ds_read_b128 v[180:183], v150 offset:3072
	ds_read_b128 v[184:187], v150 offset:4096
	ds_read_b128 v[188:191], v150 offset:5120
	ds_read_b128 v[192:195], v150 offset:6144
	ds_read_b128 v[196:199], v150 offset:7168
	global_load_lds_dwordx4 v[144:145], off
	v_lshl_add_u64 v[144:145], s[22:23], 0, v[138:139]
	s_add_i32 m0, s21, 0xe000
	s_nop 0
	global_load_lds_dwordx4 v[144:145], off
	s_waitcnt lgkmcnt(8)
	s_barrier
	s_waitcnt lgkmcnt(0)
	s_waitcnt lgkmcnt(0)
	v_mfma_f32_16x16x32_bf16 v[124:127], v[152:155], v[168:171], v[124:127]
	v_mfma_f32_16x16x32_bf16 v[120:123], v[160:163], v[168:171], v[120:123]
	v_mfma_f32_16x16x32_bf16 v[108:111], v[152:155], v[176:179], v[108:111]
	v_mfma_f32_16x16x32_bf16 v[104:107], v[160:163], v[176:179], v[104:107]
	v_mfma_f32_16x16x32_bf16 v[92:95], v[152:155], v[184:187], v[92:95]
	v_mfma_f32_16x16x32_bf16 v[88:91], v[160:163], v[184:187], v[88:91]
	v_mfma_f32_16x16x32_bf16 v[76:79], v[152:155], v[192:195], v[76:79]
	v_mfma_f32_16x16x32_bf16 v[72:75], v[160:163], v[192:195], v[72:75]
	v_mfma_f32_16x16x32_bf16 v[124:127], v[156:159], v[172:175], v[124:127]
	v_mfma_f32_16x16x32_bf16 v[120:123], v[164:167], v[172:175], v[120:123]
	v_mfma_f32_16x16x32_bf16 v[108:111], v[156:159], v[180:183], v[108:111]
	v_mfma_f32_16x16x32_bf16 v[104:107], v[164:167], v[180:183], v[104:107]
	v_mfma_f32_16x16x32_bf16 v[92:95], v[156:159], v[188:191], v[92:95]
	v_mfma_f32_16x16x32_bf16 v[88:91], v[164:167], v[188:191], v[88:91]
	v_mfma_f32_16x16x32_bf16 v[76:79], v[156:159], v[196:199], v[76:79]
	v_mfma_f32_16x16x32_bf16 v[72:75], v[164:167], v[196:199], v[72:75]
	s_barrier
	s_add_i32 s46, s38, s29
	v_lshl_add_u64 v[144:145], s[24:25], 0, v[132:133]
	s_mov_b32 m0, s46
	ds_read_b128 v[204:207], v151
	ds_read_b128 v[208:211], v151 offset:1024
	ds_read_b128 v[212:215], v151 offset:2048
	ds_read_b128 v[216:219], v151 offset:3072
	global_load_lds_dwordx4 v[144:145], off
	v_lshl_add_u64 v[200:201], s[24:25], 0, v[128:129]
	s_add_i32 m0, s46, 0x2000
	s_nop 0
	global_load_lds_dwordx4 v[200:201], off
	s_barrier
	s_waitcnt lgkmcnt(0)
	s_waitcnt lgkmcnt(0)
	v_mfma_f32_16x16x32_bf16 v[116:119], v[204:207], v[168:171], v[116:119]
	v_mfma_f32_16x16x32_bf16 v[112:115], v[212:215], v[168:171], v[112:115]
	v_mfma_f32_16x16x32_bf16 v[100:103], v[204:207], v[176:179], v[100:103]
	v_mfma_f32_16x16x32_bf16 v[96:99], v[212:215], v[176:179], v[96:99]
	v_mfma_f32_16x16x32_bf16 v[84:87], v[204:207], v[184:187], v[84:87]
	v_mfma_f32_16x16x32_bf16 v[80:83], v[212:215], v[184:187], v[80:83]
	v_mfma_f32_16x16x32_bf16 v[68:71], v[204:207], v[192:195], v[68:71]
	v_mfma_f32_16x16x32_bf16 v[64:67], v[212:215], v[192:195], v[64:67]
	v_mfma_f32_16x16x32_bf16 v[116:119], v[208:211], v[172:175], v[116:119]
	v_mfma_f32_16x16x32_bf16 v[112:115], v[216:219], v[172:175], v[112:115]
	v_mfma_f32_16x16x32_bf16 v[100:103], v[208:211], v[180:183], v[100:103]
	v_mfma_f32_16x16x32_bf16 v[96:99], v[216:219], v[180:183], v[96:99]
	v_mfma_f32_16x16x32_bf16 v[84:87], v[208:211], v[188:191], v[84:87]
	v_mfma_f32_16x16x32_bf16 v[80:83], v[216:219], v[188:191], v[80:83]
	v_mfma_f32_16x16x32_bf16 v[68:71], v[208:211], v[196:199], v[68:71]
	v_mfma_f32_16x16x32_bf16 v[64:67], v[216:219], v[196:199], v[64:67]
	s_mov_b32 m0, s21
	v_lshl_add_u64 v[220:221], s[26:27], 0, v[134:135]
	s_barrier
	ds_read_b128 v[168:171], v150 offset:16384
	ds_read_b128 v[172:175], v150 offset:17408
	ds_read_b128 v[176:179], v150 offset:18432
	ds_read_b128 v[180:183], v150 offset:19456
	ds_read_b128 v[184:187], v150 offset:20480
	ds_read_b128 v[188:191], v150 offset:21504
	ds_read_b128 v[192:195], v150 offset:22528
	ds_read_b128 v[196:199], v150 offset:23552
	global_load_lds_dwordx4 v[220:221], off
	v_lshl_add_u64 v[222:223], s[26:27], 0, v[130:131]
	s_mov_b32 m0, s31
	s_nop 0
	global_load_lds_dwordx4 v[222:223], off
	s_barrier
	s_waitcnt lgkmcnt(0)
	s_waitcnt lgkmcnt(0)
	v_mfma_f32_16x16x32_bf16 v[60:63], v[152:155], v[168:171], v[60:63]
	v_mfma_f32_16x16x32_bf16 v[56:59], v[160:163], v[168:171], v[56:59]
	v_mfma_f32_16x16x32_bf16 v[44:47], v[152:155], v[176:179], v[44:47]
	v_mfma_f32_16x16x32_bf16 v[40:43], v[160:163], v[176:179], v[40:43]
	v_mfma_f32_16x16x32_bf16 v[28:31], v[152:155], v[184:187], v[28:31]
	v_mfma_f32_16x16x32_bf16 v[24:27], v[160:163], v[184:187], v[24:27]
	v_mfma_f32_16x16x32_bf16 v[12:15], v[152:155], v[192:195], v[12:15]
	v_mfma_f32_16x16x32_bf16 v[8:11], v[160:163], v[192:195], v[8:11]
	v_mfma_f32_16x16x32_bf16 v[60:63], v[156:159], v[172:175], v[60:63]
	v_mfma_f32_16x16x32_bf16 v[56:59], v[164:167], v[172:175], v[56:59]
	v_mfma_f32_16x16x32_bf16 v[44:47], v[156:159], v[180:183], v[44:47]
	v_mfma_f32_16x16x32_bf16 v[40:43], v[164:167], v[180:183], v[40:43]
	v_mfma_f32_16x16x32_bf16 v[28:31], v[156:159], v[188:191], v[28:31]
	v_mfma_f32_16x16x32_bf16 v[24:27], v[164:167], v[188:191], v[24:27]
	v_mfma_f32_16x16x32_bf16 v[12:15], v[156:159], v[196:199], v[12:15]
	v_mfma_f32_16x16x32_bf16 v[8:11], v[164:167], v[196:199], v[8:11]
	s_barrier
	s_add_u32 s46, s24, 0x20000
	s_addc_u32 s47, s25, 0
	s_add_i32 s48, s39, s29
	v_lshl_add_u64 v[152:153], s[46:47], 0, v[132:133]
	s_mov_b32 m0, s48
	s_nop 0
	global_load_lds_dwordx4 v[152:153], off
	v_lshl_add_u64 v[152:153], s[46:47], 0, v[128:129]
	s_add_i32 m0, s48, 0x2000
	s_nop 0
	global_load_lds_dwordx4 v[152:153], off
	s_waitcnt vmcnt(6)
	s_barrier
	v_mfma_f32_16x16x32_bf16 v[52:55], v[204:207], v[168:171], v[52:55]
	v_mfma_f32_16x16x32_bf16 v[48:51], v[212:215], v[168:171], v[48:51]
	v_mfma_f32_16x16x32_bf16 v[36:39], v[204:207], v[176:179], v[36:39]
	v_mfma_f32_16x16x32_bf16 v[32:35], v[212:215], v[176:179], v[32:35]
	v_mfma_f32_16x16x32_bf16 v[20:23], v[204:207], v[184:187], v[20:23]
	v_mfma_f32_16x16x32_bf16 v[16:19], v[212:215], v[184:187], v[16:19]
	v_mfma_f32_16x16x32_bf16 v[4:7], v[204:207], v[192:195], v[4:7]
	v_mfma_f32_16x16x32_bf16 v[0:3], v[212:215], v[192:195], v[0:3]
	v_mfma_f32_16x16x32_bf16 v[52:55], v[208:211], v[172:175], v[52:55]
	v_mfma_f32_16x16x32_bf16 v[48:51], v[216:219], v[172:175], v[48:51]
	v_mfma_f32_16x16x32_bf16 v[36:39], v[208:211], v[180:183], v[36:39]
	v_mfma_f32_16x16x32_bf16 v[32:35], v[216:219], v[180:183], v[32:35]
	v_mfma_f32_16x16x32_bf16 v[20:23], v[208:211], v[188:191], v[20:23]
	v_mfma_f32_16x16x32_bf16 v[16:19], v[216:219], v[188:191], v[16:19]
	v_mfma_f32_16x16x32_bf16 v[4:7], v[208:211], v[196:199], v[4:7]
	v_mfma_f32_16x16x32_bf16 v[0:3], v[216:219], v[196:199], v[0:3]
	s_add_i32 s46, 0, 0x18000
	v_add_u32_e32 v164, s46, v147
	s_barrier
	ds_read_b128 v[152:155], v164
	ds_read_b128 v[156:159], v164 offset:1024
	ds_read_b128 v[160:163], v164 offset:2048
	ds_read_b128 v[164:167], v164 offset:3072
	s_add_u32 s26, s26, 0x80000
	s_addc_u32 s27, s27, 0
	s_mov_b32 m0, s33
	v_lshl_add_u64 v[204:205], s[26:27], 0, v[134:135]
	ds_read_b128 v[168:171], v150 offset:32768
	ds_read_b128 v[172:175], v150 offset:33792
	ds_read_b128 v[176:179], v150 offset:34816
	ds_read_b128 v[180:183], v150 offset:35840
	ds_read_b128 v[184:187], v150 offset:36864
	ds_read_b128 v[188:191], v150 offset:37888
	ds_read_b128 v[192:195], v150 offset:38912
	ds_read_b128 v[196:199], v150 offset:39936
	global_load_lds_dwordx4 v[204:205], off
	v_lshl_add_u64 v[204:205], s[26:27], 0, v[130:131]
	s_mov_b32 m0, s34
	s_nop 0
	global_load_lds_dwordx4 v[204:205], off
	s_waitcnt lgkmcnt(8)
	s_barrier
	s_waitcnt lgkmcnt(0)
	s_waitcnt lgkmcnt(0)
	v_mfma_f32_16x16x32_bf16 v[124:127], v[152:155], v[168:171], v[124:127]
	v_mfma_f32_16x16x32_bf16 v[120:123], v[160:163], v[168:171], v[120:123]
	v_mfma_f32_16x16x32_bf16 v[108:111], v[152:155], v[176:179], v[108:111]
	v_mfma_f32_16x16x32_bf16 v[104:107], v[160:163], v[176:179], v[104:107]
	v_mfma_f32_16x16x32_bf16 v[92:95], v[152:155], v[184:187], v[92:95]
	v_mfma_f32_16x16x32_bf16 v[88:91], v[160:163], v[184:187], v[88:91]
	v_mfma_f32_16x16x32_bf16 v[76:79], v[152:155], v[192:195], v[76:79]
	v_mfma_f32_16x16x32_bf16 v[72:75], v[160:163], v[192:195], v[72:75]
	v_mfma_f32_16x16x32_bf16 v[124:127], v[156:159], v[172:175], v[124:127]
	v_mfma_f32_16x16x32_bf16 v[120:123], v[164:167], v[172:175], v[120:123]
	v_mfma_f32_16x16x32_bf16 v[108:111], v[156:159], v[180:183], v[108:111]
	v_mfma_f32_16x16x32_bf16 v[104:107], v[164:167], v[180:183], v[104:107]
	v_mfma_f32_16x16x32_bf16 v[92:95], v[156:159], v[188:191], v[92:95]
	v_mfma_f32_16x16x32_bf16 v[88:91], v[164:167], v[188:191], v[88:91]
	v_mfma_f32_16x16x32_bf16 v[76:79], v[156:159], v[196:199], v[76:79]
	v_mfma_f32_16x16x32_bf16 v[72:75], v[164:167], v[196:199], v[72:75]
	s_barrier
	s_add_i32 s26, 0, 0x1c000
	s_add_i32 s27, s46, s29
	v_add_u32_e32 v216, s26, v147
	v_lshl_add_u64 v[144:145], v[144:145], 0, s[6:7]
	s_mov_b32 m0, s27
	ds_read_b128 v[204:207], v216
	ds_read_b128 v[208:211], v216 offset:1024
	ds_read_b128 v[212:215], v216 offset:2048
	ds_read_b128 v[216:219], v216 offset:3072
	global_load_lds_dwordx4 v[144:145], off
	v_lshl_add_u64 v[144:145], v[200:201], 0, s[6:7]
	s_add_i32 m0, s27, 0x2000
	s_nop 0
	global_load_lds_dwordx4 v[144:145], off
	s_barrier
	s_waitcnt lgkmcnt(0)
	s_waitcnt lgkmcnt(0)
	v_mfma_f32_16x16x32_bf16 v[116:119], v[204:207], v[168:171], v[116:119]
	v_mfma_f32_16x16x32_bf16 v[112:115], v[212:215], v[168:171], v[112:115]
	v_mfma_f32_16x16x32_bf16 v[100:103], v[204:207], v[176:179], v[100:103]
	v_mfma_f32_16x16x32_bf16 v[96:99], v[212:215], v[176:179], v[96:99]
	v_mfma_f32_16x16x32_bf16 v[84:87], v[204:207], v[184:187], v[84:87]
	v_mfma_f32_16x16x32_bf16 v[80:83], v[212:215], v[184:187], v[80:83]
	v_mfma_f32_16x16x32_bf16 v[68:71], v[204:207], v[192:195], v[68:71]
	v_mfma_f32_16x16x32_bf16 v[64:67], v[212:215], v[192:195], v[64:67]
	v_mfma_f32_16x16x32_bf16 v[116:119], v[208:211], v[172:175], v[116:119]
	v_mfma_f32_16x16x32_bf16 v[112:115], v[216:219], v[172:175], v[112:115]
	v_mfma_f32_16x16x32_bf16 v[100:103], v[208:211], v[180:183], v[100:103]
	v_mfma_f32_16x16x32_bf16 v[96:99], v[216:219], v[180:183], v[96:99]
	v_mfma_f32_16x16x32_bf16 v[84:87], v[208:211], v[188:191], v[84:87]
	v_mfma_f32_16x16x32_bf16 v[80:83], v[216:219], v[188:191], v[80:83]
	v_mfma_f32_16x16x32_bf16 v[68:71], v[208:211], v[196:199], v[68:71]
	v_mfma_f32_16x16x32_bf16 v[64:67], v[216:219], v[196:199], v[64:67]
	s_mov_b32 m0, s36
	v_lshl_add_u64 v[144:145], v[220:221], 0, s[6:7]
	s_barrier
	ds_read_b128 v[168:171], v150 offset:49152
	ds_read_b128 v[172:175], v150 offset:50176
	ds_read_b128 v[176:179], v150 offset:51200
	ds_read_b128 v[180:183], v150 offset:52224
	ds_read_b128 v[184:187], v150 offset:53248
	ds_read_b128 v[188:191], v150 offset:54272
	ds_read_b128 v[192:195], v150 offset:55296
	ds_read_b128 v[196:199], v150 offset:56320
	global_load_lds_dwordx4 v[144:145], off
	v_lshl_add_u64 v[144:145], v[222:223], 0, s[6:7]
	s_mov_b32 m0, s37
	s_nop 0
	global_load_lds_dwordx4 v[144:145], off
	s_barrier
	s_waitcnt lgkmcnt(0)
	s_waitcnt lgkmcnt(0)
	v_mfma_f32_16x16x32_bf16 v[60:63], v[152:155], v[168:171], v[60:63]
	v_mfma_f32_16x16x32_bf16 v[56:59], v[160:163], v[168:171], v[56:59]
	v_mfma_f32_16x16x32_bf16 v[44:47], v[152:155], v[176:179], v[44:47]
	v_mfma_f32_16x16x32_bf16 v[40:43], v[160:163], v[176:179], v[40:43]
	v_mfma_f32_16x16x32_bf16 v[28:31], v[152:155], v[184:187], v[28:31]
	v_mfma_f32_16x16x32_bf16 v[24:27], v[160:163], v[184:187], v[24:27]
	v_mfma_f32_16x16x32_bf16 v[12:15], v[152:155], v[192:195], v[12:15]
	v_mfma_f32_16x16x32_bf16 v[8:11], v[160:163], v[192:195], v[8:11]
	v_mfma_f32_16x16x32_bf16 v[60:63], v[156:159], v[172:175], v[60:63]
	v_mfma_f32_16x16x32_bf16 v[56:59], v[164:167], v[172:175], v[56:59]
	v_mfma_f32_16x16x32_bf16 v[44:47], v[156:159], v[180:183], v[44:47]
	v_mfma_f32_16x16x32_bf16 v[40:43], v[164:167], v[180:183], v[40:43]
	v_mfma_f32_16x16x32_bf16 v[28:31], v[156:159], v[188:191], v[28:31]
	v_mfma_f32_16x16x32_bf16 v[24:27], v[164:167], v[188:191], v[24:27]
	v_mfma_f32_16x16x32_bf16 v[12:15], v[156:159], v[196:199], v[12:15]
	v_mfma_f32_16x16x32_bf16 v[8:11], v[164:167], v[196:199], v[8:11]
	s_barrier
	s_add_u32 s24, s24, 0x20080
	s_addc_u32 s25, s25, 0
	s_add_i32 s26, s26, s29
	v_lshl_add_u64 v[144:145], s[24:25], 0, v[132:133]
	s_mov_b32 m0, s26
	s_nop 0
	global_load_lds_dwordx4 v[144:145], off
	v_lshl_add_u64 v[144:145], s[24:25], 0, v[128:129]
	s_add_i32 m0, s26, 0x2000
	s_nop 0
	global_load_lds_dwordx4 v[144:145], off
	s_waitcnt vmcnt(6)
	s_barrier
	v_mfma_f32_16x16x32_bf16 v[52:55], v[204:207], v[168:171], v[52:55]
	v_mfma_f32_16x16x32_bf16 v[48:51], v[212:215], v[168:171], v[48:51]
	v_mfma_f32_16x16x32_bf16 v[36:39], v[204:207], v[176:179], v[36:39]
	v_mfma_f32_16x16x32_bf16 v[32:35], v[212:215], v[176:179], v[32:35]
	v_mfma_f32_16x16x32_bf16 v[20:23], v[204:207], v[184:187], v[20:23]
	v_mfma_f32_16x16x32_bf16 v[16:19], v[212:215], v[184:187], v[16:19]
	v_mfma_f32_16x16x32_bf16 v[4:7], v[204:207], v[192:195], v[4:7]
	v_mfma_f32_16x16x32_bf16 v[0:3], v[212:215], v[192:195], v[0:3]
	v_mfma_f32_16x16x32_bf16 v[52:55], v[208:211], v[172:175], v[52:55]
	v_mfma_f32_16x16x32_bf16 v[48:51], v[216:219], v[172:175], v[48:51]
	v_mfma_f32_16x16x32_bf16 v[36:39], v[208:211], v[180:183], v[36:39]
	v_mfma_f32_16x16x32_bf16 v[32:35], v[216:219], v[180:183], v[32:35]
	v_mfma_f32_16x16x32_bf16 v[20:23], v[208:211], v[188:191], v[20:23]
	v_mfma_f32_16x16x32_bf16 v[16:19], v[216:219], v[188:191], v[16:19]
	v_mfma_f32_16x16x32_bf16 v[4:7], v[208:211], v[196:199], v[4:7]
	v_mfma_f32_16x16x32_bf16 v[0:3], v[216:219], v[196:199], v[0:3]
	s_add_i32 s45, s45, 2
	s_add_u32 s22, s22, 0x100
	s_addc_u32 s23, s23, 0
	s_add_u32 s43, s43, 0x100
	s_addc_u32 s44, s44, 0
	s_cmp_gt_u32 s45, 29
	s_barrier
	s_cbranch_scc0 .LBB0_531
	v_readlane_b32 s100, v248, 63
	v_readlane_b32 s101, v247, 0
	v_and_b32_e32 v242, 15, v202
	v_bfe_u32 v243, v202, 4, 2
	v_bfe_u32 v244, v202, 6, 2
	v_lshrrev_b32_e32 v245, 8, v202
	v_and_b32_e32 v240, 7, v242
	v_lshl_add_u32 v240, v245, 6, v240
	v_lshl_add_u32 v240, s20, 8, v240
	v_lshlrev_b32_e32 v240, 14, v240
	v_lshrrev_b32_e32 v241, 3, v242
	v_lshlrev_b32_e32 v241, 6, v241
	v_lshl_add_u32 v241, v244, 7, v241
	v_lshl_add_u32 v241, v243, 4, v241
	v_add_u32_e32 v240, v240, v241
	s_lshl_b32 s98, s40, 9
	v_add_u32_e32 v240, s98, v240
	v_max_f32_e32 v124, 0, v124
	v_max_f32_e32 v125, 0, v125
	v_max_f32_e32 v126, 0, v126
	v_max_f32_e32 v127, 0, v127
	v_max_f32_e32 v120, 0, v120
	v_max_f32_e32 v121, 0, v121
	v_max_f32_e32 v122, 0, v122
	v_max_f32_e32 v123, 0, v123
	v_pk_mul_f32 v[124:125], v[124:125], v[124:125]
	v_pk_mul_f32 v[126:127], v[126:127], v[126:127]
	v_pk_mul_f32 v[120:121], v[120:121], v[120:121]
	v_pk_mul_f32 v[122:123], v[122:123], v[122:123]
	v_cvt_pk_bf16_f32 v228, v124, v125
	v_cvt_pk_bf16_f32 v229, v126, v127
	v_cvt_pk_bf16_f32 v230, v120, v121
	v_cvt_pk_bf16_f32 v231, v122, v123
	v_max_f32_e32 v116, 0, v116
	v_max_f32_e32 v117, 0, v117
	v_max_f32_e32 v118, 0, v118
	v_max_f32_e32 v119, 0, v119
	v_max_f32_e32 v112, 0, v112
	v_max_f32_e32 v113, 0, v113
	v_max_f32_e32 v114, 0, v114
	v_max_f32_e32 v115, 0, v115
	v_pk_mul_f32 v[116:117], v[116:117], v[116:117]
	v_pk_mul_f32 v[118:119], v[118:119], v[118:119]
	v_pk_mul_f32 v[112:113], v[112:113], v[112:113]
	v_pk_mul_f32 v[114:115], v[114:115], v[114:115]
	v_cvt_pk_bf16_f32 v232, v116, v117
	v_cvt_pk_bf16_f32 v233, v118, v119
	v_cvt_pk_bf16_f32 v234, v112, v113
	v_cvt_pk_bf16_f32 v235, v114, v115
	v_mov_b32_e32 v236, v228
	v_mov_b32_e32 v237, v229
	v_mov_b32_e32 v238, v230
	v_mov_b32_e32 v239, v231
	v_mov_b32_dpp v228, v232 row_ror:8 row_mask:0xf bank_mask:0xc
	v_mov_b32_dpp v229, v233 row_ror:8 row_mask:0xf bank_mask:0xc
	v_mov_b32_dpp v230, v234 row_ror:8 row_mask:0xf bank_mask:0xc
	v_mov_b32_dpp v231, v235 row_ror:8 row_mask:0xf bank_mask:0xc
	v_mov_b32_dpp v232, v236 row_ror:8 row_mask:0xf bank_mask:0x3
	v_mov_b32_dpp v233, v237 row_ror:8 row_mask:0xf bank_mask:0x3
	v_mov_b32_dpp v234, v238 row_ror:8 row_mask:0xf bank_mask:0x3
	v_mov_b32_dpp v235, v239 row_ror:8 row_mask:0xf bank_mask:0x3
	global_store_dwordx4 v240, v[228:231], s[100:101]
	s_add_u32 s100, s100, 0x20000
	s_addc_u32 s101, s101, 0
	global_store_dwordx4 v240, v[232:235], s[100:101]
	v_max_f32_e32 v108, 0, v108
	v_max_f32_e32 v109, 0, v109
	v_max_f32_e32 v110, 0, v110
	v_max_f32_e32 v111, 0, v111
	v_max_f32_e32 v104, 0, v104
	v_max_f32_e32 v105, 0, v105
	v_max_f32_e32 v106, 0, v106
	v_max_f32_e32 v107, 0, v107
	v_pk_mul_f32 v[108:109], v[108:109], v[108:109]
	v_pk_mul_f32 v[110:111], v[110:111], v[110:111]
	v_pk_mul_f32 v[104:105], v[104:105], v[104:105]
	v_pk_mul_f32 v[106:107], v[106:107], v[106:107]
	v_cvt_pk_bf16_f32 v228, v108, v109
	v_cvt_pk_bf16_f32 v229, v110, v111
	v_cvt_pk_bf16_f32 v230, v104, v105
	v_cvt_pk_bf16_f32 v231, v106, v107
	v_max_f32_e32 v100, 0, v100
	v_max_f32_e32 v101, 0, v101
	v_max_f32_e32 v102, 0, v102
	v_max_f32_e32 v103, 0, v103
	v_max_f32_e32 v96, 0, v96
	v_max_f32_e32 v97, 0, v97
	v_max_f32_e32 v98, 0, v98
	v_max_f32_e32 v99, 0, v99
	v_pk_mul_f32 v[100:101], v[100:101], v[100:101]
	v_pk_mul_f32 v[102:103], v[102:103], v[102:103]
	v_pk_mul_f32 v[96:97], v[96:97], v[96:97]
	v_pk_mul_f32 v[98:99], v[98:99], v[98:99]
	v_cvt_pk_bf16_f32 v232, v100, v101
	v_cvt_pk_bf16_f32 v233, v102, v103
	v_cvt_pk_bf16_f32 v234, v96, v97
	v_cvt_pk_bf16_f32 v235, v98, v99
	v_mov_b32_e32 v236, v228
	v_mov_b32_e32 v237, v229
	v_mov_b32_e32 v238, v230
	v_mov_b32_e32 v239, v231
	v_mov_b32_dpp v228, v232 row_ror:8 row_mask:0xf bank_mask:0xc
	v_mov_b32_dpp v229, v233 row_ror:8 row_mask:0xf bank_mask:0xc
	v_mov_b32_dpp v230, v234 row_ror:8 row_mask:0xf bank_mask:0xc
	v_mov_b32_dpp v231, v235 row_ror:8 row_mask:0xf bank_mask:0xc
	v_mov_b32_dpp v232, v236 row_ror:8 row_mask:0xf bank_mask:0x3
	v_mov_b32_dpp v233, v237 row_ror:8 row_mask:0xf bank_mask:0x3
	v_mov_b32_dpp v234, v238 row_ror:8 row_mask:0xf bank_mask:0x3
	v_mov_b32_dpp v235, v239 row_ror:8 row_mask:0xf bank_mask:0x3
	s_add_u32 s100, s100, 0x20000
	s_addc_u32 s101, s101, 0
	global_store_dwordx4 v240, v[228:231], s[100:101]
	s_add_u32 s100, s100, 0x20000
	s_addc_u32 s101, s101, 0
	global_store_dwordx4 v240, v[232:235], s[100:101]
	v_max_f32_e32 v92, 0, v92
	v_max_f32_e32 v93, 0, v93
	v_max_f32_e32 v94, 0, v94
	v_max_f32_e32 v95, 0, v95
	v_max_f32_e32 v88, 0, v88
	v_max_f32_e32 v89, 0, v89
	v_max_f32_e32 v90, 0, v90
	v_max_f32_e32 v91, 0, v91
	v_pk_mul_f32 v[92:93], v[92:93], v[92:93]
	v_pk_mul_f32 v[94:95], v[94:95], v[94:95]
	v_pk_mul_f32 v[88:89], v[88:89], v[88:89]
	v_pk_mul_f32 v[90:91], v[90:91], v[90:91]
	v_cvt_pk_bf16_f32 v228, v92, v93
	v_cvt_pk_bf16_f32 v229, v94, v95
	v_cvt_pk_bf16_f32 v230, v88, v89
	v_cvt_pk_bf16_f32 v231, v90, v91
	v_max_f32_e32 v84, 0, v84
	v_max_f32_e32 v85, 0, v85
	v_max_f32_e32 v86, 0, v86
	v_max_f32_e32 v87, 0, v87
	v_max_f32_e32 v80, 0, v80
	v_max_f32_e32 v81, 0, v81
	v_max_f32_e32 v82, 0, v82
	v_max_f32_e32 v83, 0, v83
	v_pk_mul_f32 v[84:85], v[84:85], v[84:85]
	v_pk_mul_f32 v[86:87], v[86:87], v[86:87]
	v_pk_mul_f32 v[80:81], v[80:81], v[80:81]
	v_pk_mul_f32 v[82:83], v[82:83], v[82:83]
	v_cvt_pk_bf16_f32 v232, v84, v85
	v_cvt_pk_bf16_f32 v233, v86, v87
	v_cvt_pk_bf16_f32 v234, v80, v81
	v_cvt_pk_bf16_f32 v235, v82, v83
	v_mov_b32_e32 v236, v228
	v_mov_b32_e32 v237, v229
	v_mov_b32_e32 v238, v230
	v_mov_b32_e32 v239, v231
	v_mov_b32_dpp v228, v232 row_ror:8 row_mask:0xf bank_mask:0xc
	v_mov_b32_dpp v229, v233 row_ror:8 row_mask:0xf bank_mask:0xc
	v_mov_b32_dpp v230, v234 row_ror:8 row_mask:0xf bank_mask:0xc
	v_mov_b32_dpp v231, v235 row_ror:8 row_mask:0xf bank_mask:0xc
	v_mov_b32_dpp v232, v236 row_ror:8 row_mask:0xf bank_mask:0x3
	v_mov_b32_dpp v233, v237 row_ror:8 row_mask:0xf bank_mask:0x3
	v_mov_b32_dpp v234, v238 row_ror:8 row_mask:0xf bank_mask:0x3
	v_mov_b32_dpp v235, v239 row_ror:8 row_mask:0xf bank_mask:0x3
	s_add_u32 s100, s100, 0x20000
	s_addc_u32 s101, s101, 0
	global_store_dwordx4 v240, v[228:231], s[100:101]
	s_add_u32 s100, s100, 0x20000
	s_addc_u32 s101, s101, 0
	global_store_dwordx4 v240, v[232:235], s[100:101]
	v_max_f32_e32 v76, 0, v76
	v_max_f32_e32 v77, 0, v77
	v_max_f32_e32 v78, 0, v78
	v_max_f32_e32 v79, 0, v79
	v_max_f32_e32 v72, 0, v72
	v_max_f32_e32 v73, 0, v73
	v_max_f32_e32 v74, 0, v74
	v_max_f32_e32 v75, 0, v75
	v_pk_mul_f32 v[76:77], v[76:77], v[76:77]
	v_pk_mul_f32 v[78:79], v[78:79], v[78:79]
	v_pk_mul_f32 v[72:73], v[72:73], v[72:73]
	v_pk_mul_f32 v[74:75], v[74:75], v[74:75]
	v_cvt_pk_bf16_f32 v228, v76, v77
	v_cvt_pk_bf16_f32 v229, v78, v79
	v_cvt_pk_bf16_f32 v230, v72, v73
	v_cvt_pk_bf16_f32 v231, v74, v75
	v_max_f32_e32 v68, 0, v68
	v_max_f32_e32 v69, 0, v69
	v_max_f32_e32 v70, 0, v70
	v_max_f32_e32 v71, 0, v71
	v_max_f32_e32 v64, 0, v64
	v_max_f32_e32 v65, 0, v65
	v_max_f32_e32 v66, 0, v66
	v_max_f32_e32 v67, 0, v67
	v_pk_mul_f32 v[68:69], v[68:69], v[68:69]
	v_pk_mul_f32 v[70:71], v[70:71], v[70:71]
	v_pk_mul_f32 v[64:65], v[64:65], v[64:65]
	v_pk_mul_f32 v[66:67], v[66:67], v[66:67]
	v_cvt_pk_bf16_f32 v232, v68, v69
	v_cvt_pk_bf16_f32 v233, v70, v71
	v_cvt_pk_bf16_f32 v234, v64, v65
	v_cvt_pk_bf16_f32 v235, v66, v67
	v_mov_b32_e32 v236, v228
	v_mov_b32_e32 v237, v229
	v_mov_b32_e32 v238, v230
	v_mov_b32_e32 v239, v231
	v_mov_b32_dpp v228, v232 row_ror:8 row_mask:0xf bank_mask:0xc
	v_mov_b32_dpp v229, v233 row_ror:8 row_mask:0xf bank_mask:0xc
	v_mov_b32_dpp v230, v234 row_ror:8 row_mask:0xf bank_mask:0xc
	v_mov_b32_dpp v231, v235 row_ror:8 row_mask:0xf bank_mask:0xc
	v_mov_b32_dpp v232, v236 row_ror:8 row_mask:0xf bank_mask:0x3
	v_mov_b32_dpp v233, v237 row_ror:8 row_mask:0xf bank_mask:0x3
	v_mov_b32_dpp v234, v238 row_ror:8 row_mask:0xf bank_mask:0x3
	v_mov_b32_dpp v235, v239 row_ror:8 row_mask:0xf bank_mask:0x3
	s_add_u32 s100, s100, 0x20000
	s_addc_u32 s101, s101, 0
	global_store_dwordx4 v240, v[228:231], s[100:101]
	s_add_u32 s100, s100, 0x20000
	s_addc_u32 s101, s101, 0
	global_store_dwordx4 v240, v[232:235], s[100:101]
	v_max_f32_e32 v60, 0, v60
	v_max_f32_e32 v61, 0, v61
	v_max_f32_e32 v62, 0, v62
	v_max_f32_e32 v63, 0, v63
	v_max_f32_e32 v56, 0, v56
	v_max_f32_e32 v57, 0, v57
	v_max_f32_e32 v58, 0, v58
	v_max_f32_e32 v59, 0, v59
	v_pk_mul_f32 v[60:61], v[60:61], v[60:61]
	v_pk_mul_f32 v[62:63], v[62:63], v[62:63]
	v_pk_mul_f32 v[56:57], v[56:57], v[56:57]
	v_pk_mul_f32 v[58:59], v[58:59], v[58:59]
	v_cvt_pk_bf16_f32 v228, v60, v61
	v_cvt_pk_bf16_f32 v229, v62, v63
	v_cvt_pk_bf16_f32 v230, v56, v57
	v_cvt_pk_bf16_f32 v231, v58, v59
	v_max_f32_e32 v52, 0, v52
	v_max_f32_e32 v53, 0, v53
	v_max_f32_e32 v54, 0, v54
	v_max_f32_e32 v55, 0, v55
	v_max_f32_e32 v48, 0, v48
	v_max_f32_e32 v49, 0, v49
	v_max_f32_e32 v50, 0, v50
	v_max_f32_e32 v51, 0, v51
	v_pk_mul_f32 v[52:53], v[52:53], v[52:53]
	v_pk_mul_f32 v[54:55], v[54:55], v[54:55]
	v_pk_mul_f32 v[48:49], v[48:49], v[48:49]
	v_pk_mul_f32 v[50:51], v[50:51], v[50:51]
	v_cvt_pk_bf16_f32 v232, v52, v53
	v_cvt_pk_bf16_f32 v233, v54, v55
	v_cvt_pk_bf16_f32 v234, v48, v49
	v_cvt_pk_bf16_f32 v235, v50, v51
	v_mov_b32_e32 v236, v228
	v_mov_b32_e32 v237, v229
	v_mov_b32_e32 v238, v230
	v_mov_b32_e32 v239, v231
	v_mov_b32_dpp v228, v232 row_ror:8 row_mask:0xf bank_mask:0xc
	v_mov_b32_dpp v229, v233 row_ror:8 row_mask:0xf bank_mask:0xc
	v_mov_b32_dpp v230, v234 row_ror:8 row_mask:0xf bank_mask:0xc
	v_mov_b32_dpp v231, v235 row_ror:8 row_mask:0xf bank_mask:0xc
	v_mov_b32_dpp v232, v236 row_ror:8 row_mask:0xf bank_mask:0x3
	v_mov_b32_dpp v233, v237 row_ror:8 row_mask:0xf bank_mask:0x3
	v_mov_b32_dpp v234, v238 row_ror:8 row_mask:0xf bank_mask:0x3
	v_mov_b32_dpp v235, v239 row_ror:8 row_mask:0xf bank_mask:0x3
	s_add_u32 s100, s100, 0x120000
	s_addc_u32 s101, s101, 0
	global_store_dwordx4 v240, v[228:231], s[100:101]
	s_add_u32 s100, s100, 0x20000
	s_addc_u32 s101, s101, 0
	global_store_dwordx4 v240, v[232:235], s[100:101]
	v_max_f32_e32 v44, 0, v44
	v_max_f32_e32 v45, 0, v45
	v_max_f32_e32 v46, 0, v46
	v_max_f32_e32 v47, 0, v47
	v_max_f32_e32 v40, 0, v40
	v_max_f32_e32 v41, 0, v41
	v_max_f32_e32 v42, 0, v42
	v_max_f32_e32 v43, 0, v43
	v_pk_mul_f32 v[44:45], v[44:45], v[44:45]
	v_pk_mul_f32 v[46:47], v[46:47], v[46:47]
	v_pk_mul_f32 v[40:41], v[40:41], v[40:41]
	v_pk_mul_f32 v[42:43], v[42:43], v[42:43]
	v_cvt_pk_bf16_f32 v228, v44, v45
	v_cvt_pk_bf16_f32 v229, v46, v47
	v_cvt_pk_bf16_f32 v230, v40, v41
	v_cvt_pk_bf16_f32 v231, v42, v43
	v_max_f32_e32 v36, 0, v36
	v_max_f32_e32 v37, 0, v37
	v_max_f32_e32 v38, 0, v38
	v_max_f32_e32 v39, 0, v39
	v_max_f32_e32 v32, 0, v32
	v_max_f32_e32 v33, 0, v33
	v_max_f32_e32 v34, 0, v34
	v_max_f32_e32 v35, 0, v35
	v_pk_mul_f32 v[36:37], v[36:37], v[36:37]
	v_pk_mul_f32 v[38:39], v[38:39], v[38:39]
	v_pk_mul_f32 v[32:33], v[32:33], v[32:33]
	v_pk_mul_f32 v[34:35], v[34:35], v[34:35]
	v_cvt_pk_bf16_f32 v232, v36, v37
	v_cvt_pk_bf16_f32 v233, v38, v39
	v_cvt_pk_bf16_f32 v234, v32, v33
	v_cvt_pk_bf16_f32 v235, v34, v35
	v_mov_b32_e32 v236, v228
	v_mov_b32_e32 v237, v229
	v_mov_b32_e32 v238, v230
	v_mov_b32_e32 v239, v231
	v_mov_b32_dpp v228, v232 row_ror:8 row_mask:0xf bank_mask:0xc
	v_mov_b32_dpp v229, v233 row_ror:8 row_mask:0xf bank_mask:0xc
	v_mov_b32_dpp v230, v234 row_ror:8 row_mask:0xf bank_mask:0xc
	v_mov_b32_dpp v231, v235 row_ror:8 row_mask:0xf bank_mask:0xc
	v_mov_b32_dpp v232, v236 row_ror:8 row_mask:0xf bank_mask:0x3
	v_mov_b32_dpp v233, v237 row_ror:8 row_mask:0xf bank_mask:0x3
	v_mov_b32_dpp v234, v238 row_ror:8 row_mask:0xf bank_mask:0x3
	v_mov_b32_dpp v235, v239 row_ror:8 row_mask:0xf bank_mask:0x3
	s_add_u32 s100, s100, 0x20000
	s_addc_u32 s101, s101, 0
	global_store_dwordx4 v240, v[228:231], s[100:101]
	s_add_u32 s100, s100, 0x20000
	s_addc_u32 s101, s101, 0
	global_store_dwordx4 v240, v[232:235], s[100:101]
	v_max_f32_e32 v28, 0, v28
	v_max_f32_e32 v29, 0, v29
	v_max_f32_e32 v30, 0, v30
	v_max_f32_e32 v31, 0, v31
	v_max_f32_e32 v24, 0, v24
	v_max_f32_e32 v25, 0, v25
	v_max_f32_e32 v26, 0, v26
	v_max_f32_e32 v27, 0, v27
	v_pk_mul_f32 v[28:29], v[28:29], v[28:29]
	v_pk_mul_f32 v[30:31], v[30:31], v[30:31]
	v_pk_mul_f32 v[24:25], v[24:25], v[24:25]
	v_pk_mul_f32 v[26:27], v[26:27], v[26:27]
	v_cvt_pk_bf16_f32 v228, v28, v29
	v_cvt_pk_bf16_f32 v229, v30, v31
	v_cvt_pk_bf16_f32 v230, v24, v25
	v_cvt_pk_bf16_f32 v231, v26, v27
	v_max_f32_e32 v20, 0, v20
	v_max_f32_e32 v21, 0, v21
	v_max_f32_e32 v22, 0, v22
	v_max_f32_e32 v23, 0, v23
	v_max_f32_e32 v16, 0, v16
	v_max_f32_e32 v17, 0, v17
	v_max_f32_e32 v18, 0, v18
	v_max_f32_e32 v19, 0, v19
	v_pk_mul_f32 v[20:21], v[20:21], v[20:21]
	v_pk_mul_f32 v[22:23], v[22:23], v[22:23]
	v_pk_mul_f32 v[16:17], v[16:17], v[16:17]
	v_pk_mul_f32 v[18:19], v[18:19], v[18:19]
	v_cvt_pk_bf16_f32 v232, v20, v21
	v_cvt_pk_bf16_f32 v233, v22, v23
	v_cvt_pk_bf16_f32 v234, v16, v17
	v_cvt_pk_bf16_f32 v235, v18, v19
	v_mov_b32_e32 v236, v228
	v_mov_b32_e32 v237, v229
	v_mov_b32_e32 v238, v230
	v_mov_b32_e32 v239, v231
	v_mov_b32_dpp v228, v232 row_ror:8 row_mask:0xf bank_mask:0xc
	v_mov_b32_dpp v229, v233 row_ror:8 row_mask:0xf bank_mask:0xc
	v_mov_b32_dpp v230, v234 row_ror:8 row_mask:0xf bank_mask:0xc
	v_mov_b32_dpp v231, v235 row_ror:8 row_mask:0xf bank_mask:0xc
	v_mov_b32_dpp v232, v236 row_ror:8 row_mask:0xf bank_mask:0x3
	v_mov_b32_dpp v233, v237 row_ror:8 row_mask:0xf bank_mask:0x3
	v_mov_b32_dpp v234, v238 row_ror:8 row_mask:0xf bank_mask:0x3
	v_mov_b32_dpp v235, v239 row_ror:8 row_mask:0xf bank_mask:0x3
	s_add_u32 s100, s100, 0x20000
	s_addc_u32 s101, s101, 0
	global_store_dwordx4 v240, v[228:231], s[100:101]
	s_add_u32 s100, s100, 0x20000
	s_addc_u32 s101, s101, 0
	global_store_dwordx4 v240, v[232:235], s[100:101]
	v_max_f32_e32 v12, 0, v12
	v_max_f32_e32 v13, 0, v13
	v_max_f32_e32 v14, 0, v14
	v_max_f32_e32 v15, 0, v15
	v_max_f32_e32 v8, 0, v8
	v_max_f32_e32 v9, 0, v9
	v_max_f32_e32 v10, 0, v10
	v_max_f32_e32 v11, 0, v11
	v_pk_mul_f32 v[12:13], v[12:13], v[12:13]
	v_pk_mul_f32 v[14:15], v[14:15], v[14:15]
	v_pk_mul_f32 v[8:9], v[8:9], v[8:9]
	v_pk_mul_f32 v[10:11], v[10:11], v[10:11]
	v_cvt_pk_bf16_f32 v228, v12, v13
	v_cvt_pk_bf16_f32 v229, v14, v15
	v_cvt_pk_bf16_f32 v230, v8, v9
	v_cvt_pk_bf16_f32 v231, v10, v11
	v_max_f32_e32 v4, 0, v4
	v_max_f32_e32 v5, 0, v5
	v_max_f32_e32 v6, 0, v6
	v_max_f32_e32 v7, 0, v7
	v_max_f32_e32 v0, 0, v0
	v_max_f32_e32 v1, 0, v1
	v_max_f32_e32 v2, 0, v2
	v_max_f32_e32 v3, 0, v3
	v_pk_mul_f32 v[4:5], v[4:5], v[4:5]
	v_pk_mul_f32 v[6:7], v[6:7], v[6:7]
	v_pk_mul_f32 v[0:1], v[0:1], v[0:1]
	v_pk_mul_f32 v[2:3], v[2:3], v[2:3]
	v_cvt_pk_bf16_f32 v232, v4, v5
	v_cvt_pk_bf16_f32 v233, v6, v7
	v_cvt_pk_bf16_f32 v234, v0, v1
	v_cvt_pk_bf16_f32 v235, v2, v3
	v_mov_b32_e32 v236, v228
	v_mov_b32_e32 v237, v229
	v_mov_b32_e32 v238, v230
	v_mov_b32_e32 v239, v231
	v_mov_b32_dpp v228, v232 row_ror:8 row_mask:0xf bank_mask:0xc
	v_mov_b32_dpp v229, v233 row_ror:8 row_mask:0xf bank_mask:0xc
	v_mov_b32_dpp v230, v234 row_ror:8 row_mask:0xf bank_mask:0xc
	v_mov_b32_dpp v231, v235 row_ror:8 row_mask:0xf bank_mask:0xc
	v_mov_b32_dpp v232, v236 row_ror:8 row_mask:0xf bank_mask:0x3
	v_mov_b32_dpp v233, v237 row_ror:8 row_mask:0xf bank_mask:0x3
	v_mov_b32_dpp v234, v238 row_ror:8 row_mask:0xf bank_mask:0x3
	v_mov_b32_dpp v235, v239 row_ror:8 row_mask:0xf bank_mask:0x3
	s_add_u32 s100, s100, 0x20000
	s_addc_u32 s101, s101, 0
	global_store_dwordx4 v240, v[228:231], s[100:101]
	s_add_u32 s100, s100, 0x20000
	s_addc_u32 s101, s101, 0
	global_store_dwordx4 v240, v[232:235], s[100:101]
	s_and_b64 vcc, exec, s[2:3]
	s_mov_b32 s40, s8
	s_mov_b32 s20, s14
	s_mov_b64 s[24:25], s[18:19]
	s_mov_b64 s[22:23], s[16:17]
	s_cbranch_vccz .LBB0_528
	s_waitcnt vmcnt(0)
	s_cmpk_gt_u32 s28, 0xff
	s_cbranch_scc1 .LBB0_535
	s_barrier

.Lprio_skip_5:
	v_readlane_b32 s0, v247, 17
	s_mul_hi_u32 s0, s0, 0x9000
	v_readlane_b32 s4, v247, 18
	s_mul_i32 s1, s0, s4
	s_sub_i32 s1, 0x9000, s1
	s_add_i32 s2, s0, 1
	s_sub_i32 s3, s1, s4
	s_cmp_ge_u32 s1, s4
	s_cselect_b32 s0, s2, s0
	s_cselect_b32 s1, s3, s1
	s_add_i32 s2, s0, 1
	s_cmp_ge_u32 s1, s4
	s_cselect_b32 s0, s2, s0
	v_readlane_b32 s1, v247, 11
	s_xor_b32 s0, s0, s1
	s_sub_i32 s0, s0, s1
	s_cmp_gt_i32 s0, 0
	s_mul_i32 s6, s0, s42
	s_cselect_b64 s[8:9], -1, 0
	s_add_i32 s4, s6, s0
	s_ashr_i32 s0, s6, 31
	s_mul_hi_i32 s2, s6, 0x38e38e39
	s_lshr_b32 s0, s0, 25
	s_lshr_b32 s3, s2, 31
	s_ashr_i32 s2, s2, 8
	s_add_i32 s0, s6, s0
	s_add_i32 s2, s2, s3
	s_ashr_i32 s1, s0, 7
	s_mul_i32 s3, s2, -9
	s_and_b32 s7, s0, 0xffffff80
	s_add_i32 s3, s3, s1
	s_add_i32 s0, s7, 0x80
	v_writelane_b32 v247, s4, 3
	s_and_b32 s1, s2, 7
	v_writelane_b32 v247, s0, 1
	s_min_i32 s0, s0, s4
	v_writelane_b32 v248, s1, 58
	s_lshl_b32 s1, s3, 2
	s_ashr_i32 s2, s2, 3
	s_add_i32 s2, s1, s2
	s_sub_i32 s33, s0, s6
	s_add_i32 s0, s7, 0x100
	v_writelane_b32 v247, s0, 2
	s_cmp_eq_u32 s6, s7
	s_mov_b32 s0, 0x3c280000
	s_mov_b32 s5, 0
	s_cselect_b32 s4, s0, 0x39e80000
	v_writelane_b32 v248, s2, 61
	v_writelane_b32 v247, s4, 4
	v_mov_b32_e32 v10, v202
	v_writelane_b32 v248, s3, 62
	v_writelane_b32 v247, s5, 5
	s_waitcnt lgkmcnt(0)
	s_barrier
	v_writelane_b32 v248, s6, 59
	v_writelane_b32 v247, s8, 12
	v_readfirstlane_b32 s22, v10
	s_and_b64 vcc, exec, s[8:9]
	v_writelane_b32 v248, s7, 60
	v_writelane_b32 v247, s9, 13
	s_cbranch_vccz .LBB0_648
	v_lshlrev_b32_e32 v0, 4, v10
	v_add_u32_e32 v1, 0x2000, v0
	v_ashrrev_i32_e32 v2, 31, v1
	v_lshrrev_b32_e32 v2, 22, v2
	v_add_u32_e32 v2, v1, v2
	v_ashrrev_i32_e32 v8, 10, v2
	v_mul_i32_i24_e32 v2, 0x400, v8
	v_sub_u32_e32 v1, v1, v2
	v_lshrrev_b32_e32 v2, 4, v1
	v_bitop3_b32 v1, v2, v1, 32 bitop3:0x6c
	v_ashrrev_i32_e32 v2, 31, v1
	v_lshrrev_b32_e32 v2, 26, v2
	v_add_u32_e32 v2, v1, v2
	v_lshlrev_b32_e32 v3, 3, v8
	v_ashrrev_i32_e32 v9, 6, v2
	v_and_b32_e32 v3, -16, v3
	s_add_u32 s23, s58, 0x4000000
	v_readlane_b32 s3, v248, 59
	v_readlane_b32 s4, v248, 60
	v_add_u32_e32 v3, v9, v3
	s_addc_u32 s24, s59, 0
	s_sub_i32 s4, s3, s4
	v_and_b32_e32 v4, 3, v9
	s_mov_b32 s3, 0x3ffe0
	v_lshrrev_b32_e32 v5, 2, v3
	v_lshlrev_b32_e32 v6, 1, v3
	v_and_b32_e32 v2, 0xc0, v2
	v_and_or_b32 v4, v3, s3, v4
	v_and_b32_e32 v5, 4, v5
	v_and_b32_e32 v6, 24, v6
	v_sub_u32_e32 v1, v1, v2
	v_mov_b32_e32 v2, 1
	v_or3_b32 v4, v4, v5, v6
	v_lshlrev_b32_e32 v5, 5, v8
	v_ashrrev_i16_sdwa v1, v2, sext(v1) dst_sel:DWORD dst_unused:UNUSED_PAD src0_sel:DWORD src1_sel:BYTE_0
	v_and_b32_e32 v5, 32, v5
	v_bfe_i32 v11, v1, 0, 16
	v_add_lshl_u32 v1, v5, v11, 1
	v_lshl_add_u32 v128, v4, 14, v1
	v_lshl_add_u32 v130, v3, 14, v1
	v_bfe_i32 v1, v10, 27, 1
	v_lshrrev_b32_e32 v1, 22, v1
	v_add_u32_e32 v1, v0, v1
	v_and_b32_e32 v1, 0xfffffc00, v1
	v_sub_u32_e32 v0, v0, v1
	v_lshrrev_b32_e32 v1, 4, v0
	v_ashrrev_i32_e32 v3, 31, v10
	v_bitop3_b32 v0, v1, v0, 32 bitop3:0x6c
	v_lshrrev_b32_e32 v3, 26, v3
	v_ashrrev_i32_e32 v1, 31, v0
	v_add_u32_e32 v3, v10, v3
	v_lshrrev_b32_e32 v1, 26, v1
	v_ashrrev_i32_e32 v13, 6, v3
	v_readlane_b32 s12, v248, 61
	v_add_u32_e32 v1, v0, v1
	v_lshlrev_b32_e32 v3, 3, v13
	v_readlane_b32 s13, v248, 62
	v_ashrrev_i32_e32 v12, 6, v1
	v_and_b32_e32 v3, -16, v3
	s_ashr_i32 s0, s22, 6
	v_readlane_b32 s1, v248, 58
	s_ashr_i32 s5, s4, 31
	s_ashr_i32 s13, s12, 31
	v_add_u32_e32 v3, v12, v3
	s_ashr_i32 s2, s22, 8
	s_lshl_b32 s25, s0, 10
	s_lshl_b32 s1, s1, 22
	s_lshl_b64 s[4:5], s[4:5], 7
	s_lshl_b64 s[6:7], s[12:13], 22
	v_and_b32_e32 v4, 3, v12
	v_lshrrev_b32_e32 v5, 2, v3
	v_lshlrev_b32_e32 v6, 1, v3
	v_and_b32_e32 v1, 0xc0, v1
	v_and_or_b32 v4, v3, s3, v4
	v_and_b32_e32 v5, 4, v5
	v_and_b32_e32 v6, 24, v6
	v_sub_u32_e32 v0, v0, v1
	s_add_u32 s1, s23, s1
	v_or3_b32 v4, v4, v5, v6
	v_lshlrev_b32_e32 v5, 5, v13
	v_ashrrev_i16_sdwa v0, v2, sext(v0) dst_sel:DWORD dst_unused:UNUSED_PAD src0_sel:DWORD src1_sel:BYTE_0
	s_addc_u32 s3, s24, 0
	v_and_b32_e32 v5, 32, v5
	v_bfe_i32 v14, v0, 0, 16
	s_add_u32 s18, s1, s4
	v_add_lshl_u32 v0, v5, v14, 1
	s_addc_u32 s19, s3, s5
	s_add_i32 s26, s25, 0
	v_lshl_add_u32 v132, v4, 14, v0
	s_add_i32 m0, s26, 0x10000
	v_readlane_b32 s8, v248, 63
	v_mov_b32_e32 v230, s2
	v_lshlrev_b32_e32 v230, 19, v230
	v_add_u32_e32 v132, v132, v230
	v_add_u32_e32 v230, 0x100000, v230
	v_add_u32_e32 v128, v128, v230
	global_load_lds_dwordx4 v132, s[18:19]
	s_add_i32 m0, s26, 0x12000
	v_readlane_b32 s9, v247, 0
	s_add_u32 s1, s8, s6
	s_addc_u32 s3, s9, s7
	s_add_u32 s16, s1, s4
	v_lshl_add_u32 v134, v3, 14, v0
	global_load_lds_dwordx4 v128, s[18:19]
	s_addc_u32 s17, s3, s5
	s_mov_b32 m0, s26
	s_add_i32 s27, s26, 0x2000
	global_load_lds_dwordx4 v134, s[16:17]
	s_mov_b32 m0, s27
	s_add_u32 s4, s18, 0x80000
	global_load_lds_dwordx4 v130, s[16:17]
	s_addc_u32 s5, s19, 0
	s_add_i32 m0, s26, 0x14000
	v_mov_b32_e32 v133, 0
	global_load_lds_dwordx4 v132, s[4:5]
	s_add_i32 m0, s26, 0x16000
	v_mov_b32_e32 v129, v133
	global_load_lds_dwordx4 v128, s[4:5]
	s_add_u32 s4, s16, 0x200000
	s_addc_u32 s5, s17, 0
	s_add_i32 s28, s26, 0x4000
	s_mov_b32 m0, s28
	s_add_i32 s29, s26, 0x6000
	global_load_lds_dwordx4 v134, s[4:5]
	s_mov_b32 m0, s29
	v_mov_b32_e32 v135, v133
	global_load_lds_dwordx4 v130, s[4:5]
	v_mov_b32_e32 v131, v133
	v_lshl_add_u64 v[6:7], s[18:19], 0, v[132:133]
	v_lshl_add_u64 v[4:5], s[18:19], 0, v[128:129]
	v_lshl_add_u64 v[2:3], s[16:17], 0, v[134:135]
	s_cmp_lg_u32 s2, 1
	v_lshl_add_u64 v[0:1], s[16:17], 0, v[130:131]
	s_cbranch_scc1 .LBB0_637
	s_barrier

.LBB0_644:
	ds_read_b128 v[146:149], v143
	ds_read_b128 v[150:153], v143 offset:1024
	ds_read_b128 v[154:157], v143 offset:2048
	ds_read_b128 v[158:161], v143 offset:3072
	s_add_i32 s46, s18, 2
	s_add_u32 s19, s16, 0xffe00080
	s_addc_u32 s20, s17, -1
	s_cmp_eq_u32 s43, s18
	s_cselect_b32 s18, s42, s44
	s_cselect_b32 s21, s3, s20
	s_cselect_b32 s20, s5, s19
	s_cselect_b32 s19, s41, s45
	v_lshl_add_u64 v[194:195], s[16:17], 0, v[136:137]
	s_add_i32 m0, s26, 0xc000
	ds_read_b128 v[162:165], v144
	ds_read_b128 v[166:169], v144 offset:1024
	ds_read_b128 v[170:173], v144 offset:2048
	ds_read_b128 v[174:177], v144 offset:3072
	ds_read_b128 v[178:181], v144 offset:4096
	ds_read_b128 v[182:185], v144 offset:5120
	ds_read_b128 v[186:189], v144 offset:6144
	ds_read_b128 v[190:193], v144 offset:7168
	global_load_lds_dwordx4 v[194:195], off
	v_lshl_add_u64 v[194:195], s[16:17], 0, v[138:139]
	s_add_i32 m0, s26, 0xe000
	s_nop 0
	global_load_lds_dwordx4 v[194:195], off
	s_waitcnt lgkmcnt(8)
	s_barrier
	s_waitcnt lgkmcnt(0)
	s_waitcnt lgkmcnt(0)
	v_mfma_f32_16x16x32_bf16 v[124:127], v[146:149], v[162:165], v[124:127]
	v_mfma_f32_16x16x32_bf16 v[120:123], v[154:157], v[162:165], v[120:123]
	v_mfma_f32_16x16x32_bf16 v[108:111], v[146:149], v[170:173], v[108:111]
	v_mfma_f32_16x16x32_bf16 v[104:107], v[154:157], v[170:173], v[104:107]
	v_mfma_f32_16x16x32_bf16 v[92:95], v[146:149], v[178:181], v[92:95]
	v_mfma_f32_16x16x32_bf16 v[88:91], v[154:157], v[178:181], v[88:91]
	v_mfma_f32_16x16x32_bf16 v[76:79], v[146:149], v[186:189], v[76:79]
	v_mfma_f32_16x16x32_bf16 v[72:75], v[154:157], v[186:189], v[72:75]
	v_mfma_f32_16x16x32_bf16 v[124:127], v[150:153], v[166:169], v[124:127]
	v_mfma_f32_16x16x32_bf16 v[120:123], v[158:161], v[166:169], v[120:123]
	v_mfma_f32_16x16x32_bf16 v[108:111], v[150:153], v[174:177], v[108:111]
	v_mfma_f32_16x16x32_bf16 v[104:107], v[158:161], v[174:177], v[104:107]
	v_mfma_f32_16x16x32_bf16 v[92:95], v[150:153], v[182:185], v[92:95]
	v_mfma_f32_16x16x32_bf16 v[88:91], v[158:161], v[182:185], v[88:91]
	v_mfma_f32_16x16x32_bf16 v[76:79], v[150:153], v[190:193], v[76:79]
	v_mfma_f32_16x16x32_bf16 v[72:75], v[158:161], v[190:193], v[72:75]
	s_barrier
	s_add_i32 s47, s35, s25
	v_lshl_add_u64 v[212:213], s[18:19], 0, v[132:133]
	s_mov_b32 m0, s47
	ds_read_b128 v[194:197], v145
	ds_read_b128 v[198:201], v145 offset:1024
	ds_read_b128 v[204:207], v145 offset:2048
	ds_read_b128 v[208:211], v145 offset:3072
	global_load_lds_dwordx4 v[212:213], off
	v_lshl_add_u64 v[214:215], s[18:19], 0, v[128:129]
	s_add_i32 m0, s47, 0x2000
	s_nop 0
	global_load_lds_dwordx4 v[214:215], off
	s_barrier
	s_waitcnt lgkmcnt(0)
	s_waitcnt lgkmcnt(0)
	v_mfma_f32_16x16x32_bf16 v[116:119], v[194:197], v[162:165], v[116:119]
	v_mfma_f32_16x16x32_bf16 v[112:115], v[204:207], v[162:165], v[112:115]
	v_mfma_f32_16x16x32_bf16 v[100:103], v[194:197], v[170:173], v[100:103]
	v_mfma_f32_16x16x32_bf16 v[96:99], v[204:207], v[170:173], v[96:99]
	v_mfma_f32_16x16x32_bf16 v[84:87], v[194:197], v[178:181], v[84:87]
	v_mfma_f32_16x16x32_bf16 v[80:83], v[204:207], v[178:181], v[80:83]
	v_mfma_f32_16x16x32_bf16 v[68:71], v[194:197], v[186:189], v[68:71]
	v_mfma_f32_16x16x32_bf16 v[64:67], v[204:207], v[186:189], v[64:67]
	v_mfma_f32_16x16x32_bf16 v[116:119], v[198:201], v[166:169], v[116:119]
	v_mfma_f32_16x16x32_bf16 v[112:115], v[208:211], v[166:169], v[112:115]
	v_mfma_f32_16x16x32_bf16 v[100:103], v[198:201], v[174:177], v[100:103]
	v_mfma_f32_16x16x32_bf16 v[96:99], v[208:211], v[174:177], v[96:99]
	v_mfma_f32_16x16x32_bf16 v[84:87], v[198:201], v[182:185], v[84:87]
	v_mfma_f32_16x16x32_bf16 v[80:83], v[208:211], v[182:185], v[80:83]
	v_mfma_f32_16x16x32_bf16 v[68:71], v[198:201], v[190:193], v[68:71]
	v_mfma_f32_16x16x32_bf16 v[64:67], v[208:211], v[190:193], v[64:67]
	s_mov_b32 m0, s26
	v_lshl_add_u64 v[216:217], s[20:21], 0, v[134:135]
	s_barrier
	ds_read_b128 v[162:165], v144 offset:16384
	ds_read_b128 v[166:169], v144 offset:17408
	ds_read_b128 v[170:173], v144 offset:18432
	ds_read_b128 v[174:177], v144 offset:19456
	ds_read_b128 v[178:181], v144 offset:20480
	ds_read_b128 v[182:185], v144 offset:21504
	ds_read_b128 v[186:189], v144 offset:22528
	ds_read_b128 v[190:193], v144 offset:23552
	global_load_lds_dwordx4 v[216:217], off
	v_lshl_add_u64 v[218:219], s[20:21], 0, v[130:131]
	s_mov_b32 m0, s27
	s_nop 0
	global_load_lds_dwordx4 v[218:219], off
	s_barrier
	s_waitcnt lgkmcnt(0)
	s_waitcnt lgkmcnt(0)
	v_mfma_f32_16x16x32_bf16 v[60:63], v[146:149], v[162:165], v[60:63]
	v_mfma_f32_16x16x32_bf16 v[56:59], v[154:157], v[162:165], v[56:59]
	v_mfma_f32_16x16x32_bf16 v[44:47], v[146:149], v[170:173], v[44:47]
	v_mfma_f32_16x16x32_bf16 v[40:43], v[154:157], v[170:173], v[40:43]
	v_mfma_f32_16x16x32_bf16 v[28:31], v[146:149], v[178:181], v[28:31]
	v_mfma_f32_16x16x32_bf16 v[24:27], v[154:157], v[178:181], v[24:27]
	v_mfma_f32_16x16x32_bf16 v[12:15], v[146:149], v[186:189], v[12:15]
	v_mfma_f32_16x16x32_bf16 v[8:11], v[154:157], v[186:189], v[8:11]
	v_mfma_f32_16x16x32_bf16 v[60:63], v[150:153], v[166:169], v[60:63]
	v_mfma_f32_16x16x32_bf16 v[56:59], v[158:161], v[166:169], v[56:59]
	v_mfma_f32_16x16x32_bf16 v[44:47], v[150:153], v[174:177], v[44:47]
	v_mfma_f32_16x16x32_bf16 v[40:43], v[158:161], v[174:177], v[40:43]
	v_mfma_f32_16x16x32_bf16 v[28:31], v[150:153], v[182:185], v[28:31]
	v_mfma_f32_16x16x32_bf16 v[24:27], v[158:161], v[182:185], v[24:27]
	v_mfma_f32_16x16x32_bf16 v[12:15], v[150:153], v[190:193], v[12:15]
	v_mfma_f32_16x16x32_bf16 v[8:11], v[158:161], v[190:193], v[8:11]
	s_barrier
	s_add_u32 s48, s18, 0x80000
	s_addc_u32 s49, s19, 0
	s_add_i32 s47, s36, s25
	v_lshl_add_u64 v[146:147], s[48:49], 0, v[132:133]
	s_mov_b32 m0, s47
	s_nop 0
	global_load_lds_dwordx4 v[146:147], off
	v_lshl_add_u64 v[146:147], s[48:49], 0, v[128:129]
	s_add_i32 m0, s47, 0x2000
	s_nop 0
	global_load_lds_dwordx4 v[146:147], off
	s_waitcnt vmcnt(6)
	s_barrier
	v_mfma_f32_16x16x32_bf16 v[52:55], v[194:197], v[162:165], v[52:55]
	v_mfma_f32_16x16x32_bf16 v[48:51], v[204:207], v[162:165], v[48:51]
	v_mfma_f32_16x16x32_bf16 v[36:39], v[194:197], v[170:173], v[36:39]
	v_mfma_f32_16x16x32_bf16 v[32:35], v[204:207], v[170:173], v[32:35]
	v_mfma_f32_16x16x32_bf16 v[20:23], v[194:197], v[178:181], v[20:23]
	v_mfma_f32_16x16x32_bf16 v[16:19], v[204:207], v[178:181], v[16:19]
	v_mfma_f32_16x16x32_bf16 v[4:7], v[194:197], v[186:189], v[4:7]
	v_mfma_f32_16x16x32_bf16 v[0:3], v[204:207], v[186:189], v[0:3]
	v_mfma_f32_16x16x32_bf16 v[52:55], v[198:201], v[166:169], v[52:55]
	v_mfma_f32_16x16x32_bf16 v[48:51], v[208:211], v[166:169], v[48:51]
	v_mfma_f32_16x16x32_bf16 v[36:39], v[198:201], v[174:177], v[36:39]
	v_mfma_f32_16x16x32_bf16 v[32:35], v[208:211], v[174:177], v[32:35]
	v_mfma_f32_16x16x32_bf16 v[20:23], v[198:201], v[182:185], v[20:23]
	v_mfma_f32_16x16x32_bf16 v[16:19], v[208:211], v[182:185], v[16:19]
	v_mfma_f32_16x16x32_bf16 v[4:7], v[198:201], v[190:193], v[4:7]
	v_mfma_f32_16x16x32_bf16 v[0:3], v[208:211], v[190:193], v[0:3]
	s_add_i32 s47, 0, 0x18000
	v_add_u32_e32 v158, s47, v141
	s_barrier
	ds_read_b128 v[146:149], v158
	ds_read_b128 v[150:153], v158 offset:1024
	ds_read_b128 v[154:157], v158 offset:2048
	ds_read_b128 v[158:161], v158 offset:3072
	s_add_u32 s20, s20, 0x200000
	s_addc_u32 s21, s21, 0
	s_mov_b32 m0, s28
	v_lshl_add_u64 v[194:195], s[20:21], 0, v[134:135]
	ds_read_b128 v[162:165], v144 offset:32768
	ds_read_b128 v[166:169], v144 offset:33792
	ds_read_b128 v[170:173], v144 offset:34816
	ds_read_b128 v[174:177], v144 offset:35840
	ds_read_b128 v[178:181], v144 offset:36864
	ds_read_b128 v[182:185], v144 offset:37888
	ds_read_b128 v[186:189], v144 offset:38912
	ds_read_b128 v[190:193], v144 offset:39936
	global_load_lds_dwordx4 v[194:195], off
	v_lshl_add_u64 v[194:195], s[20:21], 0, v[130:131]
	s_mov_b32 m0, s29
	s_nop 0
	global_load_lds_dwordx4 v[194:195], off
	s_waitcnt lgkmcnt(8)
	s_barrier
	s_waitcnt lgkmcnt(0)
	s_waitcnt lgkmcnt(0)
	v_mfma_f32_16x16x32_bf16 v[124:127], v[146:149], v[162:165], v[124:127]
	v_mfma_f32_16x16x32_bf16 v[120:123], v[154:157], v[162:165], v[120:123]
	v_mfma_f32_16x16x32_bf16 v[108:111], v[146:149], v[170:173], v[108:111]
	v_mfma_f32_16x16x32_bf16 v[104:107], v[154:157], v[170:173], v[104:107]
	v_mfma_f32_16x16x32_bf16 v[92:95], v[146:149], v[178:181], v[92:95]
	v_mfma_f32_16x16x32_bf16 v[88:91], v[154:157], v[178:181], v[88:91]
	v_mfma_f32_16x16x32_bf16 v[76:79], v[146:149], v[186:189], v[76:79]
	v_mfma_f32_16x16x32_bf16 v[72:75], v[154:157], v[186:189], v[72:75]
	v_mfma_f32_16x16x32_bf16 v[124:127], v[150:153], v[166:169], v[124:127]
	v_mfma_f32_16x16x32_bf16 v[120:123], v[158:161], v[166:169], v[120:123]
	v_mfma_f32_16x16x32_bf16 v[108:111], v[150:153], v[174:177], v[108:111]
	v_mfma_f32_16x16x32_bf16 v[104:107], v[158:161], v[174:177], v[104:107]
	v_mfma_f32_16x16x32_bf16 v[92:95], v[150:153], v[182:185], v[92:95]
	v_mfma_f32_16x16x32_bf16 v[88:91], v[158:161], v[182:185], v[88:91]
	v_mfma_f32_16x16x32_bf16 v[76:79], v[150:153], v[190:193], v[76:79]
	v_mfma_f32_16x16x32_bf16 v[72:75], v[158:161], v[190:193], v[72:75]
	s_barrier
	s_add_i32 s20, 0, 0x1c000
	s_add_i32 s21, s47, s25
	v_add_u32_e32 v208, s20, v141
	v_lshl_add_u64 v[212:213], v[212:213], 0, s[0:1]
	s_mov_b32 m0, s21
	ds_read_b128 v[194:197], v208
	ds_read_b128 v[198:201], v208 offset:1024
	ds_read_b128 v[204:207], v208 offset:2048
	ds_read_b128 v[208:211], v208 offset:3072
	global_load_lds_dwordx4 v[212:213], off
	v_lshl_add_u64 v[212:213], v[214:215], 0, s[0:1]
	s_add_i32 m0, s21, 0x2000
	s_nop 0
	global_load_lds_dwordx4 v[212:213], off
	s_barrier
	s_waitcnt lgkmcnt(0)
	s_waitcnt lgkmcnt(0)
	v_mfma_f32_16x16x32_bf16 v[116:119], v[194:197], v[162:165], v[116:119]
	v_mfma_f32_16x16x32_bf16 v[112:115], v[204:207], v[162:165], v[112:115]
	v_mfma_f32_16x16x32_bf16 v[100:103], v[194:197], v[170:173], v[100:103]
	v_mfma_f32_16x16x32_bf16 v[96:99], v[204:207], v[170:173], v[96:99]
	v_mfma_f32_16x16x32_bf16 v[84:87], v[194:197], v[178:181], v[84:87]
	v_mfma_f32_16x16x32_bf16 v[80:83], v[204:207], v[178:181], v[80:83]
	v_mfma_f32_16x16x32_bf16 v[68:71], v[194:197], v[186:189], v[68:71]
	v_mfma_f32_16x16x32_bf16 v[64:67], v[204:207], v[186:189], v[64:67]
	v_mfma_f32_16x16x32_bf16 v[116:119], v[198:201], v[166:169], v[116:119]
	v_mfma_f32_16x16x32_bf16 v[112:115], v[208:211], v[166:169], v[112:115]
	v_mfma_f32_16x16x32_bf16 v[100:103], v[198:201], v[174:177], v[100:103]
	v_mfma_f32_16x16x32_bf16 v[96:99], v[208:211], v[174:177], v[96:99]
	v_mfma_f32_16x16x32_bf16 v[84:87], v[198:201], v[182:185], v[84:87]
	v_mfma_f32_16x16x32_bf16 v[80:83], v[208:211], v[182:185], v[80:83]
	v_mfma_f32_16x16x32_bf16 v[68:71], v[198:201], v[190:193], v[68:71]
	v_mfma_f32_16x16x32_bf16 v[64:67], v[208:211], v[190:193], v[64:67]
	s_mov_b32 m0, s30
	v_lshl_add_u64 v[212:213], v[216:217], 0, s[0:1]
	s_barrier
	ds_read_b128 v[162:165], v144 offset:49152
	ds_read_b128 v[166:169], v144 offset:50176
	ds_read_b128 v[170:173], v144 offset:51200
	ds_read_b128 v[174:177], v144 offset:52224
	ds_read_b128 v[178:181], v144 offset:53248
	ds_read_b128 v[182:185], v144 offset:54272
	ds_read_b128 v[186:189], v144 offset:55296
	ds_read_b128 v[190:193], v144 offset:56320
	global_load_lds_dwordx4 v[212:213], off
	v_lshl_add_u64 v[212:213], v[218:219], 0, s[0:1]
	s_mov_b32 m0, s31
	s_nop 0
	global_load_lds_dwordx4 v[212:213], off
	s_barrier
	s_waitcnt lgkmcnt(0)
	s_waitcnt lgkmcnt(0)
	v_mfma_f32_16x16x32_bf16 v[60:63], v[146:149], v[162:165], v[60:63]
	v_mfma_f32_16x16x32_bf16 v[56:59], v[154:157], v[162:165], v[56:59]
	v_mfma_f32_16x16x32_bf16 v[44:47], v[146:149], v[170:173], v[44:47]
	v_mfma_f32_16x16x32_bf16 v[40:43], v[154:157], v[170:173], v[40:43]
	v_mfma_f32_16x16x32_bf16 v[28:31], v[146:149], v[178:181], v[28:31]
	v_mfma_f32_16x16x32_bf16 v[24:27], v[154:157], v[178:181], v[24:27]
	v_mfma_f32_16x16x32_bf16 v[12:15], v[146:149], v[186:189], v[12:15]
	v_mfma_f32_16x16x32_bf16 v[8:11], v[154:157], v[186:189], v[8:11]
	v_mfma_f32_16x16x32_bf16 v[60:63], v[150:153], v[166:169], v[60:63]
	v_mfma_f32_16x16x32_bf16 v[56:59], v[158:161], v[166:169], v[56:59]
	v_mfma_f32_16x16x32_bf16 v[44:47], v[150:153], v[174:177], v[44:47]
	v_mfma_f32_16x16x32_bf16 v[40:43], v[158:161], v[174:177], v[40:43]
	v_mfma_f32_16x16x32_bf16 v[28:31], v[150:153], v[182:185], v[28:31]
	v_mfma_f32_16x16x32_bf16 v[24:27], v[158:161], v[182:185], v[24:27]
	v_mfma_f32_16x16x32_bf16 v[12:15], v[150:153], v[190:193], v[12:15]
	v_mfma_f32_16x16x32_bf16 v[8:11], v[158:161], v[190:193], v[8:11]
	s_barrier
	s_add_u32 s18, s18, 0x80080
	s_addc_u32 s19, s19, 0
	s_add_i32 s20, s20, s25
	v_lshl_add_u64 v[146:147], s[18:19], 0, v[132:133]
	s_mov_b32 m0, s20
	s_nop 0
	global_load_lds_dwordx4 v[146:147], off
	v_lshl_add_u64 v[146:147], s[18:19], 0, v[128:129]
	s_add_i32 m0, s20, 0x2000
	s_nop 0
	global_load_lds_dwordx4 v[146:147], off
	s_waitcnt vmcnt(6)
	s_barrier
	v_mfma_f32_16x16x32_bf16 v[52:55], v[194:197], v[162:165], v[52:55]
	v_mfma_f32_16x16x32_bf16 v[48:51], v[204:207], v[162:165], v[48:51]
	v_mfma_f32_16x16x32_bf16 v[36:39], v[194:197], v[170:173], v[36:39]
	v_mfma_f32_16x16x32_bf16 v[32:35], v[204:207], v[170:173], v[32:35]
	v_mfma_f32_16x16x32_bf16 v[20:23], v[194:197], v[178:181], v[20:23]
	v_mfma_f32_16x16x32_bf16 v[16:19], v[204:207], v[178:181], v[16:19]
	v_mfma_f32_16x16x32_bf16 v[4:7], v[194:197], v[186:189], v[4:7]
	v_mfma_f32_16x16x32_bf16 v[0:3], v[204:207], v[186:189], v[0:3]
	v_mfma_f32_16x16x32_bf16 v[52:55], v[198:201], v[166:169], v[52:55]
	v_mfma_f32_16x16x32_bf16 v[48:51], v[208:211], v[166:169], v[48:51]
	v_mfma_f32_16x16x32_bf16 v[36:39], v[198:201], v[174:177], v[36:39]
	v_mfma_f32_16x16x32_bf16 v[32:35], v[208:211], v[174:177], v[32:35]
	v_mfma_f32_16x16x32_bf16 v[20:23], v[198:201], v[182:185], v[20:23]
	v_mfma_f32_16x16x32_bf16 v[16:19], v[208:211], v[182:185], v[16:19]
	v_mfma_f32_16x16x32_bf16 v[4:7], v[198:201], v[190:193], v[4:7]
	v_mfma_f32_16x16x32_bf16 v[0:3], v[208:211], v[190:193], v[0:3]
	s_add_u32 s16, s16, 0x100
	s_addc_u32 s17, s17, 0
	s_add_u32 s44, s44, 0x100
	s_addc_u32 s45, s45, 0
	s_cmp_ge_i32 s46, s40
	s_mov_b32 s18, s46
	s_barrier
	s_cbranch_scc0 .LBB0_644
	s_branch .LBB0_639

.LBB0_700:
	s_or_b64 exec, exec, s[0:1]
	s_setprio 0
	s_waitcnt lgkmcnt(0)
	v_mov_b32_e32 v0, v202
	v_mov_b32_e32 v1, v202
	s_barrier
	v_readlane_b32 s0, v247, 6
	v_ashrrev_i32_e32 v32, 6, v1
	s_movk_i32 s30, 0x2400
	v_add_u32_e32 v97, s0, v32
	v_cmp_gt_i32_e32 vcc, s30, v97
	v_readlane_b32 s1, v247, 7
	s_and_saveexec_b64 s[0:1], vcc
	s_xor_b64 s[2:3], exec, s[0:1]
	s_cbranch_execz .LBB0_740
	v_and_b32_e32 v96, 63, v0
	v_or_b32_e32 v98, 0x100, v96
	v_or_b32_e32 v100, 0x140, v96
	v_or_b32_e32 v102, 0x180, v96
	v_or_b32_e32 v104, 0x1c0, v96
	v_readlane_b32 s12, v248, 29
	v_lshlrev_b32_e32 v0, 4, v104
	v_lshlrev_b32_e32 v4, 4, v102
	v_readlane_b32 s14, v248, 31
	v_readlane_b32 s15, v248, 32
	v_lshlrev_b32_e32 v8, 4, v100
	v_lshlrev_b32_e32 v12, 4, v98
	v_lshlrev_b32_e32 v34, 4, v96
	s_nop 1
	global_load_dwordx4 v[0:3], v0, s[14:15]
	s_nop 0
	global_load_dwordx4 v[4:7], v4, s[14:15]
	s_nop 0
	global_load_dwordx4 v[8:11], v8, s[14:15]
	s_nop 0
	global_load_dwordx4 v[12:15], v12, s[14:15]
	s_nop 0
	global_load_dwordx4 v[16:19], v34, s[14:15] offset:3072
	global_load_dwordx4 v[20:23], v34, s[14:15] offset:2048
	global_load_dwordx4 v[24:27], v34, s[14:15] offset:1024
	global_load_dwordx4 v[28:31], v34, s[14:15]
	v_mbcnt_hi_u32_b32 v33, -1, v203
	v_and_b32_e32 v35, 64, v33
	v_add_u32_e32 v35, 64, v35
	v_xor_b32_e32 v36, 1, v33
	v_cmp_lt_i32_e32 vcc, v36, v35
	v_readlane_b32 s0, v248, 50
	v_mov_b32_e32 v107, 0
	v_cndmask_b32_e32 v36, v33, v36, vcc
	v_lshlrev_b32_e32 v99, 2, v36
	v_xor_b32_e32 v36, 2, v33
	v_cmp_lt_i32_e32 vcc, v36, v35
	v_lshlrev_b32_e32 v106, 3, v96
	v_readlane_b32 s1, v248, 51
	v_cndmask_b32_e32 v36, v33, v36, vcc
	v_lshlrev_b32_e32 v101, 2, v36
	v_xor_b32_e32 v36, 4, v33
	v_cmp_lt_i32_e32 vcc, v36, v35
	v_lshl_add_u64 v[108:109], s[0:1], 0, v[106:107]
	v_readlane_b32 s0, v247, 9
	v_cndmask_b32_e32 v36, v33, v36, vcc
	v_lshlrev_b32_e32 v103, 2, v36
	v_xor_b32_e32 v36, 8, v33
	v_cmp_lt_i32_e32 vcc, v36, v35
	v_readlane_b32 s1, v247, 10
	v_readlane_b32 s13, v248, 30
	v_cndmask_b32_e32 v36, v33, v36, vcc
	v_lshlrev_b32_e32 v105, 2, v36
	v_xor_b32_e32 v36, 16, v33
	v_cmp_lt_i32_e32 vcc, v36, v35
	v_lshl_add_u64 v[110:111], s[0:1], 0, v[106:107]
	v_readlane_b32 s0, v247, 6
	v_cndmask_b32_e32 v36, v33, v36, vcc
	v_lshlrev_b32_e32 v204, 2, v36
	v_xor_b32_e32 v36, 32, v33
	v_cmp_lt_i32_e32 vcc, v36, v35
	v_readlane_b32 s1, v247, 7
	s_mov_b32 s4, s0
	v_cndmask_b32_e32 v33, v33, v36, vcc
	v_lshlrev_b32_e32 v205, 2, v33
	v_ashrrev_i32_e32 v33, 31, v32
	s_ashr_i32 s5, s0, 31
	v_writelane_b32 v247, s0, 6
	v_lshl_add_u64 v[32:33], v[32:33], 0, s[4:5]
	v_readlane_b32 s16, v248, 33
	v_writelane_b32 v247, s1, 7
	v_readlane_b32 s0, v248, 52
	v_readlane_b32 s17, v248, 34
	v_readlane_b32 s18, v248, 35
	v_readlane_b32 s19, v248, 36
	v_readlane_b32 s20, v248, 37
	v_readlane_b32 s21, v248, 38
	v_readlane_b32 s22, v248, 39
	v_readlane_b32 s23, v248, 40
	v_readlane_b32 s24, v248, 41
	v_readlane_b32 s25, v248, 42
	v_lshlrev_b64 v[112:113], 12, v[32:33]
	v_readlane_b32 s1, v248, 53
	s_mov_b32 s6, s0
	s_ashr_i32 s7, s0, 31
	v_lshlrev_b64 v[114:115], 13, v[32:33]
	v_readlane_b32 s26, v248, 43
	v_readlane_b32 s27, v248, 44
	v_or_b32_e32 v112, v112, v106
	s_lshl_b64 s[4:5], s[6:7], 12
	v_or_b32_e32 v114, v114, v34
	v_writelane_b32 v248, s0, 52
	s_lshl_b64 s[8:9], s[6:7], 13
	s_mov_b64 s[6:7], 0
	s_mov_b32 s31, 0x38e38e39
	s_mov_b64 s[12:13], 0xe100400
	s_mov_b64 s[14:15], 0xe100800
	s_mov_b64 s[16:17], 0xe100c00
	s_mov_b64 s[18:19], 0xe101000
	s_mov_b64 s[20:21], 0xe101400
	s_mov_b64 s[22:23], 0xe101800
	s_mov_b64 s[24:25], 0xe101c00
	v_mov_b32_e32 v206, 0x358637bd
	s_mov_b32 s34, 0x800000
	s_mov_b32 s35, 0x12900000
	s_movk_i32 s36, 0x23ff
	v_writelane_b32 v248, s1, 53
	s_branch .LBB0_703

.Lprio_skip_7:
	s_add_u32 s12, s58, 0x24900000
	s_addc_u32 s13, s59, 0
	v_readlane_b32 s0, v248, 45
	v_mov_b32_e32 v10, v202
	s_waitcnt lgkmcnt(0)
	s_barrier
	s_cmpk_lt_i32 s0, 0x6e4
	s_nop 0
	v_readfirstlane_b32 s26, v10
	s_cbranch_scc0 .LBB0_814
	v_lshlrev_b32_e32 v0, 4, v10
	v_add_u32_e32 v1, 0x2000, v0
	v_ashrrev_i32_e32 v2, 31, v1
	v_lshrrev_b32_e32 v2, 22, v2
	v_add_u32_e32 v2, v1, v2
	v_ashrrev_i32_e32 v8, 10, v2
	v_mul_i32_i24_e32 v2, 0x400, v8
	v_sub_u32_e32 v1, v1, v2
	v_lshrrev_b32_e32 v2, 4, v1
	v_bitop3_b32 v1, v2, v1, 32 bitop3:0x6c
	v_ashrrev_i32_e32 v2, 31, v1
	v_lshrrev_b32_e32 v2, 26, v2
	v_add_u32_e32 v2, v1, v2
	v_lshlrev_b32_e32 v3, 3, v8
	v_ashrrev_i32_e32 v9, 6, v2
	v_and_b32_e32 v3, -16, v3
	v_add_u32_e32 v3, v9, v3
	v_and_b32_e32 v4, 3, v9
	s_mov_b32 s1, 0xfffe0
	v_lshrrev_b32_e32 v5, 2, v3
	v_lshlrev_b32_e32 v6, 1, v3
	v_and_b32_e32 v2, 0xc0, v2
	v_and_or_b32 v4, v3, s1, v4
	v_and_b32_e32 v5, 4, v5
	v_and_b32_e32 v6, 24, v6
	v_sub_u32_e32 v1, v1, v2
	v_mov_b32_e32 v2, 1
	v_or3_b32 v4, v4, v5, v6
	v_lshlrev_b32_e32 v5, 5, v8
	v_ashrrev_i16_sdwa v1, v2, sext(v1) dst_sel:DWORD dst_unused:UNUSED_PAD src0_sel:DWORD src1_sel:BYTE_0
	v_and_b32_e32 v5, 32, v5
	v_bfe_i32 v11, v1, 0, 16
	v_add_lshl_u32 v1, v5, v11, 1
	v_lshl_add_u32 v128, v4, 12, v1
	v_lshl_add_u32 v130, v3, 12, v1
	v_bfe_i32 v1, v10, 27, 1
	v_lshrrev_b32_e32 v1, 22, v1
	v_add_u32_e32 v1, v0, v1
	v_and_b32_e32 v1, 0xfffffc00, v1
	v_sub_u32_e32 v0, v0, v1
	v_lshrrev_b32_e32 v1, 4, v0
	v_ashrrev_i32_e32 v3, 31, v10
	v_bitop3_b32 v0, v1, v0, 32 bitop3:0x6c
	v_lshrrev_b32_e32 v3, 26, v3
	v_ashrrev_i32_e32 v1, 31, v0
	v_add_u32_e32 v3, v10, v3
	v_lshrrev_b32_e32 v1, 26, v1
	v_ashrrev_i32_e32 v13, 6, v3
	v_add_u32_e32 v1, v0, v1
	v_lshlrev_b32_e32 v3, 3, v13
	v_ashrrev_i32_e32 v12, 6, v1
	v_and_b32_e32 v3, -16, v3
	v_add_u32_e32 v3, v12, v3
	v_and_b32_e32 v4, 3, v12
	s_add_u32 s27, s58, 0x6000000
	v_and_or_b32 v4, v3, s1, v4
	v_readlane_b32 s1, v247, 8
	s_addc_u32 s28, s59, 0
	s_lshr_b32 s1, s1, 29
	v_readlane_b32 s4, v248, 45
	s_add_i32 s1, s4, s1
	s_and_b32 s2, s1, -8
	s_sub_i32 s2, s4, s2
	s_ashr_i32 s0, s26, 6
	s_mul_i32 s5, s2, 0xdc
	s_ashr_i32 s3, s26, 8
	s_lshl_b32 s29, s0, 10
	s_add_i32 s5, s5, 4
	s_ashr_i32 s1, s1, 3
	s_mul_i32 s4, s2, 0xdd
	s_cmp_lt_i32 s2, 4
	s_cselect_b32 s2, s4, s5
	s_add_i32 s2, s2, s1
	s_mul_hi_i32 s1, s2, 0x5397829d
	s_lshr_b32 s4, s1, 31
	s_ashr_i32 s1, s1, 7
	v_lshrrev_b32_e32 v5, 2, v3
	v_lshlrev_b32_e32 v6, 1, v3
	v_and_b32_e32 v1, 0xc0, v1
	s_add_i32 s1, s1, s4
	v_and_b32_e32 v5, 4, v5
	v_and_b32_e32 v6, 24, v6
	v_sub_u32_e32 v0, v0, v1
	s_lshl_b32 s6, s1, 3
	v_or3_b32 v4, v4, v5, v6
	v_lshlrev_b32_e32 v5, 5, v13
	v_ashrrev_i16_sdwa v0, v2, sext(v0) dst_sel:DWORD dst_unused:UNUSED_PAD src0_sel:DWORD src1_sel:BYTE_0
	s_sub_i32 s4, 36, s6
	s_mulk_i32 s1, 0x188
	v_and_b32_e32 v5, 32, v5
	v_bfe_i32 v14, v0, 0, 16
	s_min_u32 s7, s4, 8
	s_sub_i32 s1, s2, s1
	v_add_lshl_u32 v0, v5, v14, 1
	s_sext_i32_i16 s2, s1
	v_cvt_f32_ubyte0_e32 v2, s7
	v_lshl_add_u32 v132, v4, 12, v0
	v_cvt_f32_i32_e32 v1, s2
	v_rcp_iflag_f32_e32 v4, v2
	v_lshl_add_u32 v134, v3, 12, v0
	s_ashr_i32 s2, s2, 30
	s_or_b32 s2, s2, 1
	v_mul_f32_e32 v0, v1, v4
	v_trunc_f32_e32 v0, v0
	v_fma_f32 v1, -v0, v2, v1
	v_cvt_i32_f32_e32 v0, v0
	v_cmp_ge_f32_e64 s[4:5], |v1|, v2
	s_and_b64 s[4:5], s[4:5], exec
	s_cselect_b32 s2, s2, 0
	v_readfirstlane_b32 s4, v0
	s_add_i32 s2, s4, s2
	s_mul_i32 s4, s2, s7
	s_sub_i32 s1, s1, s4
	s_sext_i32_i16 s1, s1
	s_add_i32 s16, s6, s1
	s_ashr_i32 s17, s16, 31
	s_bfe_i64 s[6:7], s[2:3], 0x100000
	s_lshl_b64 s[4:5], s[16:17], 20
	s_lshl_b64 s[6:7], s[6:7], 20
	s_add_u32 s22, s27, s6
	s_addc_u32 s23, s28, s7
	s_add_i32 s30, s29, 0
	s_add_i32 m0, s30, 0x10000
	v_readlane_b32 s6, v247, 9
	v_mov_b32_e32 v230, s3
	v_lshlrev_b32_e32 v230, 17, v230
	v_add_u32_e32 v132, v132, v230
	v_add_u32_e32 v230, 0x40000, v230
	v_add_u32_e32 v128, v128, v230
	global_load_lds_dwordx4 v132, s[22:23]
	s_add_i32 m0, s30, 0x12000
	v_readlane_b32 s7, v247, 10
	s_add_u32 s20, s6, s4
	global_load_lds_dwordx4 v128, s[22:23]
	s_addc_u32 s21, s7, s5
	s_mov_b32 m0, s30
	s_add_i32 s31, s30, 0x2000
	global_load_lds_dwordx4 v134, s[20:21]
	s_mov_b32 m0, s31
	s_add_u32 s4, s22, 0x20000
	global_load_lds_dwordx4 v130, s[20:21]
	s_addc_u32 s5, s23, 0
	s_add_i32 m0, s30, 0x14000
	v_mov_b32_e32 v133, 0
	global_load_lds_dwordx4 v132, s[4:5]
	s_add_i32 m0, s30, 0x16000
	v_mov_b32_e32 v129, v133
	global_load_lds_dwordx4 v128, s[4:5]
	s_add_u32 s4, s20, 0x80000
	s_addc_u32 s5, s21, 0
	s_add_i32 s34, s30, 0x4000
	s_mov_b32 m0, s34
	s_add_i32 s35, s30, 0x6000
	global_load_lds_dwordx4 v134, s[4:5]
	s_mov_b32 m0, s35
	v_mov_b32_e32 v135, v133
	global_load_lds_dwordx4 v130, s[4:5]
	v_mov_b32_e32 v131, v133
	s_mov_b32 s36, 0
	v_lshl_add_u64 v[6:7], s[22:23], 0, v[132:133]
	v_lshl_add_u64 v[4:5], s[22:23], 0, v[128:129]
	v_lshl_add_u64 v[2:3], s[20:21], 0, v[134:135]
	s_cmp_lg_u32 s3, 1
	v_lshl_add_u64 v[0:1], s[20:21], 0, v[130:131]
	s_cbranch_scc1 .LBB0_795
	s_barrier

.LBB0_804:
	ds_read_b128 v[154:157], v151
	ds_read_b128 v[158:161], v151 offset:1024
	ds_read_b128 v[162:165], v151 offset:2048
	ds_read_b128 v[166:169], v151 offset:3072
	s_add_u32 s22, s20, 0xfff80080
	s_addc_u32 s23, s21, -1
	s_cmp_eq_u32 s45, 28
	s_cselect_b32 s25, s9, s23
	s_cselect_b32 s24, s17, s22
	s_cselect_b32 s23, s7, s44
	s_cselect_b32 s22, s42, s43
	v_lshl_add_u64 v[146:147], s[20:21], 0, v[138:139]
	s_add_i32 m0, s30, 0xc000
	ds_read_b128 v[170:173], v152
	ds_read_b128 v[174:177], v152 offset:1024
	ds_read_b128 v[178:181], v152 offset:2048
	ds_read_b128 v[182:185], v152 offset:3072
	ds_read_b128 v[186:189], v152 offset:4096
	ds_read_b128 v[190:193], v152 offset:5120
	ds_read_b128 v[194:197], v152 offset:6144
	ds_read_b128 v[198:201], v152 offset:7168
	global_load_lds_dwordx4 v[146:147], off
	v_lshl_add_u64 v[146:147], s[20:21], 0, v[140:141]
	s_add_i32 m0, s30, 0xe000
	s_nop 0
	global_load_lds_dwordx4 v[146:147], off
	s_waitcnt lgkmcnt(8)
	s_barrier
	s_waitcnt lgkmcnt(0)
	s_waitcnt lgkmcnt(0)
	v_mfma_f32_16x16x32_bf16 v[124:127], v[154:157], v[170:173], v[124:127]
	v_mfma_f32_16x16x32_bf16 v[120:123], v[162:165], v[170:173], v[120:123]
	v_mfma_f32_16x16x32_bf16 v[116:119], v[154:157], v[178:181], v[116:119]
	v_mfma_f32_16x16x32_bf16 v[112:115], v[162:165], v[178:181], v[112:115]
	v_mfma_f32_16x16x32_bf16 v[100:103], v[154:157], v[186:189], v[100:103]
	v_mfma_f32_16x16x32_bf16 v[96:99], v[162:165], v[186:189], v[96:99]
	v_mfma_f32_16x16x32_bf16 v[84:87], v[154:157], v[194:197], v[84:87]
	v_mfma_f32_16x16x32_bf16 v[80:83], v[162:165], v[194:197], v[80:83]
	v_mfma_f32_16x16x32_bf16 v[124:127], v[158:161], v[174:177], v[124:127]
	v_mfma_f32_16x16x32_bf16 v[120:123], v[166:169], v[174:177], v[120:123]
	v_mfma_f32_16x16x32_bf16 v[116:119], v[158:161], v[182:185], v[116:119]
	v_mfma_f32_16x16x32_bf16 v[112:115], v[166:169], v[182:185], v[112:115]
	v_mfma_f32_16x16x32_bf16 v[100:103], v[158:161], v[190:193], v[100:103]
	v_mfma_f32_16x16x32_bf16 v[96:99], v[166:169], v[190:193], v[96:99]
	v_mfma_f32_16x16x32_bf16 v[84:87], v[158:161], v[198:201], v[84:87]
	v_mfma_f32_16x16x32_bf16 v[80:83], v[166:169], v[198:201], v[80:83]
	s_barrier
	s_add_i32 s46, s39, s29
	v_lshl_add_u64 v[146:147], s[22:23], 0, v[132:133]
	s_mov_b32 m0, s46
	ds_read_b128 v[204:207], v153
	ds_read_b128 v[208:211], v153 offset:1024
	ds_read_b128 v[212:215], v153 offset:2048
	ds_read_b128 v[216:219], v153 offset:3072
	global_load_lds_dwordx4 v[146:147], off
	v_lshl_add_u64 v[220:221], s[22:23], 0, v[128:129]
	s_add_i32 m0, s46, 0x2000
	s_nop 0
	global_load_lds_dwordx4 v[220:221], off
	s_barrier
	s_waitcnt lgkmcnt(0)
	s_waitcnt lgkmcnt(0)
	v_mfma_f32_16x16x32_bf16 v[108:111], v[204:207], v[170:173], v[108:111]
	v_mfma_f32_16x16x32_bf16 v[104:107], v[212:215], v[170:173], v[104:107]
	v_mfma_f32_16x16x32_bf16 v[92:95], v[204:207], v[178:181], v[92:95]
	v_mfma_f32_16x16x32_bf16 v[88:91], v[212:215], v[178:181], v[88:91]
	v_mfma_f32_16x16x32_bf16 v[76:79], v[204:207], v[186:189], v[76:79]
	v_mfma_f32_16x16x32_bf16 v[72:75], v[212:215], v[186:189], v[72:75]
	v_mfma_f32_16x16x32_bf16 v[68:71], v[204:207], v[194:197], v[68:71]
	v_mfma_f32_16x16x32_bf16 v[64:67], v[212:215], v[194:197], v[64:67]
	v_mfma_f32_16x16x32_bf16 v[108:111], v[208:211], v[174:177], v[108:111]
	v_mfma_f32_16x16x32_bf16 v[104:107], v[216:219], v[174:177], v[104:107]
	v_mfma_f32_16x16x32_bf16 v[92:95], v[208:211], v[182:185], v[92:95]
	v_mfma_f32_16x16x32_bf16 v[88:91], v[216:219], v[182:185], v[88:91]
	v_mfma_f32_16x16x32_bf16 v[76:79], v[208:211], v[190:193], v[76:79]
	v_mfma_f32_16x16x32_bf16 v[72:75], v[216:219], v[190:193], v[72:75]
	v_mfma_f32_16x16x32_bf16 v[68:71], v[208:211], v[198:201], v[68:71]
	v_mfma_f32_16x16x32_bf16 v[64:67], v[216:219], v[198:201], v[64:67]
	s_mov_b32 m0, s30
	v_lshl_add_u64 v[222:223], s[24:25], 0, v[134:135]
	s_barrier
	ds_read_b128 v[170:173], v152 offset:16384
	ds_read_b128 v[174:177], v152 offset:17408
	ds_read_b128 v[178:181], v152 offset:18432
	ds_read_b128 v[182:185], v152 offset:19456
	ds_read_b128 v[186:189], v152 offset:20480
	ds_read_b128 v[190:193], v152 offset:21504
	ds_read_b128 v[194:197], v152 offset:22528
	ds_read_b128 v[198:201], v152 offset:23552
	global_load_lds_dwordx4 v[222:223], off
	v_lshl_add_u64 v[224:225], s[24:25], 0, v[130:131]
	s_mov_b32 m0, s31
	s_nop 0
	global_load_lds_dwordx4 v[224:225], off
	s_barrier
	s_waitcnt lgkmcnt(0)
	s_waitcnt lgkmcnt(0)
	v_mfma_f32_16x16x32_bf16 v[60:63], v[154:157], v[170:173], v[60:63]
	v_mfma_f32_16x16x32_bf16 v[56:59], v[162:165], v[170:173], v[56:59]
	v_mfma_f32_16x16x32_bf16 v[52:55], v[154:157], v[178:181], v[52:55]
	v_mfma_f32_16x16x32_bf16 v[48:51], v[162:165], v[178:181], v[48:51]
	v_mfma_f32_16x16x32_bf16 v[36:39], v[154:157], v[186:189], v[36:39]
	v_mfma_f32_16x16x32_bf16 v[32:35], v[162:165], v[186:189], v[32:35]
	v_mfma_f32_16x16x32_bf16 v[20:23], v[154:157], v[194:197], v[20:23]
	v_mfma_f32_16x16x32_bf16 v[16:19], v[162:165], v[194:197], v[16:19]
	v_mfma_f32_16x16x32_bf16 v[60:63], v[158:161], v[174:177], v[60:63]
	v_mfma_f32_16x16x32_bf16 v[56:59], v[166:169], v[174:177], v[56:59]
	v_mfma_f32_16x16x32_bf16 v[52:55], v[158:161], v[182:185], v[52:55]
	v_mfma_f32_16x16x32_bf16 v[48:51], v[166:169], v[182:185], v[48:51]
	v_mfma_f32_16x16x32_bf16 v[36:39], v[158:161], v[190:193], v[36:39]
	v_mfma_f32_16x16x32_bf16 v[32:35], v[166:169], v[190:193], v[32:35]
	v_mfma_f32_16x16x32_bf16 v[20:23], v[158:161], v[198:201], v[20:23]
	v_mfma_f32_16x16x32_bf16 v[16:19], v[166:169], v[198:201], v[16:19]
	s_barrier
	s_add_u32 s46, s22, 0x20000
	s_addc_u32 s47, s23, 0
	s_add_i32 s48, s40, s29
	v_lshl_add_u64 v[154:155], s[46:47], 0, v[132:133]
	s_mov_b32 m0, s48
	s_nop 0
	global_load_lds_dwordx4 v[154:155], off
	v_lshl_add_u64 v[154:155], s[46:47], 0, v[128:129]
	s_add_i32 m0, s48, 0x2000
	s_nop 0
	global_load_lds_dwordx4 v[154:155], off
	s_waitcnt vmcnt(6)
	s_barrier
	v_mfma_f32_16x16x32_bf16 v[44:47], v[204:207], v[170:173], v[44:47]
	v_mfma_f32_16x16x32_bf16 v[40:43], v[212:215], v[170:173], v[40:43]
	v_mfma_f32_16x16x32_bf16 v[28:31], v[204:207], v[178:181], v[28:31]
	v_mfma_f32_16x16x32_bf16 v[24:27], v[212:215], v[178:181], v[24:27]
	v_mfma_f32_16x16x32_bf16 v[12:15], v[204:207], v[186:189], v[12:15]
	v_mfma_f32_16x16x32_bf16 v[8:11], v[212:215], v[186:189], v[8:11]
	v_mfma_f32_16x16x32_bf16 v[4:7], v[204:207], v[194:197], v[4:7]
	v_mfma_f32_16x16x32_bf16 v[0:3], v[212:215], v[194:197], v[0:3]
	v_mfma_f32_16x16x32_bf16 v[44:47], v[208:211], v[174:177], v[44:47]
	v_mfma_f32_16x16x32_bf16 v[40:43], v[216:219], v[174:177], v[40:43]
	v_mfma_f32_16x16x32_bf16 v[28:31], v[208:211], v[182:185], v[28:31]
	v_mfma_f32_16x16x32_bf16 v[24:27], v[216:219], v[182:185], v[24:27]
	v_mfma_f32_16x16x32_bf16 v[12:15], v[208:211], v[190:193], v[12:15]
	v_mfma_f32_16x16x32_bf16 v[8:11], v[216:219], v[190:193], v[8:11]
	v_mfma_f32_16x16x32_bf16 v[4:7], v[208:211], v[198:201], v[4:7]
	v_mfma_f32_16x16x32_bf16 v[0:3], v[216:219], v[198:201], v[0:3]
	s_add_i32 s46, 0, 0x18000
	v_add_u32_e32 v166, s46, v149
	s_barrier
	ds_read_b128 v[154:157], v166
	ds_read_b128 v[158:161], v166 offset:1024
	ds_read_b128 v[162:165], v166 offset:2048
	ds_read_b128 v[166:169], v166 offset:3072
	s_add_u32 s24, s24, 0x80000
	s_addc_u32 s25, s25, 0
	s_mov_b32 m0, s34
	v_lshl_add_u64 v[204:205], s[24:25], 0, v[134:135]
	ds_read_b128 v[170:173], v152 offset:32768
	ds_read_b128 v[174:177], v152 offset:33792
	ds_read_b128 v[178:181], v152 offset:34816
	ds_read_b128 v[182:185], v152 offset:35840
	ds_read_b128 v[186:189], v152 offset:36864
	ds_read_b128 v[190:193], v152 offset:37888
	ds_read_b128 v[194:197], v152 offset:38912
	ds_read_b128 v[198:201], v152 offset:39936
	global_load_lds_dwordx4 v[204:205], off
	v_lshl_add_u64 v[204:205], s[24:25], 0, v[130:131]
	s_mov_b32 m0, s35
	s_nop 0
	global_load_lds_dwordx4 v[204:205], off
	s_waitcnt lgkmcnt(8)
	s_barrier
	s_waitcnt lgkmcnt(0)
	s_waitcnt lgkmcnt(0)
	v_mfma_f32_16x16x32_bf16 v[124:127], v[154:157], v[170:173], v[124:127]
	v_mfma_f32_16x16x32_bf16 v[120:123], v[162:165], v[170:173], v[120:123]
	v_mfma_f32_16x16x32_bf16 v[116:119], v[154:157], v[178:181], v[116:119]
	v_mfma_f32_16x16x32_bf16 v[112:115], v[162:165], v[178:181], v[112:115]
	v_mfma_f32_16x16x32_bf16 v[100:103], v[154:157], v[186:189], v[100:103]
	v_mfma_f32_16x16x32_bf16 v[96:99], v[162:165], v[186:189], v[96:99]
	v_mfma_f32_16x16x32_bf16 v[84:87], v[154:157], v[194:197], v[84:87]
	v_mfma_f32_16x16x32_bf16 v[80:83], v[162:165], v[194:197], v[80:83]
	v_mfma_f32_16x16x32_bf16 v[124:127], v[158:161], v[174:177], v[124:127]
	v_mfma_f32_16x16x32_bf16 v[120:123], v[166:169], v[174:177], v[120:123]
	v_mfma_f32_16x16x32_bf16 v[116:119], v[158:161], v[182:185], v[116:119]
	v_mfma_f32_16x16x32_bf16 v[112:115], v[166:169], v[182:185], v[112:115]
	v_mfma_f32_16x16x32_bf16 v[100:103], v[158:161], v[190:193], v[100:103]
	v_mfma_f32_16x16x32_bf16 v[96:99], v[166:169], v[190:193], v[96:99]
	v_mfma_f32_16x16x32_bf16 v[84:87], v[158:161], v[198:201], v[84:87]
	v_mfma_f32_16x16x32_bf16 v[80:83], v[166:169], v[198:201], v[80:83]
	s_barrier
	s_add_i32 s24, 0, 0x1c000
	s_add_i32 s25, s46, s29
	v_add_u32_e32 v216, s24, v149
	v_lshl_add_u64 v[146:147], v[146:147], 0, s[0:1]
	s_mov_b32 m0, s25
	ds_read_b128 v[204:207], v216
	ds_read_b128 v[208:211], v216 offset:1024
	ds_read_b128 v[212:215], v216 offset:2048
	ds_read_b128 v[216:219], v216 offset:3072
	global_load_lds_dwordx4 v[146:147], off
	v_lshl_add_u64 v[146:147], v[220:221], 0, s[0:1]
	s_add_i32 m0, s25, 0x2000
	s_nop 0
	global_load_lds_dwordx4 v[146:147], off
	s_barrier
	s_waitcnt lgkmcnt(0)
	s_waitcnt lgkmcnt(0)
	v_mfma_f32_16x16x32_bf16 v[108:111], v[204:207], v[170:173], v[108:111]
	v_mfma_f32_16x16x32_bf16 v[104:107], v[212:215], v[170:173], v[104:107]
	v_mfma_f32_16x16x32_bf16 v[92:95], v[204:207], v[178:181], v[92:95]
	v_mfma_f32_16x16x32_bf16 v[88:91], v[212:215], v[178:181], v[88:91]
	v_mfma_f32_16x16x32_bf16 v[76:79], v[204:207], v[186:189], v[76:79]
	v_mfma_f32_16x16x32_bf16 v[72:75], v[212:215], v[186:189], v[72:75]
	v_mfma_f32_16x16x32_bf16 v[68:71], v[204:207], v[194:197], v[68:71]
	v_mfma_f32_16x16x32_bf16 v[64:67], v[212:215], v[194:197], v[64:67]
	v_mfma_f32_16x16x32_bf16 v[108:111], v[208:211], v[174:177], v[108:111]
	v_mfma_f32_16x16x32_bf16 v[104:107], v[216:219], v[174:177], v[104:107]
	v_mfma_f32_16x16x32_bf16 v[92:95], v[208:211], v[182:185], v[92:95]
	v_mfma_f32_16x16x32_bf16 v[88:91], v[216:219], v[182:185], v[88:91]
	v_mfma_f32_16x16x32_bf16 v[76:79], v[208:211], v[190:193], v[76:79]
	v_mfma_f32_16x16x32_bf16 v[72:75], v[216:219], v[190:193], v[72:75]
	v_mfma_f32_16x16x32_bf16 v[68:71], v[208:211], v[198:201], v[68:71]
	v_mfma_f32_16x16x32_bf16 v[64:67], v[216:219], v[198:201], v[64:67]
	s_mov_b32 m0, s37
	v_lshl_add_u64 v[146:147], v[222:223], 0, s[0:1]
	s_barrier
	ds_read_b128 v[170:173], v152 offset:49152
	ds_read_b128 v[174:177], v152 offset:50176
	ds_read_b128 v[178:181], v152 offset:51200
	ds_read_b128 v[182:185], v152 offset:52224
	ds_read_b128 v[186:189], v152 offset:53248
	ds_read_b128 v[190:193], v152 offset:54272
	ds_read_b128 v[194:197], v152 offset:55296
	ds_read_b128 v[198:201], v152 offset:56320
	global_load_lds_dwordx4 v[146:147], off
	v_lshl_add_u64 v[146:147], v[224:225], 0, s[0:1]
	s_mov_b32 m0, s38
	s_nop 0
	global_load_lds_dwordx4 v[146:147], off
	s_barrier
	s_waitcnt lgkmcnt(0)
	s_waitcnt lgkmcnt(0)
	v_mfma_f32_16x16x32_bf16 v[60:63], v[154:157], v[170:173], v[60:63]
	v_mfma_f32_16x16x32_bf16 v[56:59], v[162:165], v[170:173], v[56:59]
	v_mfma_f32_16x16x32_bf16 v[52:55], v[154:157], v[178:181], v[52:55]
	v_mfma_f32_16x16x32_bf16 v[48:51], v[162:165], v[178:181], v[48:51]
	v_mfma_f32_16x16x32_bf16 v[36:39], v[154:157], v[186:189], v[36:39]
	v_mfma_f32_16x16x32_bf16 v[32:35], v[162:165], v[186:189], v[32:35]
	v_mfma_f32_16x16x32_bf16 v[20:23], v[154:157], v[194:197], v[20:23]
	v_mfma_f32_16x16x32_bf16 v[16:19], v[162:165], v[194:197], v[16:19]
	v_mfma_f32_16x16x32_bf16 v[60:63], v[158:161], v[174:177], v[60:63]
	v_mfma_f32_16x16x32_bf16 v[56:59], v[166:169], v[174:177], v[56:59]
	v_mfma_f32_16x16x32_bf16 v[52:55], v[158:161], v[182:185], v[52:55]
	v_mfma_f32_16x16x32_bf16 v[48:51], v[166:169], v[182:185], v[48:51]
	v_mfma_f32_16x16x32_bf16 v[36:39], v[158:161], v[190:193], v[36:39]
	v_mfma_f32_16x16x32_bf16 v[32:35], v[166:169], v[190:193], v[32:35]
	v_mfma_f32_16x16x32_bf16 v[20:23], v[158:161], v[198:201], v[20:23]
	v_mfma_f32_16x16x32_bf16 v[16:19], v[166:169], v[198:201], v[16:19]
	s_barrier
	s_add_u32 s22, s22, 0x20080
	s_addc_u32 s23, s23, 0
	s_add_i32 s24, s24, s29
	v_lshl_add_u64 v[146:147], s[22:23], 0, v[132:133]
	s_mov_b32 m0, s24
	s_nop 0
	global_load_lds_dwordx4 v[146:147], off
	v_lshl_add_u64 v[146:147], s[22:23], 0, v[128:129]
	s_add_i32 m0, s24, 0x2000
	s_nop 0
	global_load_lds_dwordx4 v[146:147], off
	s_waitcnt vmcnt(6)
	s_barrier
	v_mfma_f32_16x16x32_bf16 v[44:47], v[204:207], v[170:173], v[44:47]
	v_mfma_f32_16x16x32_bf16 v[40:43], v[212:215], v[170:173], v[40:43]
	v_mfma_f32_16x16x32_bf16 v[28:31], v[204:207], v[178:181], v[28:31]
	v_mfma_f32_16x16x32_bf16 v[24:27], v[212:215], v[178:181], v[24:27]
	v_mfma_f32_16x16x32_bf16 v[12:15], v[204:207], v[186:189], v[12:15]
	v_mfma_f32_16x16x32_bf16 v[8:11], v[212:215], v[186:189], v[8:11]
	v_mfma_f32_16x16x32_bf16 v[4:7], v[204:207], v[194:197], v[4:7]
	v_mfma_f32_16x16x32_bf16 v[0:3], v[212:215], v[194:197], v[0:3]
	v_mfma_f32_16x16x32_bf16 v[44:47], v[208:211], v[174:177], v[44:47]
	v_mfma_f32_16x16x32_bf16 v[40:43], v[216:219], v[174:177], v[40:43]
	v_mfma_f32_16x16x32_bf16 v[28:31], v[208:211], v[182:185], v[28:31]
	v_mfma_f32_16x16x32_bf16 v[24:27], v[216:219], v[182:185], v[24:27]
	v_mfma_f32_16x16x32_bf16 v[12:15], v[208:211], v[190:193], v[12:15]
	v_mfma_f32_16x16x32_bf16 v[8:11], v[216:219], v[190:193], v[8:11]
	v_mfma_f32_16x16x32_bf16 v[4:7], v[208:211], v[198:201], v[4:7]
	v_mfma_f32_16x16x32_bf16 v[0:3], v[216:219], v[198:201], v[0:3]
	s_add_i32 s45, s45, 2
	s_add_u32 s20, s20, 0x100
	s_addc_u32 s21, s21, 0
	s_add_u32 s43, s43, 0x100
	s_addc_u32 s44, s44, 0
	s_cmp_gt_u32 s45, 29
	s_barrier
	s_cbranch_scc0 .LBB0_804
	v_and_b32_e32 v242, 15, v202
	v_bfe_u32 v243, v202, 4, 2
	v_bfe_u32 v244, v202, 6, 2
	v_lshrrev_b32_e32 v245, 8, v202
	s_cmp_gt_i32 s41, 47
	s_cbranch_scc1 .Lfl8_ba
	s_cmp_gt_i32 s41, 31
	s_cbranch_scc1 .Lfl8_z
	v_readlane_b32 s100, v248, 63
	v_readlane_b32 s101, v247, 0
	v_and_b32_e32 v240, 7, v242
	v_lshl_add_u32 v240, v245, 6, v240
	v_lshl_add_u32 v240, s16, 8, v240
	v_lshlrev_b32_e32 v240, 14, v240
	v_lshrrev_b32_e32 v241, 3, v242
	v_lshlrev_b32_e32 v241, 6, v241
	v_lshl_add_u32 v241, v244, 7, v241
	v_lshl_add_u32 v241, v243, 4, v241
	v_add_u32_e32 v240, v240, v241
	s_lshl_b32 s98, s41, 9
	v_add_u32_e32 v240, s98, v240
	v_cvt_pk_bf16_f32 v228, v124, v125
	v_cvt_pk_bf16_f32 v229, v126, v127
	v_cvt_pk_bf16_f32 v230, v120, v121
	v_cvt_pk_bf16_f32 v231, v122, v123
	v_cvt_pk_bf16_f32 v232, v108, v109
	v_cvt_pk_bf16_f32 v233, v110, v111
	v_cvt_pk_bf16_f32 v234, v104, v105
	v_cvt_pk_bf16_f32 v235, v106, v107
	v_mov_b32_e32 v236, v228
	v_mov_b32_e32 v237, v229
	v_mov_b32_e32 v238, v230
	v_mov_b32_e32 v239, v231
	v_mov_b32_dpp v228, v232 row_ror:8 row_mask:0xf bank_mask:0xc
	v_mov_b32_dpp v229, v233 row_ror:8 row_mask:0xf bank_mask:0xc
	v_mov_b32_dpp v230, v234 row_ror:8 row_mask:0xf bank_mask:0xc
	v_mov_b32_dpp v231, v235 row_ror:8 row_mask:0xf bank_mask:0xc
	v_mov_b32_dpp v232, v236 row_ror:8 row_mask:0xf bank_mask:0x3
	v_mov_b32_dpp v233, v237 row_ror:8 row_mask:0xf bank_mask:0x3
	v_mov_b32_dpp v234, v238 row_ror:8 row_mask:0xf bank_mask:0x3
	v_mov_b32_dpp v235, v239 row_ror:8 row_mask:0xf bank_mask:0x3
	global_store_dwordx4 v240, v[228:231], s[100:101]
	s_add_u32 s100, s100, 0x20000
	s_addc_u32 s101, s101, 0
	global_store_dwordx4 v240, v[232:235], s[100:101]
	v_cvt_pk_bf16_f32 v228, v116, v117
	v_cvt_pk_bf16_f32 v229, v118, v119
	v_cvt_pk_bf16_f32 v230, v112, v113
	v_cvt_pk_bf16_f32 v231, v114, v115
	v_cvt_pk_bf16_f32 v232, v92, v93
	v_cvt_pk_bf16_f32 v233, v94, v95
	v_cvt_pk_bf16_f32 v234, v88, v89
	v_cvt_pk_bf16_f32 v235, v90, v91
	v_mov_b32_e32 v236, v228
	v_mov_b32_e32 v237, v229
	v_mov_b32_e32 v238, v230
	v_mov_b32_e32 v239, v231
	v_mov_b32_dpp v228, v232 row_ror:8 row_mask:0xf bank_mask:0xc
	v_mov_b32_dpp v229, v233 row_ror:8 row_mask:0xf bank_mask:0xc
	v_mov_b32_dpp v230, v234 row_ror:8 row_mask:0xf bank_mask:0xc
	v_mov_b32_dpp v231, v235 row_ror:8 row_mask:0xf bank_mask:0xc
	v_mov_b32_dpp v232, v236 row_ror:8 row_mask:0xf bank_mask:0x3
	v_mov_b32_dpp v233, v237 row_ror:8 row_mask:0xf bank_mask:0x3
	v_mov_b32_dpp v234, v238 row_ror:8 row_mask:0xf bank_mask:0x3
	v_mov_b32_dpp v235, v239 row_ror:8 row_mask:0xf bank_mask:0x3
	s_add_u32 s100, s100, 0x20000
	s_addc_u32 s101, s101, 0
	global_store_dwordx4 v240, v[228:231], s[100:101]
	s_add_u32 s100, s100, 0x20000
	s_addc_u32 s101, s101, 0
	global_store_dwordx4 v240, v[232:235], s[100:101]
	v_cvt_pk_bf16_f32 v228, v100, v101
	v_cvt_pk_bf16_f32 v229, v102, v103
	v_cvt_pk_bf16_f32 v230, v96, v97
	v_cvt_pk_bf16_f32 v231, v98, v99
	v_cvt_pk_bf16_f32 v232, v76, v77
	v_cvt_pk_bf16_f32 v233, v78, v79
	v_cvt_pk_bf16_f32 v234, v72, v73
	v_cvt_pk_bf16_f32 v235, v74, v75
	v_mov_b32_e32 v236, v228
	v_mov_b32_e32 v237, v229
	v_mov_b32_e32 v238, v230
	v_mov_b32_e32 v239, v231
	v_mov_b32_dpp v228, v232 row_ror:8 row_mask:0xf bank_mask:0xc
	v_mov_b32_dpp v229, v233 row_ror:8 row_mask:0xf bank_mask:0xc
	v_mov_b32_dpp v230, v234 row_ror:8 row_mask:0xf bank_mask:0xc
	v_mov_b32_dpp v231, v235 row_ror:8 row_mask:0xf bank_mask:0xc
	v_mov_b32_dpp v232, v236 row_ror:8 row_mask:0xf bank_mask:0x3
	v_mov_b32_dpp v233, v237 row_ror:8 row_mask:0xf bank_mask:0x3
	v_mov_b32_dpp v234, v238 row_ror:8 row_mask:0xf bank_mask:0x3
	v_mov_b32_dpp v235, v239 row_ror:8 row_mask:0xf bank_mask:0x3
	s_add_u32 s100, s100, 0x20000
	s_addc_u32 s101, s101, 0
	global_store_dwordx4 v240, v[228:231], s[100:101]
	s_add_u32 s100, s100, 0x20000
	s_addc_u32 s101, s101, 0
	global_store_dwordx4 v240, v[232:235], s[100:101]
	v_cvt_pk_bf16_f32 v228, v84, v85
	v_cvt_pk_bf16_f32 v229, v86, v87
	v_cvt_pk_bf16_f32 v230, v80, v81
	v_cvt_pk_bf16_f32 v231, v82, v83
	v_cvt_pk_bf16_f32 v232, v68, v69
	v_cvt_pk_bf16_f32 v233, v70, v71
	v_cvt_pk_bf16_f32 v234, v64, v65
	v_cvt_pk_bf16_f32 v235, v66, v67
	v_mov_b32_e32 v236, v228
	v_mov_b32_e32 v237, v229
	v_mov_b32_e32 v238, v230
	v_mov_b32_e32 v239, v231
	v_mov_b32_dpp v228, v232 row_ror:8 row_mask:0xf bank_mask:0xc
	v_mov_b32_dpp v229, v233 row_ror:8 row_mask:0xf bank_mask:0xc
	v_mov_b32_dpp v230, v234 row_ror:8 row_mask:0xf bank_mask:0xc
	v_mov_b32_dpp v231, v235 row_ror:8 row_mask:0xf bank_mask:0xc
	v_mov_b32_dpp v232, v236 row_ror:8 row_mask:0xf bank_mask:0x3
	v_mov_b32_dpp v233, v237 row_ror:8 row_mask:0xf bank_mask:0x3
	v_mov_b32_dpp v234, v238 row_ror:8 row_mask:0xf bank_mask:0x3
	v_mov_b32_dpp v235, v239 row_ror:8 row_mask:0xf bank_mask:0x3
	s_add_u32 s100, s100, 0x20000
	s_addc_u32 s101, s101, 0
	global_store_dwordx4 v240, v[228:231], s[100:101]
	s_add_u32 s100, s100, 0x20000
	s_addc_u32 s101, s101, 0
	global_store_dwordx4 v240, v[232:235], s[100:101]
	v_cvt_pk_bf16_f32 v228, v60, v61
	v_cvt_pk_bf16_f32 v229, v62, v63
	v_cvt_pk_bf16_f32 v230, v56, v57
	v_cvt_pk_bf16_f32 v231, v58, v59
	v_cvt_pk_bf16_f32 v232, v44, v45
	v_cvt_pk_bf16_f32 v233, v46, v47
	v_cvt_pk_bf16_f32 v234, v40, v41
	v_cvt_pk_bf16_f32 v235, v42, v43
	v_mov_b32_e32 v236, v228
	v_mov_b32_e32 v237, v229
	v_mov_b32_e32 v238, v230
	v_mov_b32_e32 v239, v231
	v_mov_b32_dpp v228, v232 row_ror:8 row_mask:0xf bank_mask:0xc
	v_mov_b32_dpp v229, v233 row_ror:8 row_mask:0xf bank_mask:0xc
	v_mov_b32_dpp v230, v234 row_ror:8 row_mask:0xf bank_mask:0xc
	v_mov_b32_dpp v231, v235 row_ror:8 row_mask:0xf bank_mask:0xc
	v_mov_b32_dpp v232, v236 row_ror:8 row_mask:0xf bank_mask:0x3
	v_mov_b32_dpp v233, v237 row_ror:8 row_mask:0xf bank_mask:0x3
	v_mov_b32_dpp v234, v238 row_ror:8 row_mask:0xf bank_mask:0x3
	v_mov_b32_dpp v235, v239 row_ror:8 row_mask:0xf bank_mask:0x3
	s_add_u32 s100, s100, 0x120000
	s_addc_u32 s101, s101, 0
	global_store_dwordx4 v240, v[228:231], s[100:101]
	s_add_u32 s100, s100, 0x20000
	s_addc_u32 s101, s101, 0
	global_store_dwordx4 v240, v[232:235], s[100:101]
	v_cvt_pk_bf16_f32 v228, v52, v53
	v_cvt_pk_bf16_f32 v229, v54, v55
	v_cvt_pk_bf16_f32 v230, v48, v49
	v_cvt_pk_bf16_f32 v231, v50, v51
	v_cvt_pk_bf16_f32 v232, v28, v29
	v_cvt_pk_bf16_f32 v233, v30, v31
	v_cvt_pk_bf16_f32 v234, v24, v25
	v_cvt_pk_bf16_f32 v235, v26, v27
	v_mov_b32_e32 v236, v228
	v_mov_b32_e32 v237, v229
	v_mov_b32_e32 v238, v230
	v_mov_b32_e32 v239, v231
	v_mov_b32_dpp v228, v232 row_ror:8 row_mask:0xf bank_mask:0xc
	v_mov_b32_dpp v229, v233 row_ror:8 row_mask:0xf bank_mask:0xc
	v_mov_b32_dpp v230, v234 row_ror:8 row_mask:0xf bank_mask:0xc
	v_mov_b32_dpp v231, v235 row_ror:8 row_mask:0xf bank_mask:0xc
	v_mov_b32_dpp v232, v236 row_ror:8 row_mask:0xf bank_mask:0x3
	v_mov_b32_dpp v233, v237 row_ror:8 row_mask:0xf bank_mask:0x3
	v_mov_b32_dpp v234, v238 row_ror:8 row_mask:0xf bank_mask:0x3
	v_mov_b32_dpp v235, v239 row_ror:8 row_mask:0xf bank_mask:0x3
	s_add_u32 s100, s100, 0x20000
	s_addc_u32 s101, s101, 0
	global_store_dwordx4 v240, v[228:231], s[100:101]
	s_add_u32 s100, s100, 0x20000
	s_addc_u32 s101, s101, 0
	global_store_dwordx4 v240, v[232:235], s[100:101]
	v_cvt_pk_bf16_f32 v228, v36, v37
	v_cvt_pk_bf16_f32 v229, v38, v39
	v_cvt_pk_bf16_f32 v230, v32, v33
	v_cvt_pk_bf16_f32 v231, v34, v35
	v_cvt_pk_bf16_f32 v232, v12, v13
	v_cvt_pk_bf16_f32 v233, v14, v15
	v_cvt_pk_bf16_f32 v234, v8, v9
	v_cvt_pk_bf16_f32 v235, v10, v11
	v_mov_b32_e32 v236, v228
	v_mov_b32_e32 v237, v229
	v_mov_b32_e32 v238, v230
	v_mov_b32_e32 v239, v231
	v_mov_b32_dpp v228, v232 row_ror:8 row_mask:0xf bank_mask:0xc
	v_mov_b32_dpp v229, v233 row_ror:8 row_mask:0xf bank_mask:0xc
	v_mov_b32_dpp v230, v234 row_ror:8 row_mask:0xf bank_mask:0xc
	v_mov_b32_dpp v231, v235 row_ror:8 row_mask:0xf bank_mask:0xc
	v_mov_b32_dpp v232, v236 row_ror:8 row_mask:0xf bank_mask:0x3
	v_mov_b32_dpp v233, v237 row_ror:8 row_mask:0xf bank_mask:0x3
	v_mov_b32_dpp v234, v238 row_ror:8 row_mask:0xf bank_mask:0x3
	v_mov_b32_dpp v235, v239 row_ror:8 row_mask:0xf bank_mask:0x3
	s_add_u32 s100, s100, 0x20000
	s_addc_u32 s101, s101, 0
	global_store_dwordx4 v240, v[228:231], s[100:101]
	s_add_u32 s100, s100, 0x20000
	s_addc_u32 s101, s101, 0
	global_store_dwordx4 v240, v[232:235], s[100:101]
	v_cvt_pk_bf16_f32 v228, v20, v21
	v_cvt_pk_bf16_f32 v229, v22, v23
	v_cvt_pk_bf16_f32 v230, v16, v17
	v_cvt_pk_bf16_f32 v231, v18, v19
	v_cvt_pk_bf16_f32 v232, v4, v5
	v_cvt_pk_bf16_f32 v233, v6, v7
	v_cvt_pk_bf16_f32 v234, v0, v1
	v_cvt_pk_bf16_f32 v235, v2, v3
	v_mov_b32_e32 v236, v228
	v_mov_b32_e32 v237, v229
	v_mov_b32_e32 v238, v230
	v_mov_b32_e32 v239, v231
	v_mov_b32_dpp v228, v232 row_ror:8 row_mask:0xf bank_mask:0xc
	v_mov_b32_dpp v229, v233 row_ror:8 row_mask:0xf bank_mask:0xc
	v_mov_b32_dpp v230, v234 row_ror:8 row_mask:0xf bank_mask:0xc
	v_mov_b32_dpp v231, v235 row_ror:8 row_mask:0xf bank_mask:0xc
	v_mov_b32_dpp v232, v236 row_ror:8 row_mask:0xf bank_mask:0x3
	v_mov_b32_dpp v233, v237 row_ror:8 row_mask:0xf bank_mask:0x3
	v_mov_b32_dpp v234, v238 row_ror:8 row_mask:0xf bank_mask:0x3
	v_mov_b32_dpp v235, v239 row_ror:8 row_mask:0xf bank_mask:0x3
	s_add_u32 s100, s100, 0x20000
	s_addc_u32 s101, s101, 0
	global_store_dwordx4 v240, v[228:231], s[100:101]
	s_add_u32 s100, s100, 0x20000
	s_addc_u32 s101, s101, 0
	global_store_dwordx4 v240, v[232:235], s[100:101]
	s_branch .Lfl8_done

.LBB0_866:
	s_or_b64 exec, exec, s[0:1]
	s_setprio 0
	v_mov_b32_e32 v32, v202
	s_waitcnt lgkmcnt(0)
	v_mov_b32_e32 v0, v202
	s_barrier
	v_readlane_b32 s0, v247, 6
	v_ashrrev_i32_e32 v0, 6, v0
	v_readlane_b32 s1, v247, 7
	v_add_u32_e32 v105, s0, v0
	s_movk_i32 s0, 0x4800
	v_cmp_gt_i32_e32 vcc, s0, v105
	s_and_saveexec_b64 s[0:1], vcc
	s_xor_b64 s[14:15], exec, s[0:1]
	s_cbranch_execz .LBB0_898
	v_lshlrev_b32_e32 v0, 7, v105
	v_and_b32_e32 v33, 0x1f80, v0
	v_lshlrev_b32_e32 v0, 1, v32
	v_and_b32_e32 v36, 0x78, v0
	v_or_b32_e32 v104, v33, v36
	v_mov_b32_e32 v107, 0
	v_readlane_b32 s16, v248, 29
	v_lshlrev_b32_e32 v34, 2, v104
	v_mov_b32_e32 v35, v107
	v_readlane_b32 s22, v248, 35
	v_readlane_b32 s23, v248, 36
	s_mov_b64 s[0:1], 0x18000
	v_readlane_b32 s17, v248, 30
	v_lshl_add_u64 v[16:17], s[22:23], 0, v[34:35]
	v_lshl_add_u64 v[4:5], v[16:17], 0, s[0:1]
	s_mov_b32 s0, 0x18000
	v_add_co_u32_e32 v0, vcc, s0, v16
	s_mov_b32 s0, 0x10000
	s_nop 0
	v_addc_co_u32_e32 v1, vcc, 0, v17, vcc
	v_readlane_b32 s18, v248, 31
	v_readlane_b32 s19, v248, 32
	v_add_co_u32_e32 v8, vcc, s0, v16
	s_mov_b64 s[16:17], 0x10000
	s_nop 0
	v_addc_co_u32_e32 v9, vcc, 0, v17, vcc
	s_mov_b64 s[18:19], 0x8000
	s_mov_b32 s0, 0x8000
	v_lshl_add_u64 v[12:13], v[16:17], 0, s[16:17]
	v_lshl_add_u64 v[20:21], v[16:17], 0, s[18:19]
	v_add_co_u32_e32 v16, vcc, s0, v16
	global_load_dwordx4 v[0:3], v[0:1], off
	s_nop 0
	global_load_dwordx4 v[4:7], v[4:5], off offset:16
	v_addc_co_u32_e32 v17, vcc, 0, v17, vcc
	global_load_dwordx4 v[8:11], v[8:9], off
	s_nop 0
	global_load_dwordx4 v[12:15], v[12:13], off offset:16
	s_nop 0
	global_load_dwordx4 v[16:19], v[16:17], off
	s_nop 0
	global_load_dwordx4 v[20:23], v[20:21], off offset:16
	s_nop 0
	global_load_dwordx4 v[24:27], v34, s[22:23]
	global_load_dwordx4 v[28:31], v34, s[22:23] offset:16
	v_readlane_b32 s0, v248, 63
	v_lshlrev_b32_e32 v106, 1, v104
	v_readlane_b32 s1, v247, 0
	v_readlane_b32 s36, v248, 13
	v_lshlrev_b32_e32 v32, 3, v32
	v_lshl_add_u64 v[108:109], s[0:1], 0, v[106:107]
	s_movk_i32 s0, 0x1000
	v_cmp_gt_u32_e64 s[2:3], s0, v33
	s_movk_i32 s0, 0xfff
	v_cmp_lt_u32_e64 s[4:5], s0, v33
	s_movk_i32 s0, 0x7ff
	v_cmp_lt_u32_e64 s[6:7], s0, v33
	s_movk_i32 s0, 0x800
	v_readlane_b32 s42, v248, 19
	v_readlane_b32 s43, v248, 20
	v_and_b32_e32 v148, 24, v32
	v_mov_b32_e32 v32, 0x3db504f3
	v_cmp_gt_u32_e32 vcc, s0, v33
	v_lshl_add_u64 v[110:111], s[42:43], 0, v[34:35]
	v_lshlrev_b32_e32 v34, 7, v36
	v_cndmask_b32_e32 v149, 1.0, v32, vcc
	v_add_u32_e32 v32, 0xfffff000, v104
	v_lshl_add_u64 v[34:35], s[58:59], 0, v[34:35]
	s_mov_b64 s[0:1], 0x2bb40000
	v_ashrrev_i32_e32 v33, 31, v32
	v_ashrrev_i32_e32 v150, 7, v32
	v_lshl_add_u64 v[112:113], v[34:35], 0, s[0:1]
	v_lshl_add_u64 v[32:33], v[32:33], 1, s[58:59]
	s_mov_b64 s[0:1], 0x29340000
	v_lshl_add_u64 v[114:115], v[32:33], 0, s[0:1]
	v_add_u32_e32 v32, 0xfffff800, v104
	v_mov_b32_e32 v33, v107
	v_lshl_add_u64 v[36:37], v[32:33], 1, s[58:59]
	s_mov_b64 s[0:1], 0x26f40000
	v_lshl_add_u64 v[116:117], v[36:37], 0, s[0:1]
	s_mov_b64 s[0:1], 0x29b40000
	v_readlane_b32 s20, v248, 33
	v_readlane_b32 s21, v248, 34
	v_readlane_b32 s28, v248, 41
	v_readlane_b32 s29, v248, 42
	v_readlane_b32 s30, v248, 43
	v_readlane_b32 s31, v248, 44
	v_lshrrev_b32_e32 v151, 7, v32
	v_lshl_add_u64 v[118:119], v[34:35], 0, s[0:1]
	v_lshl_add_u64 v[32:33], s[58:59], 0, v[106:107]
	s_mov_b64 s[0:1], 0x24b40000
	v_lshl_add_u64 v[120:121], v[32:33], 0, s[0:1]
	s_mov_b64 s[20:21], 0
	s_movk_i32 s23, 0xffe0
	s_movk_i32 s28, 0x1fff
	s_movk_i32 s29, 0x2000
	s_movk_i32 s30, 0x7f8
	s_movk_i32 s31, 0x8000
	s_movk_i32 s34, 0xc000
	s_mov_b32 s22, 0x358637bd
	s_mov_b32 s35, 0x800000
	s_movk_i32 s36, 0x47ff
	v_mov_b32_e32 v152, 0x1204000
	v_mov_b32_e32 v153, 0x149c000
	v_mbcnt_hi_u32_b32 v154, -1, v203
	v_readlane_b32 s24, v248, 37
	v_readlane_b32 s25, v248, 38
	v_readlane_b32 s26, v248, 39
	v_readlane_b32 s27, v248, 40
	v_readlane_b32 s37, v248, 14
	v_readlane_b32 s38, v248, 15
	v_readlane_b32 s39, v248, 16
	v_readlane_b32 s40, v248, 17
	v_readlane_b32 s41, v248, 18
	v_readlane_b32 s44, v248, 21
	v_readlane_b32 s45, v248, 22
	v_readlane_b32 s46, v248, 23
	v_readlane_b32 s47, v248, 24
	v_readlane_b32 s48, v248, 25
	v_readlane_b32 s49, v248, 26
	v_readlane_b32 s50, v248, 27
	v_readlane_b32 s51, v248, 28
	s_branch .LBB0_869

.LBB0_953:
	s_or_b64 exec, exec, s[0:1]
	s_setprio 0
	s_add_u32 s62, s58, 0x2fb40000
	s_addc_u32 s63, s59, 0
	s_add_u32 s80, s58, 0x2fc60000
	s_addc_u32 s81, s59, 0
	s_add_u32 s82, s58, 0x24b40000
	s_addc_u32 s83, s59, 0
	s_add_u32 s84, s58, 0x26f40000
	v_mov_b32_e32 v1, v202
	s_waitcnt lgkmcnt(0)
	v_mov_b32_e32 v0, v202
	s_addc_u32 s85, s59, 0
	s_barrier
	s_add_u32 s86, s58, 0x29b40000
	v_ashrrev_i32_e32 v0, 6, v0
	s_addc_u32 s87, s59, 0
	v_readlane_b32 s0, v247, 6
	s_add_u32 s64, s58, 0x2fd80000
	s_addc_u32 s65, s59, 0
	v_add_u32_e32 v164, s0, v0
	s_movk_i32 s0, 0x1000
	v_cmp_gt_i32_e32 vcc, s0, v164
	v_readlane_b32 s1, v247, 7
	s_and_saveexec_b64 s[0:1], vcc
	s_xor_b64 s[0:1], exec, s[0:1]
	v_writelane_b32 v247, s0, 19
	s_nop 1
	v_writelane_b32 v247, s1, 20
	s_cbranch_execz .LBB0_957
	v_readlane_b32 s0, v247, 6
	v_readlane_b32 s1, v247, 7
	v_writelane_b32 v246, s61, 11
	s_mov_b32 s2, s0
	s_ashr_i32 s3, s0, 31
	v_writelane_b32 v247, s0, 6
	s_ashr_i32 s61, s60, 31
	v_and_b32_e32 v165, 63, v1
	v_writelane_b32 v247, s1, 7
	s_lshl_b64 s[0:1], s[60:61], 13
	v_writelane_b32 v246, s0, 7
	v_writelane_b32 v247, s56, 61
	v_ashrrev_i32_e32 v1, 31, v0
	v_writelane_b32 v246, s1, 8
	s_lshl_b64 s[0:1], s[60:61], 14
	v_writelane_b32 v246, s0, 9
	v_lshl_add_u32 v166, v0, 14, 0
	v_lshl_add_u64 v[0:1], v[0:1], 0, s[2:3]
	v_writelane_b32 v246, s1, 10
	v_writelane_b32 v246, s59, 0
	v_writelane_b32 v246, s60, 3
	v_mbcnt_hi_u32_b32 v167, -1, v203
	v_writelane_b32 v247, s57, 62
	v_writelane_b32 v246, s61, 4
	v_writelane_b32 v246, s62, 5
	v_lshlrev_b64 v[140:141], 13, v[0:1]
	v_lshlrev_b64 v[142:143], 14, v[0:1]
	v_writelane_b32 v246, s63, 6
	v_writelane_b32 v246, s64, 1
	s_mov_b64 s[0:1], 0
	v_add_u32_e32 v168, -1, v167
	v_and_b32_e32 v169, 64, v167
	v_add_u32_e32 v170, -2, v167
	v_add_u32_e32 v171, -4, v167
	v_add_u32_e32 v172, -8, v167
	v_add_u32_e32 v173, -16, v167
	v_subrev_u32_e32 v174, 32, v167
	v_mov_b32_e32 v145, 0
	v_writelane_b32 v247, s58, 63
	v_writelane_b32 v246, s65, 2

.LBB0_1009:
	s_or_b64 exec, exec, s[0:1]
	s_setprio 0
	v_readlane_b32 s0, v248, 45
	s_and_b32 s37, s0, 31
	s_lshl_b32 s2, s0, 7
	s_lshl_b32 s16, s37, 7
	s_and_b32 s36, s2, 0xf80
	s_cmpk_gt_i32 s0, 0x7f
	s_mov_b64 s[0:1], -1
	s_waitcnt lgkmcnt(0)
	s_barrier
	s_cbranch_scc0 .LBB0_1173
	v_readlane_b32 s0, v248, 45
	s_add_i32 s6, s0, 0xffffff80
	s_cmpk_lt_u32 s6, 0x1000
	s_cselect_b64 s[0:1], -1, 0
	s_lshr_b32 s12, s6, 2
	s_add_u32 s8, s58, 0x29340000
	s_addc_u32 s9, s59, 0
	s_add_u32 s10, s58, 0x20100000
	s_addc_u32 s11, s59, 0
	s_cmpk_gt_u32 s6, 0xfff
	v_mov_b32_e32 v129, v202
	s_cbranch_scc1 .LBB0_1014
	v_readlane_b32 s40, v248, 13
	s_and_b32 s14, s12, 0x3f8
	v_readlane_b32 s48, v248, 21
	v_readlane_b32 s49, v248, 22
	s_lshl_b32 s4, s6, 16
	s_or_b32 s13, s14, 0x2000
	v_ashrrev_i32_e32 v42, 6, v129
	s_mov_b64 s[20:21], s[48:49]
	s_add_u32 s4, s20, s4
	v_lshlrev_b32_e32 v32, 4, v42
	s_addc_u32 s5, s21, 0
	v_ashrrev_i32_e32 v33, 31, v32
	v_and_b32_e32 v36, 15, v129
	v_lshl_add_u64 v[0:1], v[32:33], 2, s[4:5]
	v_and_b32_e32 v34, 48, v129
	v_mov_b32_e32 v35, 0
	v_lshl_add_u64 v[0:1], v[0:1], 0, v[34:35]
	v_lshlrev_b32_e32 v34, 9, v36
	s_movk_i32 s7, 0x2000
	v_lshl_add_u64 v[0:1], v[0:1], 0, v[34:35]
	v_add_co_u32_e32 v2, vcc, s7, v0
	s_movk_i32 s4, 0x4000
	s_nop 0
	v_addc_co_u32_e32 v3, vcc, 0, v1, vcc
	global_load_dwordx4 v[28:31], v[0:1], off
	global_load_dwordx4 v[24:27], v[2:3], off
	v_add_co_u32_e32 v2, vcc, s4, v0
	s_movk_i32 s4, 0x6000
	s_nop 0
	v_addc_co_u32_e32 v3, vcc, 0, v1, vcc
	v_add_co_u32_e32 v4, vcc, s4, v0
	s_mov_b32 s4, 0x8000
	s_nop 0
	v_addc_co_u32_e32 v5, vcc, 0, v1, vcc
	global_load_dwordx4 v[20:23], v[2:3], off
	global_load_dwordx4 v[16:19], v[4:5], off
	v_add_co_u32_e32 v2, vcc, s4, v0
	s_mov_b32 s4, 0xa000
	s_nop 0
	v_addc_co_u32_e32 v3, vcc, 0, v1, vcc
	v_add_co_u32_e32 v4, vcc, s4, v0
	v_add_u32_e32 v38, s13, v42
	s_nop 0
	v_addc_co_u32_e32 v5, vcc, 0, v1, vcc
	s_mov_b32 s4, 0xc000
	v_ashrrev_i32_e32 v39, 31, v38
	v_add_u32_e32 v42, s14, v42
	global_load_dwordx4 v[12:15], v[2:3], off
	global_load_dwordx4 v[8:11], v[4:5], off
	v_add_co_u32_e32 v2, vcc, s4, v0
	v_lshlrev_b64 v[38:39], 12, v[38:39]
	v_ashrrev_i32_e32 v43, 31, v42
	s_mov_b32 s3, 0
	v_and_b32_e32 v37, 63, v129
	v_addc_co_u32_e32 v3, vcc, 0, v1, vcc
	s_mov_b32 s4, 0xe000
	v_lshl_add_u64 v[40:41], s[84:85], 0, v[38:39]
	s_and_b32 s2, s2, 0xf00
	v_lshl_add_u64 v[38:39], s[82:83], 0, v[38:39]
	v_lshlrev_b64 v[42:43], 13, v[42:43]
	v_add_co_u32_e32 v0, vcc, s4, v0
	v_lshl_add_u64 v[40:41], v[40:41], 0, s[2:3]
	v_lshlrev_b32_e32 v34, 2, v37
	v_lshl_add_u64 v[38:39], v[38:39], 0, s[2:3]
	v_lshl_add_u64 v[42:43], s[8:9], 0, v[42:43]
	s_lshl_b32 s2, s16, 1
	v_addc_co_u32_e32 v1, vcc, 0, v1, vcc
	v_lshl_add_u64 v[40:41], v[40:41], 0, v[34:35]
	v_lshl_add_u64 v[42:43], v[42:43], 0, s[2:3]
	global_load_dwordx4 v[4:7], v[2:3], off
	s_nop 0
	global_load_dwordx4 v[0:3], v[0:1], off
	v_lshl_add_u64 v[38:39], v[38:39], 0, v[34:35]
	v_lshl_add_u64 v[42:43], v[42:43], 0, v[34:35]
	global_load_dword v131, v[40:41], off
	global_load_dword v133, v[38:39], off
	global_load_dword v132, v[42:43], off
	v_bfe_u32 v34, v129, 4, 2
	v_cmp_gt_i32_e32 vcc, 8, v129
	v_mov_b32_e32 v130, 0
	v_mov_b32_e32 v134, 0
	v_readlane_b32 s41, v248, 14
	v_readlane_b32 s42, v248, 15
	v_readlane_b32 s43, v248, 16
	v_readlane_b32 s44, v248, 17
	v_readlane_b32 s45, v248, 18
	v_readlane_b32 s46, v248, 19
	v_readlane_b32 s47, v248, 20
	v_readlane_b32 s50, v248, 23
	v_readlane_b32 s51, v248, 24
	v_readlane_b32 s52, v248, 25
	v_readlane_b32 s53, v248, 26
	v_readlane_b32 s54, v248, 27
	v_readlane_b32 s55, v248, 28
	s_and_saveexec_b64 s[4:5], vcc
	s_cbranch_execz .LBB0_1013
	v_add_u32_e32 v38, s13, v129
	v_ashrrev_i32_e32 v39, 31, v38
	v_lshlrev_b64 v[38:39], 7, v[38:39]
	v_lshl_or_b32 v38, s37, 2, v38
	v_lshl_add_u64 v[40:41], s[80:81], 0, v[38:39]
	v_lshl_add_u64 v[38:39], s[62:63], 0, v[38:39]
	global_load_dword v134, v[40:41], off
	global_load_dword v130, v[38:39], off

.Lprio_skip_11:
	v_readlane_b32 s0, v247, 17
	s_mul_hi_u32 s0, s0, 0x4800
	v_readlane_b32 s4, v247, 18
	s_mul_i32 s1, s0, s4
	s_sub_i32 s1, 0x4800, s1
	s_add_i32 s2, s0, 1
	s_sub_i32 s3, s1, s4
	s_cmp_ge_u32 s1, s4
	s_cselect_b32 s0, s2, s0
	s_cselect_b32 s1, s3, s1
	s_add_i32 s2, s0, 1
	s_cmp_ge_u32 s1, s4
	s_cselect_b32 s0, s2, s0
	v_readlane_b32 s1, v247, 11
	s_xor_b32 s0, s0, s1
	s_sub_i32 s0, s0, s1
	v_mov_b32_e32 v8, v202
	s_waitcnt lgkmcnt(0)
	s_barrier
	s_cmp_gt_i32 s0, 0
	s_nop 0
	v_readfirstlane_b32 s24, v8
	s_cbranch_scc0 .LBB0_1413
	v_lshlrev_b32_e32 v0, 4, v8
	v_add_u32_e32 v1, 0x2000, v0
	v_ashrrev_i32_e32 v2, 31, v1
	v_lshrrev_b32_e32 v2, 22, v2
	v_readlane_b32 s1, v248, 45
	v_add_u32_e32 v2, v1, v2
	s_mul_i32 s1, s0, s1
	v_ashrrev_i32_e32 v9, 10, v2
	s_ashr_i32 s2, s1, 31
	s_mul_hi_i32 s3, s1, 0x38e38e39
	v_mul_i32_i24_e32 v2, 0x400, v9
	s_lshr_b32 s2, s2, 26
	s_lshr_b32 s4, s3, 31
	s_ashr_i32 s3, s3, 7
	v_sub_u32_e32 v1, v1, v2
	s_add_i32 s6, s1, s2
	s_add_i32 s3, s3, s4
	v_lshrrev_b32_e32 v2, 4, v1
	s_ashr_i32 s2, s6, 6
	s_mul_i32 s4, s3, -9
	v_bitop3_b32 v1, v2, v1, 32 bitop3:0x6c
	s_add_i32 s4, s4, s2
	v_ashrrev_i32_e32 v2, 31, v1
	s_and_b32 s38, s3, 7
	s_lshl_b32 s2, s4, 2
	s_ashr_i32 s3, s3, 3
	v_lshrrev_b32_e32 v2, 26, v2
	s_andn2_b32 s6, s6, 63
	s_add_i32 s2, s2, s3
	v_add_u32_e32 v2, v1, v2
	v_lshlrev_b32_e32 v3, 3, v9
	s_add_u32 s25, s58, 0x9100000
	v_ashrrev_i32_e32 v10, 6, v2
	v_and_b32_e32 v3, -16, v3
	s_addc_u32 s26, s59, 0
	s_ashr_i32 s3, s2, 31
	v_add_u32_e32 v3, v10, v3
	s_lshl_b64 s[10:11], s[2:3], 21
	v_and_b32_e32 v4, 3, v10
	s_mov_b32 s3, 0x7ffe0
	v_lshrrev_b32_e32 v5, 2, v3
	v_lshlrev_b32_e32 v6, 1, v3
	v_and_b32_e32 v2, 0xc0, v2
	v_and_or_b32 v4, v3, s3, v4
	v_and_b32_e32 v5, 4, v5
	v_and_b32_e32 v6, 24, v6
	v_sub_u32_e32 v1, v1, v2
	v_mov_b32_e32 v2, 1
	v_or3_b32 v4, v4, v5, v6
	v_lshlrev_b32_e32 v5, 5, v9
	v_ashrrev_i16_sdwa v1, v2, sext(v1) dst_sel:DWORD dst_unused:UNUSED_PAD src0_sel:DWORD src1_sel:BYTE_0
	v_and_b32_e32 v5, 32, v5
	v_bfe_i32 v11, v1, 0, 16
	v_add_lshl_u32 v1, v5, v11, 1
	v_lshl_add_u32 v128, v4, 13, v1
	v_lshl_add_u32 v130, v3, 13, v1
	v_bfe_i32 v1, v8, 27, 1
	v_lshrrev_b32_e32 v1, 22, v1
	v_add_u32_e32 v1, v0, v1
	v_and_b32_e32 v1, 0xfffffc00, v1
	v_sub_u32_e32 v0, v0, v1
	v_lshrrev_b32_e32 v1, 4, v0
	v_ashrrev_i32_e32 v3, 31, v8
	v_bitop3_b32 v0, v1, v0, 32 bitop3:0x6c
	v_lshrrev_b32_e32 v3, 26, v3
	v_ashrrev_i32_e32 v1, 31, v0
	v_add_u32_e32 v3, v8, v3
	v_lshrrev_b32_e32 v1, 26, v1
	v_ashrrev_i32_e32 v13, 6, v3
	v_add_u32_e32 v1, v0, v1
	v_lshlrev_b32_e32 v3, 3, v13
	s_sub_i32 s8, s1, s6
	v_ashrrev_i32_e32 v12, 6, v1
	v_and_b32_e32 v3, -16, v3
	s_ashr_i32 s5, s24, 6
	s_ashr_i32 s9, s8, 31
	v_add_u32_e32 v3, v12, v3
	s_ashr_i32 s4, s24, 8
	s_lshl_b32 s27, s5, 10
	s_lshl_b32 s7, s38, 21
	s_lshl_b64 s[8:9], s[8:9], 7
	v_and_b32_e32 v4, 3, v12
	v_lshrrev_b32_e32 v5, 2, v3
	v_lshlrev_b32_e32 v6, 1, v3
	v_and_b32_e32 v1, 0xc0, v1
	v_and_or_b32 v4, v3, s3, v4
	v_and_b32_e32 v5, 4, v5
	v_and_b32_e32 v6, 24, v6
	v_sub_u32_e32 v0, v0, v1
	s_add_u32 s3, s25, s7
	v_or3_b32 v4, v4, v5, v6
	v_lshlrev_b32_e32 v5, 5, v13
	v_ashrrev_i16_sdwa v0, v2, sext(v0) dst_sel:DWORD dst_unused:UNUSED_PAD src0_sel:DWORD src1_sel:BYTE_0
	s_addc_u32 s7, s26, 0
	v_and_b32_e32 v5, 32, v5
	v_bfe_i32 v14, v0, 0, 16
	s_add_u32 s20, s3, s8
	v_add_lshl_u32 v0, v5, v14, 1
	s_addc_u32 s21, s7, s9
	s_add_i32 s3, s27, 0
	v_lshl_add_u32 v132, v4, 13, v0
	s_add_i32 m0, s3, 0x10000
	v_readlane_b32 s12, v247, 9
	v_mov_b32_e32 v230, s4
	v_lshlrev_b32_e32 v230, 18, v230
	v_add_u32_e32 v132, v132, v230
	v_add_u32_e32 v230, 0x80000, v230
	v_add_u32_e32 v128, v128, v230
	global_load_lds_dwordx4 v132, s[20:21]
	s_add_i32 m0, s3, 0x12000
	v_readlane_b32 s13, v247, 10
	s_add_u32 s7, s12, s10
	s_addc_u32 s10, s13, s11
	s_add_u32 s18, s7, s8
	v_lshl_add_u32 v134, v3, 13, v0
	global_load_lds_dwordx4 v128, s[20:21]
	s_addc_u32 s19, s10, s9
	s_mov_b32 m0, s3
	s_add_i32 s28, s3, 0x2000
	global_load_lds_dwordx4 v134, s[18:19]
	s_mov_b32 m0, s28
	s_add_u32 s8, s20, 0x40000
	global_load_lds_dwordx4 v130, s[18:19]
	s_addc_u32 s9, s21, 0
	s_add_i32 m0, s3, 0x14000
	v_mov_b32_e32 v133, 0
	global_load_lds_dwordx4 v132, s[8:9]
	s_add_i32 m0, s3, 0x16000
	v_mov_b32_e32 v129, v133
	global_load_lds_dwordx4 v128, s[8:9]
	s_add_u32 s8, s18, 0x100000
	s_addc_u32 s9, s19, 0
	s_add_i32 s29, s3, 0x4000
	s_mov_b32 m0, s29
	s_add_i32 s30, s3, 0x6000
	global_load_lds_dwordx4 v134, s[8:9]
	s_mov_b32 m0, s30
	v_mov_b32_e32 v135, v133
	global_load_lds_dwordx4 v130, s[8:9]
	v_mov_b32_e32 v131, v133
	v_lshl_add_u64 v[6:7], s[20:21], 0, v[132:133]
	v_lshl_add_u64 v[4:5], s[20:21], 0, v[128:129]
	v_lshl_add_u64 v[2:3], s[18:19], 0, v[134:135]
	s_cmp_lg_u32 s4, 1
	v_lshl_add_u64 v[0:1], s[18:19], 0, v[130:131]
	s_cbranch_scc1 .LBB0_1402
	s_barrier

.LBB0_1409:
	ds_read_b128 v[146:149], v143
	ds_read_b128 v[150:153], v143 offset:1024
	ds_read_b128 v[154:157], v143 offset:2048
	ds_read_b128 v[158:161], v143 offset:3072
	s_add_i32 s51, s20, 2
	s_add_u32 s21, s18, 0xfff00080
	s_addc_u32 s22, s19, -1
	s_cmp_eq_u32 s48, s20
	s_cselect_b32 s20, s47, s49
	s_cselect_b32 s23, s7, s22
	s_cselect_b32 s22, s9, s21
	s_cselect_b32 s21, s46, s50
	v_lshl_add_u64 v[194:195], s[18:19], 0, v[136:137]
	s_add_i32 m0, s3, 0xc000
	ds_read_b128 v[162:165], v144
	ds_read_b128 v[166:169], v144 offset:1024
	ds_read_b128 v[170:173], v144 offset:2048
	ds_read_b128 v[174:177], v144 offset:3072
	ds_read_b128 v[178:181], v144 offset:4096
	ds_read_b128 v[182:185], v144 offset:5120
	ds_read_b128 v[186:189], v144 offset:6144
	ds_read_b128 v[190:193], v144 offset:7168
	global_load_lds_dwordx4 v[194:195], off
	v_lshl_add_u64 v[194:195], s[18:19], 0, v[138:139]
	s_add_i32 m0, s3, 0xe000
	s_nop 0
	global_load_lds_dwordx4 v[194:195], off
	s_waitcnt lgkmcnt(8)
	s_barrier
	s_waitcnt lgkmcnt(0)
	s_waitcnt lgkmcnt(0)
	v_mfma_f32_16x16x32_bf16 v[124:127], v[146:149], v[162:165], v[124:127]
	v_mfma_f32_16x16x32_bf16 v[120:123], v[154:157], v[162:165], v[120:123]
	v_mfma_f32_16x16x32_bf16 v[108:111], v[146:149], v[170:173], v[108:111]
	v_mfma_f32_16x16x32_bf16 v[104:107], v[154:157], v[170:173], v[104:107]
	v_mfma_f32_16x16x32_bf16 v[92:95], v[146:149], v[178:181], v[92:95]
	v_mfma_f32_16x16x32_bf16 v[88:91], v[154:157], v[178:181], v[88:91]
	v_mfma_f32_16x16x32_bf16 v[76:79], v[146:149], v[186:189], v[76:79]
	v_mfma_f32_16x16x32_bf16 v[72:75], v[154:157], v[186:189], v[72:75]
	v_mfma_f32_16x16x32_bf16 v[124:127], v[150:153], v[166:169], v[124:127]
	v_mfma_f32_16x16x32_bf16 v[120:123], v[158:161], v[166:169], v[120:123]
	v_mfma_f32_16x16x32_bf16 v[108:111], v[150:153], v[174:177], v[108:111]
	v_mfma_f32_16x16x32_bf16 v[104:107], v[158:161], v[174:177], v[104:107]
	v_mfma_f32_16x16x32_bf16 v[92:95], v[150:153], v[182:185], v[92:95]
	v_mfma_f32_16x16x32_bf16 v[88:91], v[158:161], v[182:185], v[88:91]
	v_mfma_f32_16x16x32_bf16 v[76:79], v[150:153], v[190:193], v[76:79]
	v_mfma_f32_16x16x32_bf16 v[72:75], v[158:161], v[190:193], v[72:75]
	s_barrier
	s_add_i32 s52, s39, s27
	v_lshl_add_u64 v[212:213], s[20:21], 0, v[132:133]
	s_mov_b32 m0, s52
	ds_read_b128 v[194:197], v145
	ds_read_b128 v[198:201], v145 offset:1024
	ds_read_b128 v[204:207], v145 offset:2048
	ds_read_b128 v[208:211], v145 offset:3072
	global_load_lds_dwordx4 v[212:213], off
	v_lshl_add_u64 v[214:215], s[20:21], 0, v[128:129]
	s_add_i32 m0, s52, 0x2000
	s_nop 0
	global_load_lds_dwordx4 v[214:215], off
	s_barrier
	s_waitcnt lgkmcnt(0)
	s_waitcnt lgkmcnt(0)
	v_mfma_f32_16x16x32_bf16 v[116:119], v[194:197], v[162:165], v[116:119]
	v_mfma_f32_16x16x32_bf16 v[112:115], v[204:207], v[162:165], v[112:115]
	v_mfma_f32_16x16x32_bf16 v[100:103], v[194:197], v[170:173], v[100:103]
	v_mfma_f32_16x16x32_bf16 v[96:99], v[204:207], v[170:173], v[96:99]
	v_mfma_f32_16x16x32_bf16 v[84:87], v[194:197], v[178:181], v[84:87]
	v_mfma_f32_16x16x32_bf16 v[80:83], v[204:207], v[178:181], v[80:83]
	v_mfma_f32_16x16x32_bf16 v[68:71], v[194:197], v[186:189], v[68:71]
	v_mfma_f32_16x16x32_bf16 v[64:67], v[204:207], v[186:189], v[64:67]
	v_mfma_f32_16x16x32_bf16 v[116:119], v[198:201], v[166:169], v[116:119]
	v_mfma_f32_16x16x32_bf16 v[112:115], v[208:211], v[166:169], v[112:115]
	v_mfma_f32_16x16x32_bf16 v[100:103], v[198:201], v[174:177], v[100:103]
	v_mfma_f32_16x16x32_bf16 v[96:99], v[208:211], v[174:177], v[96:99]
	v_mfma_f32_16x16x32_bf16 v[84:87], v[198:201], v[182:185], v[84:87]
	v_mfma_f32_16x16x32_bf16 v[80:83], v[208:211], v[182:185], v[80:83]
	v_mfma_f32_16x16x32_bf16 v[68:71], v[198:201], v[190:193], v[68:71]
	v_mfma_f32_16x16x32_bf16 v[64:67], v[208:211], v[190:193], v[64:67]
	s_mov_b32 m0, s3
	v_lshl_add_u64 v[216:217], s[22:23], 0, v[134:135]
	s_barrier
	ds_read_b128 v[162:165], v144 offset:16384
	ds_read_b128 v[166:169], v144 offset:17408
	ds_read_b128 v[170:173], v144 offset:18432
	ds_read_b128 v[174:177], v144 offset:19456
	ds_read_b128 v[178:181], v144 offset:20480
	ds_read_b128 v[182:185], v144 offset:21504
	ds_read_b128 v[186:189], v144 offset:22528
	ds_read_b128 v[190:193], v144 offset:23552
	global_load_lds_dwordx4 v[216:217], off
	v_lshl_add_u64 v[218:219], s[22:23], 0, v[130:131]
	s_mov_b32 m0, s28
	s_nop 0
	global_load_lds_dwordx4 v[218:219], off
	s_barrier
	s_waitcnt lgkmcnt(0)
	s_waitcnt lgkmcnt(0)
	v_mfma_f32_16x16x32_bf16 v[60:63], v[146:149], v[162:165], v[60:63]
	v_mfma_f32_16x16x32_bf16 v[56:59], v[154:157], v[162:165], v[56:59]
	v_mfma_f32_16x16x32_bf16 v[44:47], v[146:149], v[170:173], v[44:47]
	v_mfma_f32_16x16x32_bf16 v[40:43], v[154:157], v[170:173], v[40:43]
	v_mfma_f32_16x16x32_bf16 v[28:31], v[146:149], v[178:181], v[28:31]
	v_mfma_f32_16x16x32_bf16 v[24:27], v[154:157], v[178:181], v[24:27]
	v_mfma_f32_16x16x32_bf16 v[12:15], v[146:149], v[186:189], v[12:15]
	v_mfma_f32_16x16x32_bf16 v[8:11], v[154:157], v[186:189], v[8:11]
	v_mfma_f32_16x16x32_bf16 v[60:63], v[150:153], v[166:169], v[60:63]
	v_mfma_f32_16x16x32_bf16 v[56:59], v[158:161], v[166:169], v[56:59]
	v_mfma_f32_16x16x32_bf16 v[44:47], v[150:153], v[174:177], v[44:47]
	v_mfma_f32_16x16x32_bf16 v[40:43], v[158:161], v[174:177], v[40:43]
	v_mfma_f32_16x16x32_bf16 v[28:31], v[150:153], v[182:185], v[28:31]
	v_mfma_f32_16x16x32_bf16 v[24:27], v[158:161], v[182:185], v[24:27]
	v_mfma_f32_16x16x32_bf16 v[12:15], v[150:153], v[190:193], v[12:15]
	v_mfma_f32_16x16x32_bf16 v[8:11], v[158:161], v[190:193], v[8:11]
	s_barrier
	s_add_u32 s52, s20, 0x40000
	s_addc_u32 s53, s21, 0
	s_add_i32 s54, s40, s27
	v_lshl_add_u64 v[146:147], s[52:53], 0, v[132:133]
	s_mov_b32 m0, s54
	s_nop 0
	global_load_lds_dwordx4 v[146:147], off
	v_lshl_add_u64 v[146:147], s[52:53], 0, v[128:129]
	s_add_i32 m0, s54, 0x2000
	s_nop 0
	global_load_lds_dwordx4 v[146:147], off
	s_waitcnt vmcnt(6)
	s_barrier
	v_mfma_f32_16x16x32_bf16 v[52:55], v[194:197], v[162:165], v[52:55]
	v_mfma_f32_16x16x32_bf16 v[48:51], v[204:207], v[162:165], v[48:51]
	v_mfma_f32_16x16x32_bf16 v[36:39], v[194:197], v[170:173], v[36:39]
	v_mfma_f32_16x16x32_bf16 v[32:35], v[204:207], v[170:173], v[32:35]
	v_mfma_f32_16x16x32_bf16 v[20:23], v[194:197], v[178:181], v[20:23]
	v_mfma_f32_16x16x32_bf16 v[16:19], v[204:207], v[178:181], v[16:19]
	v_mfma_f32_16x16x32_bf16 v[4:7], v[194:197], v[186:189], v[4:7]
	v_mfma_f32_16x16x32_bf16 v[0:3], v[204:207], v[186:189], v[0:3]
	v_mfma_f32_16x16x32_bf16 v[52:55], v[198:201], v[166:169], v[52:55]
	v_mfma_f32_16x16x32_bf16 v[48:51], v[208:211], v[166:169], v[48:51]
	v_mfma_f32_16x16x32_bf16 v[36:39], v[198:201], v[174:177], v[36:39]
	v_mfma_f32_16x16x32_bf16 v[32:35], v[208:211], v[174:177], v[32:35]
	v_mfma_f32_16x16x32_bf16 v[20:23], v[198:201], v[182:185], v[20:23]
	v_mfma_f32_16x16x32_bf16 v[16:19], v[208:211], v[182:185], v[16:19]
	v_mfma_f32_16x16x32_bf16 v[4:7], v[198:201], v[190:193], v[4:7]
	v_mfma_f32_16x16x32_bf16 v[0:3], v[208:211], v[190:193], v[0:3]
	s_add_i32 s52, 0, 0x18000
	v_add_u32_e32 v158, s52, v141
	s_barrier
	ds_read_b128 v[146:149], v158
	ds_read_b128 v[150:153], v158 offset:1024
	ds_read_b128 v[154:157], v158 offset:2048
	ds_read_b128 v[158:161], v158 offset:3072
	s_add_u32 s22, s22, 0x100000
	s_addc_u32 s23, s23, 0
	s_mov_b32 m0, s29
	v_lshl_add_u64 v[194:195], s[22:23], 0, v[134:135]
	ds_read_b128 v[162:165], v144 offset:32768
	ds_read_b128 v[166:169], v144 offset:33792
	ds_read_b128 v[170:173], v144 offset:34816
	ds_read_b128 v[174:177], v144 offset:35840
	ds_read_b128 v[178:181], v144 offset:36864
	ds_read_b128 v[182:185], v144 offset:37888
	ds_read_b128 v[186:189], v144 offset:38912
	ds_read_b128 v[190:193], v144 offset:39936
	global_load_lds_dwordx4 v[194:195], off
	v_lshl_add_u64 v[194:195], s[22:23], 0, v[130:131]
	s_mov_b32 m0, s30
	s_nop 0
	global_load_lds_dwordx4 v[194:195], off
	s_waitcnt lgkmcnt(8)
	s_barrier
	s_waitcnt lgkmcnt(0)
	s_waitcnt lgkmcnt(0)
	v_mfma_f32_16x16x32_bf16 v[124:127], v[146:149], v[162:165], v[124:127]
	v_mfma_f32_16x16x32_bf16 v[120:123], v[154:157], v[162:165], v[120:123]
	v_mfma_f32_16x16x32_bf16 v[108:111], v[146:149], v[170:173], v[108:111]
	v_mfma_f32_16x16x32_bf16 v[104:107], v[154:157], v[170:173], v[104:107]
	v_mfma_f32_16x16x32_bf16 v[92:95], v[146:149], v[178:181], v[92:95]
	v_mfma_f32_16x16x32_bf16 v[88:91], v[154:157], v[178:181], v[88:91]
	v_mfma_f32_16x16x32_bf16 v[76:79], v[146:149], v[186:189], v[76:79]
	v_mfma_f32_16x16x32_bf16 v[72:75], v[154:157], v[186:189], v[72:75]
	v_mfma_f32_16x16x32_bf16 v[124:127], v[150:153], v[166:169], v[124:127]
	v_mfma_f32_16x16x32_bf16 v[120:123], v[158:161], v[166:169], v[120:123]
	v_mfma_f32_16x16x32_bf16 v[108:111], v[150:153], v[174:177], v[108:111]
	v_mfma_f32_16x16x32_bf16 v[104:107], v[158:161], v[174:177], v[104:107]
	v_mfma_f32_16x16x32_bf16 v[92:95], v[150:153], v[182:185], v[92:95]
	v_mfma_f32_16x16x32_bf16 v[88:91], v[158:161], v[182:185], v[88:91]
	v_mfma_f32_16x16x32_bf16 v[76:79], v[150:153], v[190:193], v[76:79]
	v_mfma_f32_16x16x32_bf16 v[72:75], v[158:161], v[190:193], v[72:75]
	s_barrier
	s_add_i32 s22, 0, 0x1c000
	s_add_i32 s23, s52, s27
	v_add_u32_e32 v208, s22, v141
	v_lshl_add_u64 v[212:213], v[212:213], 0, s[0:1]
	s_mov_b32 m0, s23
	ds_read_b128 v[194:197], v208
	ds_read_b128 v[198:201], v208 offset:1024
	ds_read_b128 v[204:207], v208 offset:2048
	ds_read_b128 v[208:211], v208 offset:3072
	global_load_lds_dwordx4 v[212:213], off
	v_lshl_add_u64 v[212:213], v[214:215], 0, s[0:1]
	s_add_i32 m0, s23, 0x2000
	s_nop 0
	global_load_lds_dwordx4 v[212:213], off
	s_barrier
	s_waitcnt lgkmcnt(0)
	s_waitcnt lgkmcnt(0)
	v_mfma_f32_16x16x32_bf16 v[116:119], v[194:197], v[162:165], v[116:119]
	v_mfma_f32_16x16x32_bf16 v[112:115], v[204:207], v[162:165], v[112:115]
	v_mfma_f32_16x16x32_bf16 v[100:103], v[194:197], v[170:173], v[100:103]
	v_mfma_f32_16x16x32_bf16 v[96:99], v[204:207], v[170:173], v[96:99]
	v_mfma_f32_16x16x32_bf16 v[84:87], v[194:197], v[178:181], v[84:87]
	v_mfma_f32_16x16x32_bf16 v[80:83], v[204:207], v[178:181], v[80:83]
	v_mfma_f32_16x16x32_bf16 v[68:71], v[194:197], v[186:189], v[68:71]
	v_mfma_f32_16x16x32_bf16 v[64:67], v[204:207], v[186:189], v[64:67]
	v_mfma_f32_16x16x32_bf16 v[116:119], v[198:201], v[166:169], v[116:119]
	v_mfma_f32_16x16x32_bf16 v[112:115], v[208:211], v[166:169], v[112:115]
	v_mfma_f32_16x16x32_bf16 v[100:103], v[198:201], v[174:177], v[100:103]
	v_mfma_f32_16x16x32_bf16 v[96:99], v[208:211], v[174:177], v[96:99]
	v_mfma_f32_16x16x32_bf16 v[84:87], v[198:201], v[182:185], v[84:87]
	v_mfma_f32_16x16x32_bf16 v[80:83], v[208:211], v[182:185], v[80:83]
	v_mfma_f32_16x16x32_bf16 v[68:71], v[198:201], v[190:193], v[68:71]
	v_mfma_f32_16x16x32_bf16 v[64:67], v[208:211], v[190:193], v[64:67]
	s_mov_b32 m0, s36
	v_lshl_add_u64 v[212:213], v[216:217], 0, s[0:1]
	s_barrier
	ds_read_b128 v[162:165], v144 offset:49152
	ds_read_b128 v[166:169], v144 offset:50176
	ds_read_b128 v[170:173], v144 offset:51200
	ds_read_b128 v[174:177], v144 offset:52224
	ds_read_b128 v[178:181], v144 offset:53248
	ds_read_b128 v[182:185], v144 offset:54272
	ds_read_b128 v[186:189], v144 offset:55296
	ds_read_b128 v[190:193], v144 offset:56320
	global_load_lds_dwordx4 v[212:213], off
	v_lshl_add_u64 v[212:213], v[218:219], 0, s[0:1]
	s_mov_b32 m0, s37
	s_nop 0
	global_load_lds_dwordx4 v[212:213], off
	s_barrier
	s_waitcnt lgkmcnt(0)
	s_waitcnt lgkmcnt(0)
	v_mfma_f32_16x16x32_bf16 v[60:63], v[146:149], v[162:165], v[60:63]
	v_mfma_f32_16x16x32_bf16 v[56:59], v[154:157], v[162:165], v[56:59]
	v_mfma_f32_16x16x32_bf16 v[44:47], v[146:149], v[170:173], v[44:47]
	v_mfma_f32_16x16x32_bf16 v[40:43], v[154:157], v[170:173], v[40:43]
	v_mfma_f32_16x16x32_bf16 v[28:31], v[146:149], v[178:181], v[28:31]
	v_mfma_f32_16x16x32_bf16 v[24:27], v[154:157], v[178:181], v[24:27]
	v_mfma_f32_16x16x32_bf16 v[12:15], v[146:149], v[186:189], v[12:15]
	v_mfma_f32_16x16x32_bf16 v[8:11], v[154:157], v[186:189], v[8:11]
	v_mfma_f32_16x16x32_bf16 v[60:63], v[150:153], v[166:169], v[60:63]
	v_mfma_f32_16x16x32_bf16 v[56:59], v[158:161], v[166:169], v[56:59]
	v_mfma_f32_16x16x32_bf16 v[44:47], v[150:153], v[174:177], v[44:47]
	v_mfma_f32_16x16x32_bf16 v[40:43], v[158:161], v[174:177], v[40:43]
	v_mfma_f32_16x16x32_bf16 v[28:31], v[150:153], v[182:185], v[28:31]
	v_mfma_f32_16x16x32_bf16 v[24:27], v[158:161], v[182:185], v[24:27]
	v_mfma_f32_16x16x32_bf16 v[12:15], v[150:153], v[190:193], v[12:15]
	v_mfma_f32_16x16x32_bf16 v[8:11], v[158:161], v[190:193], v[8:11]
	s_barrier
	s_add_u32 s20, s20, 0x40080
	s_addc_u32 s21, s21, 0
	s_add_i32 s22, s22, s27
	v_lshl_add_u64 v[146:147], s[20:21], 0, v[132:133]
	s_mov_b32 m0, s22
	s_nop 0
	global_load_lds_dwordx4 v[146:147], off
	v_lshl_add_u64 v[146:147], s[20:21], 0, v[128:129]
	s_add_i32 m0, s22, 0x2000
	s_nop 0
	global_load_lds_dwordx4 v[146:147], off
	s_waitcnt vmcnt(6)
	s_barrier
	v_mfma_f32_16x16x32_bf16 v[52:55], v[194:197], v[162:165], v[52:55]
	v_mfma_f32_16x16x32_bf16 v[48:51], v[204:207], v[162:165], v[48:51]
	v_mfma_f32_16x16x32_bf16 v[36:39], v[194:197], v[170:173], v[36:39]
	v_mfma_f32_16x16x32_bf16 v[32:35], v[204:207], v[170:173], v[32:35]
	v_mfma_f32_16x16x32_bf16 v[20:23], v[194:197], v[178:181], v[20:23]
	v_mfma_f32_16x16x32_bf16 v[16:19], v[204:207], v[178:181], v[16:19]
	v_mfma_f32_16x16x32_bf16 v[4:7], v[194:197], v[186:189], v[4:7]
	v_mfma_f32_16x16x32_bf16 v[0:3], v[204:207], v[186:189], v[0:3]
	v_mfma_f32_16x16x32_bf16 v[52:55], v[198:201], v[166:169], v[52:55]
	v_mfma_f32_16x16x32_bf16 v[48:51], v[208:211], v[166:169], v[48:51]
	v_mfma_f32_16x16x32_bf16 v[36:39], v[198:201], v[174:177], v[36:39]
	v_mfma_f32_16x16x32_bf16 v[32:35], v[208:211], v[174:177], v[32:35]
	v_mfma_f32_16x16x32_bf16 v[20:23], v[198:201], v[182:185], v[20:23]
	v_mfma_f32_16x16x32_bf16 v[16:19], v[208:211], v[182:185], v[16:19]
	v_mfma_f32_16x16x32_bf16 v[4:7], v[198:201], v[190:193], v[4:7]
	v_mfma_f32_16x16x32_bf16 v[0:3], v[208:211], v[190:193], v[0:3]
	s_add_u32 s18, s18, 0x100
	s_addc_u32 s19, s19, 0
	s_add_u32 s49, s49, 0x100
	s_addc_u32 s50, s50, 0
	s_cmp_ge_i32 s51, s45
	s_mov_b32 s20, s51
	s_barrier
	s_cbranch_scc0 .LBB0_1409
	s_branch .LBB0_1404

.LBB0_1465:
	s_or_b64 exec, exec, s[0:1]
	s_setprio 0
	s_waitcnt lgkmcnt(0)
	v_mov_b32_e32 v0, v202
	v_mov_b32_e32 v1, v202
	s_barrier
	v_readlane_b32 s0, v247, 6
	v_ashrrev_i32_e32 v32, 6, v1
	s_movk_i32 s30, 0x2400
	v_add_u32_e32 v97, s0, v32
	v_cmp_gt_i32_e32 vcc, s30, v97
	v_readlane_b32 s1, v247, 7
	s_and_saveexec_b64 s[0:1], vcc
	s_xor_b64 s[2:3], exec, s[0:1]
	s_cbranch_execz .LBB0_1505
	v_readlane_b32 s4, v248, 0
	v_readlane_b32 s5, v248, 1
	v_and_b32_e32 v96, 63, v0
	s_mov_b64 s[0:1], s[4:5]
	v_or_b32_e32 v98, 0x100, v96
	v_or_b32_e32 v100, 0x140, v96
	v_or_b32_e32 v102, 0x180, v96
	v_or_b32_e32 v104, 0x1c0, v96
	s_add_u32 s0, s0, 0x2000
	v_lshlrev_b32_e32 v34, 4, v96
	s_addc_u32 s1, s1, 0
	v_lshlrev_b32_e32 v0, 4, v104
	v_lshlrev_b32_e32 v4, 4, v102
	v_lshlrev_b32_e32 v8, 4, v100
	v_lshlrev_b32_e32 v12, 4, v98
	v_or_b32_e32 v24, 0xc00, v34
	v_or_b32_e32 v16, 0x800, v34
	v_or_b32_e32 v20, 0x400, v34
	global_load_dwordx4 v[0:3], v0, s[0:1]
	s_nop 0
	global_load_dwordx4 v[4:7], v4, s[0:1]
	s_nop 0
	global_load_dwordx4 v[8:11], v8, s[0:1]
	s_nop 0
	global_load_dwordx4 v[12:15], v12, s[0:1]
	s_nop 0
	global_load_dwordx4 v[16:19], v16, s[0:1]
	s_nop 0
	global_load_dwordx4 v[20:23], v20, s[0:1]
	s_nop 0
	global_load_dwordx4 v[24:27], v24, s[0:1]
	s_nop 0
	global_load_dwordx4 v[28:31], v34, s[0:1]
	v_mbcnt_hi_u32_b32 v33, -1, v203
	v_and_b32_e32 v35, 64, v33
	v_add_u32_e32 v35, 64, v35
	v_xor_b32_e32 v36, 1, v33
	v_cmp_lt_i32_e32 vcc, v36, v35
	v_readlane_b32 s0, v248, 50
	v_mov_b32_e32 v107, 0
	v_cndmask_b32_e32 v36, v33, v36, vcc
	v_lshlrev_b32_e32 v99, 2, v36
	v_xor_b32_e32 v36, 2, v33
	v_cmp_lt_i32_e32 vcc, v36, v35
	v_lshlrev_b32_e32 v106, 3, v96
	v_readlane_b32 s1, v248, 51
	v_cndmask_b32_e32 v36, v33, v36, vcc
	v_lshlrev_b32_e32 v101, 2, v36
	v_xor_b32_e32 v36, 4, v33
	v_cmp_lt_i32_e32 vcc, v36, v35
	v_lshl_add_u64 v[108:109], s[0:1], 0, v[106:107]
	v_readlane_b32 s0, v247, 9
	v_cndmask_b32_e32 v36, v33, v36, vcc
	v_lshlrev_b32_e32 v103, 2, v36
	v_xor_b32_e32 v36, 8, v33
	v_cmp_lt_i32_e32 vcc, v36, v35
	v_readlane_b32 s1, v247, 10
	v_readlane_b32 s6, v248, 2
	v_cndmask_b32_e32 v36, v33, v36, vcc
	v_lshlrev_b32_e32 v105, 2, v36
	v_xor_b32_e32 v36, 16, v33
	v_cmp_lt_i32_e32 vcc, v36, v35
	v_lshl_add_u64 v[110:111], s[0:1], 0, v[106:107]
	v_readlane_b32 s0, v247, 6
	v_cndmask_b32_e32 v36, v33, v36, vcc
	v_lshlrev_b32_e32 v204, 2, v36
	v_xor_b32_e32 v36, 32, v33
	v_cmp_lt_i32_e32 vcc, v36, v35
	v_readlane_b32 s1, v247, 7
	s_mov_b32 s4, s0
	v_cndmask_b32_e32 v33, v33, v36, vcc
	v_lshlrev_b32_e32 v205, 2, v33
	v_ashrrev_i32_e32 v33, 31, v32
	s_ashr_i32 s5, s0, 31
	v_writelane_b32 v247, s0, 6
	v_readlane_b32 s7, v248, 3
	v_lshl_add_u64 v[32:33], v[32:33], 0, s[4:5]
	v_writelane_b32 v247, s1, 7
	v_readlane_b32 s0, v248, 52
	v_readlane_b32 s8, v248, 4
	v_readlane_b32 s9, v248, 5
	v_readlane_b32 s10, v248, 6
	v_readlane_b32 s11, v248, 7
	v_lshlrev_b64 v[112:113], 12, v[32:33]
	v_readlane_b32 s1, v248, 53
	s_mov_b32 s6, s0
	s_ashr_i32 s7, s0, 31
	v_lshlrev_b64 v[114:115], 13, v[32:33]
	v_or_b32_e32 v112, v112, v106
	s_lshl_b64 s[4:5], s[6:7], 12
	v_or_b32_e32 v114, v114, v34
	v_writelane_b32 v248, s0, 52
	s_lshl_b64 s[8:9], s[6:7], 13
	s_mov_b64 s[6:7], 0
	s_mov_b64 s[10:11], 0xe100000
	s_mov_b32 s31, 0xe100000
	s_mov_b32 s34, 0x3c280000
	s_mov_b32 s35, 0x38e38e39
	s_mov_b64 s[12:13], 0xe100400
	s_mov_b64 s[14:15], 0xe100800
	s_mov_b64 s[16:17], 0xe100c00
	s_mov_b64 s[18:19], 0xe101000
	s_mov_b64 s[20:21], 0xe101400
	s_mov_b64 s[22:23], 0xe101800
	s_mov_b64 s[24:25], 0xe101c00
	v_mov_b32_e32 v206, 0x358637bd
	s_mov_b32 s36, 0x800000
	s_mov_b32 s37, 0x12900000
	s_movk_i32 s38, 0x23ff
	v_writelane_b32 v248, s1, 53
	s_branch .LBB0_1468

.Lprio_skip_13:
	v_readlane_b32 s0, v247, 14
	v_mov_b32_e32 v8, v202
	v_readlane_b32 s1, v247, 15
	s_waitcnt lgkmcnt(0)
	s_barrier
	s_and_b64 vcc, exec, s[0:1]
	v_readfirstlane_b32 s28, v8
	s_cbranch_vccz .LBB0_1569
	v_lshlrev_b32_e32 v0, 4, v8
	s_add_u32 s29, s58, 0xa100000
	v_readlane_b32 s1, v247, 8
	v_add_u32_e32 v1, 0x2000, v0
	s_addc_u32 s30, s59, 0
	s_lshr_b32 s1, s1, 29
	v_readlane_b32 s4, v248, 45
	v_ashrrev_i32_e32 v2, 31, v1
	s_add_i32 s1, s4, s1
	v_lshrrev_b32_e32 v2, 22, v2
	s_ashr_i32 s0, s28, 6
	s_and_b32 s2, s1, -8
	v_add_u32_e32 v2, v1, v2
	s_ashr_i32 s3, s28, 8
	s_lshl_b32 s31, s0, 10
	s_sub_i32 s2, s4, s2
	v_ashrrev_i32_e32 v9, 10, v2
	s_cmp_lt_i32 s2, 0
	s_movk_i32 s34, 0x91
	v_mul_i32_i24_e32 v2, 0x400, v9
	s_cselect_b32 s4, s34, 0x90
	v_sub_u32_e32 v1, v1, v2
	s_mul_i32 s2, s4, s2
	s_ashr_i32 s1, s1, 3
	v_lshrrev_b32_e32 v2, 4, v1
	s_add_i32 s1, s2, s1
	v_bitop3_b32 v1, v2, v1, 32 bitop3:0x6c
	s_ashr_i32 s2, s1, 31
	v_ashrrev_i32_e32 v2, 31, v1
	s_lshr_b32 s2, s2, 24
	v_lshrrev_b32_e32 v2, 26, v2
	s_add_i32 s2, s1, s2
	v_add_u32_e32 v2, v1, v2
	v_lshlrev_b32_e32 v3, 3, v9
	s_ashr_i32 s2, s2, 8
	v_ashrrev_i32_e32 v10, 6, v2
	v_and_b32_e32 v3, -16, v3
	s_lshl_b32 s6, s2, 3
	s_lshl_b32 s2, s2, 8
	v_add_u32_e32 v3, v10, v3
	s_sub_i32 s1, s1, s2
	v_and_b32_e32 v4, 3, v10
	s_mov_b32 s2, 0xfffe0
	v_lshrrev_b32_e32 v5, 2, v3
	v_lshlrev_b32_e32 v6, 1, v3
	v_and_b32_e32 v2, 0xc0, v2
	v_and_or_b32 v4, v3, s2, v4
	v_and_b32_e32 v5, 4, v5
	v_and_b32_e32 v6, 24, v6
	v_sub_u32_e32 v1, v1, v2
	v_mov_b32_e32 v2, 1
	v_or3_b32 v4, v4, v5, v6
	v_lshlrev_b32_e32 v5, 5, v9
	v_ashrrev_i16_sdwa v1, v2, sext(v1) dst_sel:DWORD dst_unused:UNUSED_PAD src0_sel:DWORD src1_sel:BYTE_0
	v_and_b32_e32 v5, 32, v5
	v_bfe_i32 v11, v1, 0, 16
	v_add_lshl_u32 v1, v5, v11, 1
	v_lshl_add_u32 v128, v4, 12, v1
	v_lshl_add_u32 v130, v3, 12, v1
	v_bfe_i32 v1, v8, 27, 1
	v_lshrrev_b32_e32 v1, 22, v1
	v_add_u32_e32 v1, v0, v1
	v_and_b32_e32 v1, 0xfffffc00, v1
	v_sub_u32_e32 v0, v0, v1
	v_lshrrev_b32_e32 v1, 4, v0
	v_ashrrev_i32_e32 v3, 31, v8
	v_bitop3_b32 v0, v1, v0, 32 bitop3:0x6c
	v_lshrrev_b32_e32 v3, 26, v3
	v_ashrrev_i32_e32 v1, 31, v0
	v_add_u32_e32 v3, v8, v3
	v_lshrrev_b32_e32 v1, 26, v1
	v_ashrrev_i32_e32 v13, 6, v3
	v_add_u32_e32 v1, v0, v1
	v_lshlrev_b32_e32 v3, 3, v13
	v_ashrrev_i32_e32 v12, 6, v1
	v_and_b32_e32 v3, -16, v3
	v_add_u32_e32 v3, v12, v3
	v_and_b32_e32 v4, 3, v12
	v_lshrrev_b32_e32 v5, 2, v3
	v_lshlrev_b32_e32 v6, 1, v3
	v_and_b32_e32 v1, 0xc0, v1
	v_and_or_b32 v4, v3, s2, v4
	v_and_b32_e32 v5, 4, v5
	v_and_b32_e32 v6, 24, v6
	v_sub_u32_e32 v0, v0, v1
	s_sub_i32 s4, 36, s6
	v_or3_b32 v4, v4, v5, v6
	v_lshlrev_b32_e32 v5, 5, v13
	v_ashrrev_i16_sdwa v0, v2, sext(v0) dst_sel:DWORD dst_unused:UNUSED_PAD src0_sel:DWORD src1_sel:BYTE_0
	s_min_u32 s7, s4, 8
	v_and_b32_e32 v5, 32, v5
	v_bfe_i32 v14, v0, 0, 16
	v_add_lshl_u32 v0, v5, v14, 1
	s_sext_i32_i16 s2, s1
	v_cvt_f32_ubyte0_e32 v2, s7
	v_lshl_add_u32 v132, v4, 12, v0
	v_cvt_f32_i32_e32 v1, s2
	v_rcp_iflag_f32_e32 v4, v2
	v_lshl_add_u32 v134, v3, 12, v0
	s_ashr_i32 s2, s2, 30
	s_or_b32 s2, s2, 1
	v_mul_f32_e32 v0, v1, v4
	v_trunc_f32_e32 v0, v0
	v_fma_f32 v1, -v0, v2, v1
	v_cvt_i32_f32_e32 v0, v0
	v_cmp_ge_f32_e64 s[4:5], |v1|, v2
	s_and_b64 s[4:5], s[4:5], exec
	s_cselect_b32 s2, s2, 0
	v_readfirstlane_b32 s4, v0
	s_add_i32 s2, s4, s2
	s_mul_i32 s4, s2, s7
	s_sub_i32 s1, s1, s4
	s_sext_i32_i16 s1, s1
	s_add_i32 s20, s6, s1
	s_ashr_i32 s21, s20, 31
	s_bfe_i64 s[6:7], s[2:3], 0x100000
	s_lshl_b64 s[4:5], s[20:21], 20
	s_lshl_b64 s[6:7], s[6:7], 20
	s_add_u32 s24, s29, s6
	s_addc_u32 s25, s30, s7
	s_add_i32 s21, s31, 0
	s_add_i32 m0, s21, 0x10000
	v_readlane_b32 s6, v247, 9
	v_mov_b32_e32 v230, s3
	v_lshlrev_b32_e32 v230, 17, v230
	v_add_u32_e32 v132, v132, v230
	v_add_u32_e32 v230, 0x40000, v230
	v_add_u32_e32 v128, v128, v230
	global_load_lds_dwordx4 v132, s[24:25]
	s_add_i32 m0, s21, 0x12000
	v_readlane_b32 s7, v247, 10
	s_add_u32 s22, s6, s4
	global_load_lds_dwordx4 v128, s[24:25]
	s_addc_u32 s23, s7, s5
	s_mov_b32 m0, s21
	s_add_i32 s35, s21, 0x2000
	global_load_lds_dwordx4 v134, s[22:23]
	s_mov_b32 m0, s35
	s_add_u32 s4, s24, 0x20000
	global_load_lds_dwordx4 v130, s[22:23]
	s_addc_u32 s5, s25, 0
	s_add_i32 m0, s21, 0x14000
	v_mov_b32_e32 v133, 0
	global_load_lds_dwordx4 v132, s[4:5]
	s_add_i32 m0, s21, 0x16000
	v_mov_b32_e32 v129, v133
	global_load_lds_dwordx4 v128, s[4:5]
	s_add_u32 s4, s22, 0x80000
	s_addc_u32 s5, s23, 0
	s_add_i32 s36, s21, 0x4000
	s_mov_b32 m0, s36
	s_add_i32 s37, s21, 0x6000
	global_load_lds_dwordx4 v134, s[4:5]
	s_mov_b32 m0, s37
	v_mov_b32_e32 v135, v133
	global_load_lds_dwordx4 v130, s[4:5]
	v_mov_b32_e32 v131, v133
	s_mov_b32 s38, 0
	v_lshl_add_u64 v[6:7], s[24:25], 0, v[132:133]
	v_lshl_add_u64 v[4:5], s[24:25], 0, v[128:129]
	v_lshl_add_u64 v[2:3], s[22:23], 0, v[134:135]
	s_cmp_lg_u32 s3, 1
	v_lshl_add_u64 v[0:1], s[22:23], 0, v[130:131]
	s_cbranch_scc1 .LBB0_1560
	s_barrier

.LBB0_1564:
	ds_read_b128 v[152:155], v149
	ds_read_b128 v[156:159], v149 offset:1024
	ds_read_b128 v[160:163], v149 offset:2048
	ds_read_b128 v[164:167], v149 offset:3072
	s_add_u32 s24, s22, 0xfff80080
	s_addc_u32 s25, s23, -1
	s_cmp_eq_u32 s52, 28
	s_cselect_b32 s27, s15, s25
	s_cselect_b32 s26, s48, s24
	s_cselect_b32 s25, s13, s51
	s_cselect_b32 s24, s49, s50
	v_lshl_add_u64 v[144:145], s[22:23], 0, v[136:137]
	s_add_i32 m0, s21, 0xc000
	ds_read_b128 v[168:171], v150
	ds_read_b128 v[172:175], v150 offset:1024
	ds_read_b128 v[176:179], v150 offset:2048
	ds_read_b128 v[180:183], v150 offset:3072
	ds_read_b128 v[184:187], v150 offset:4096
	ds_read_b128 v[188:191], v150 offset:5120
	ds_read_b128 v[192:195], v150 offset:6144
	ds_read_b128 v[196:199], v150 offset:7168
	global_load_lds_dwordx4 v[144:145], off
	v_lshl_add_u64 v[144:145], s[22:23], 0, v[138:139]
	s_add_i32 m0, s21, 0xe000
	s_nop 0
	global_load_lds_dwordx4 v[144:145], off
	s_waitcnt lgkmcnt(8)
	s_barrier
	s_waitcnt lgkmcnt(0)
	s_waitcnt lgkmcnt(0)
	v_mfma_f32_16x16x32_bf16 v[124:127], v[152:155], v[168:171], v[124:127]
	v_mfma_f32_16x16x32_bf16 v[120:123], v[160:163], v[168:171], v[120:123]
	v_mfma_f32_16x16x32_bf16 v[108:111], v[152:155], v[176:179], v[108:111]
	v_mfma_f32_16x16x32_bf16 v[104:107], v[160:163], v[176:179], v[104:107]
	v_mfma_f32_16x16x32_bf16 v[92:95], v[152:155], v[184:187], v[92:95]
	v_mfma_f32_16x16x32_bf16 v[88:91], v[160:163], v[184:187], v[88:91]
	v_mfma_f32_16x16x32_bf16 v[76:79], v[152:155], v[192:195], v[76:79]
	v_mfma_f32_16x16x32_bf16 v[72:75], v[160:163], v[192:195], v[72:75]
	v_mfma_f32_16x16x32_bf16 v[124:127], v[156:159], v[172:175], v[124:127]
	v_mfma_f32_16x16x32_bf16 v[120:123], v[164:167], v[172:175], v[120:123]
	v_mfma_f32_16x16x32_bf16 v[108:111], v[156:159], v[180:183], v[108:111]
	v_mfma_f32_16x16x32_bf16 v[104:107], v[164:167], v[180:183], v[104:107]
	v_mfma_f32_16x16x32_bf16 v[92:95], v[156:159], v[188:191], v[92:95]
	v_mfma_f32_16x16x32_bf16 v[88:91], v[164:167], v[188:191], v[88:91]
	v_mfma_f32_16x16x32_bf16 v[76:79], v[156:159], v[196:199], v[76:79]
	v_mfma_f32_16x16x32_bf16 v[72:75], v[164:167], v[196:199], v[72:75]
	s_barrier
	s_add_i32 s53, s41, s31
	v_lshl_add_u64 v[144:145], s[24:25], 0, v[132:133]
	s_mov_b32 m0, s53
	ds_read_b128 v[204:207], v151
	ds_read_b128 v[208:211], v151 offset:1024
	ds_read_b128 v[212:215], v151 offset:2048
	ds_read_b128 v[216:219], v151 offset:3072
	global_load_lds_dwordx4 v[144:145], off
	v_lshl_add_u64 v[200:201], s[24:25], 0, v[128:129]
	s_add_i32 m0, s53, 0x2000
	s_nop 0
	global_load_lds_dwordx4 v[200:201], off
	s_barrier
	s_waitcnt lgkmcnt(0)
	s_waitcnt lgkmcnt(0)
	v_mfma_f32_16x16x32_bf16 v[116:119], v[204:207], v[168:171], v[116:119]
	v_mfma_f32_16x16x32_bf16 v[112:115], v[212:215], v[168:171], v[112:115]
	v_mfma_f32_16x16x32_bf16 v[100:103], v[204:207], v[176:179], v[100:103]
	v_mfma_f32_16x16x32_bf16 v[96:99], v[212:215], v[176:179], v[96:99]
	v_mfma_f32_16x16x32_bf16 v[84:87], v[204:207], v[184:187], v[84:87]
	v_mfma_f32_16x16x32_bf16 v[80:83], v[212:215], v[184:187], v[80:83]
	v_mfma_f32_16x16x32_bf16 v[68:71], v[204:207], v[192:195], v[68:71]
	v_mfma_f32_16x16x32_bf16 v[64:67], v[212:215], v[192:195], v[64:67]
	v_mfma_f32_16x16x32_bf16 v[116:119], v[208:211], v[172:175], v[116:119]
	v_mfma_f32_16x16x32_bf16 v[112:115], v[216:219], v[172:175], v[112:115]
	v_mfma_f32_16x16x32_bf16 v[100:103], v[208:211], v[180:183], v[100:103]
	v_mfma_f32_16x16x32_bf16 v[96:99], v[216:219], v[180:183], v[96:99]
	v_mfma_f32_16x16x32_bf16 v[84:87], v[208:211], v[188:191], v[84:87]
	v_mfma_f32_16x16x32_bf16 v[80:83], v[216:219], v[188:191], v[80:83]
	v_mfma_f32_16x16x32_bf16 v[68:71], v[208:211], v[196:199], v[68:71]
	v_mfma_f32_16x16x32_bf16 v[64:67], v[216:219], v[196:199], v[64:67]
	s_mov_b32 m0, s21
	v_lshl_add_u64 v[220:221], s[26:27], 0, v[134:135]
	s_barrier
	ds_read_b128 v[168:171], v150 offset:16384
	ds_read_b128 v[172:175], v150 offset:17408
	ds_read_b128 v[176:179], v150 offset:18432
	ds_read_b128 v[180:183], v150 offset:19456
	ds_read_b128 v[184:187], v150 offset:20480
	ds_read_b128 v[188:191], v150 offset:21504
	ds_read_b128 v[192:195], v150 offset:22528
	ds_read_b128 v[196:199], v150 offset:23552
	global_load_lds_dwordx4 v[220:221], off
	v_lshl_add_u64 v[222:223], s[26:27], 0, v[130:131]
	s_mov_b32 m0, s35
	s_nop 0
	global_load_lds_dwordx4 v[222:223], off
	s_barrier
	s_waitcnt lgkmcnt(0)
	s_waitcnt lgkmcnt(0)
	v_mfma_f32_16x16x32_bf16 v[60:63], v[152:155], v[168:171], v[60:63]
	v_mfma_f32_16x16x32_bf16 v[56:59], v[160:163], v[168:171], v[56:59]
	v_mfma_f32_16x16x32_bf16 v[44:47], v[152:155], v[176:179], v[44:47]
	v_mfma_f32_16x16x32_bf16 v[40:43], v[160:163], v[176:179], v[40:43]
	v_mfma_f32_16x16x32_bf16 v[28:31], v[152:155], v[184:187], v[28:31]
	v_mfma_f32_16x16x32_bf16 v[24:27], v[160:163], v[184:187], v[24:27]
	v_mfma_f32_16x16x32_bf16 v[12:15], v[152:155], v[192:195], v[12:15]
	v_mfma_f32_16x16x32_bf16 v[8:11], v[160:163], v[192:195], v[8:11]
	v_mfma_f32_16x16x32_bf16 v[60:63], v[156:159], v[172:175], v[60:63]
	v_mfma_f32_16x16x32_bf16 v[56:59], v[164:167], v[172:175], v[56:59]
	v_mfma_f32_16x16x32_bf16 v[44:47], v[156:159], v[180:183], v[44:47]
	v_mfma_f32_16x16x32_bf16 v[40:43], v[164:167], v[180:183], v[40:43]
	v_mfma_f32_16x16x32_bf16 v[28:31], v[156:159], v[188:191], v[28:31]
	v_mfma_f32_16x16x32_bf16 v[24:27], v[164:167], v[188:191], v[24:27]
	v_mfma_f32_16x16x32_bf16 v[12:15], v[156:159], v[196:199], v[12:15]
	v_mfma_f32_16x16x32_bf16 v[8:11], v[164:167], v[196:199], v[8:11]
	s_barrier
	s_add_u32 s54, s24, 0x20000
	s_addc_u32 s55, s25, 0
	s_add_i32 s53, s42, s31
	v_lshl_add_u64 v[152:153], s[54:55], 0, v[132:133]
	s_mov_b32 m0, s53
	s_nop 0
	global_load_lds_dwordx4 v[152:153], off
	v_lshl_add_u64 v[152:153], s[54:55], 0, v[128:129]
	s_add_i32 m0, s53, 0x2000
	s_nop 0
	global_load_lds_dwordx4 v[152:153], off
	s_waitcnt vmcnt(6)
	s_barrier
	v_mfma_f32_16x16x32_bf16 v[52:55], v[204:207], v[168:171], v[52:55]
	v_mfma_f32_16x16x32_bf16 v[48:51], v[212:215], v[168:171], v[48:51]
	v_mfma_f32_16x16x32_bf16 v[36:39], v[204:207], v[176:179], v[36:39]
	v_mfma_f32_16x16x32_bf16 v[32:35], v[212:215], v[176:179], v[32:35]
	v_mfma_f32_16x16x32_bf16 v[20:23], v[204:207], v[184:187], v[20:23]
	v_mfma_f32_16x16x32_bf16 v[16:19], v[212:215], v[184:187], v[16:19]
	v_mfma_f32_16x16x32_bf16 v[4:7], v[204:207], v[192:195], v[4:7]
	v_mfma_f32_16x16x32_bf16 v[0:3], v[212:215], v[192:195], v[0:3]
	v_mfma_f32_16x16x32_bf16 v[52:55], v[208:211], v[172:175], v[52:55]
	v_mfma_f32_16x16x32_bf16 v[48:51], v[216:219], v[172:175], v[48:51]
	v_mfma_f32_16x16x32_bf16 v[36:39], v[208:211], v[180:183], v[36:39]
	v_mfma_f32_16x16x32_bf16 v[32:35], v[216:219], v[180:183], v[32:35]
	v_mfma_f32_16x16x32_bf16 v[20:23], v[208:211], v[188:191], v[20:23]
	v_mfma_f32_16x16x32_bf16 v[16:19], v[216:219], v[188:191], v[16:19]
	v_mfma_f32_16x16x32_bf16 v[4:7], v[208:211], v[196:199], v[4:7]
	v_mfma_f32_16x16x32_bf16 v[0:3], v[216:219], v[196:199], v[0:3]
	s_add_i32 s53, 0, 0x18000
	v_add_u32_e32 v164, s53, v147
	s_barrier
	ds_read_b128 v[152:155], v164
	ds_read_b128 v[156:159], v164 offset:1024
	ds_read_b128 v[160:163], v164 offset:2048
	ds_read_b128 v[164:167], v164 offset:3072
	s_add_u32 s26, s26, 0x80000
	s_addc_u32 s27, s27, 0
	s_mov_b32 m0, s36
	v_lshl_add_u64 v[204:205], s[26:27], 0, v[134:135]
	ds_read_b128 v[168:171], v150 offset:32768
	ds_read_b128 v[172:175], v150 offset:33792
	ds_read_b128 v[176:179], v150 offset:34816
	ds_read_b128 v[180:183], v150 offset:35840
	ds_read_b128 v[184:187], v150 offset:36864
	ds_read_b128 v[188:191], v150 offset:37888
	ds_read_b128 v[192:195], v150 offset:38912
	ds_read_b128 v[196:199], v150 offset:39936
	global_load_lds_dwordx4 v[204:205], off
	v_lshl_add_u64 v[204:205], s[26:27], 0, v[130:131]
	s_mov_b32 m0, s37
	s_nop 0
	global_load_lds_dwordx4 v[204:205], off
	s_waitcnt lgkmcnt(8)
	s_barrier
	s_waitcnt lgkmcnt(0)
	s_waitcnt lgkmcnt(0)
	v_mfma_f32_16x16x32_bf16 v[124:127], v[152:155], v[168:171], v[124:127]
	v_mfma_f32_16x16x32_bf16 v[120:123], v[160:163], v[168:171], v[120:123]
	v_mfma_f32_16x16x32_bf16 v[108:111], v[152:155], v[176:179], v[108:111]
	v_mfma_f32_16x16x32_bf16 v[104:107], v[160:163], v[176:179], v[104:107]
	v_mfma_f32_16x16x32_bf16 v[92:95], v[152:155], v[184:187], v[92:95]
	v_mfma_f32_16x16x32_bf16 v[88:91], v[160:163], v[184:187], v[88:91]
	v_mfma_f32_16x16x32_bf16 v[76:79], v[152:155], v[192:195], v[76:79]
	v_mfma_f32_16x16x32_bf16 v[72:75], v[160:163], v[192:195], v[72:75]
	v_mfma_f32_16x16x32_bf16 v[124:127], v[156:159], v[172:175], v[124:127]
	v_mfma_f32_16x16x32_bf16 v[120:123], v[164:167], v[172:175], v[120:123]
	v_mfma_f32_16x16x32_bf16 v[108:111], v[156:159], v[180:183], v[108:111]
	v_mfma_f32_16x16x32_bf16 v[104:107], v[164:167], v[180:183], v[104:107]
	v_mfma_f32_16x16x32_bf16 v[92:95], v[156:159], v[188:191], v[92:95]
	v_mfma_f32_16x16x32_bf16 v[88:91], v[164:167], v[188:191], v[88:91]
	v_mfma_f32_16x16x32_bf16 v[76:79], v[156:159], v[196:199], v[76:79]
	v_mfma_f32_16x16x32_bf16 v[72:75], v[164:167], v[196:199], v[72:75]
	s_barrier
	s_add_i32 s26, 0, 0x1c000
	s_add_i32 s27, s53, s31
	v_add_u32_e32 v216, s26, v147
	v_lshl_add_u64 v[144:145], v[144:145], 0, s[0:1]
	s_mov_b32 m0, s27
	ds_read_b128 v[204:207], v216
	ds_read_b128 v[208:211], v216 offset:1024
	ds_read_b128 v[212:215], v216 offset:2048
	ds_read_b128 v[216:219], v216 offset:3072
	global_load_lds_dwordx4 v[144:145], off
	v_lshl_add_u64 v[144:145], v[200:201], 0, s[0:1]
	s_add_i32 m0, s27, 0x2000
	s_nop 0
	global_load_lds_dwordx4 v[144:145], off
	s_barrier
	s_waitcnt lgkmcnt(0)
	s_waitcnt lgkmcnt(0)
	v_mfma_f32_16x16x32_bf16 v[116:119], v[204:207], v[168:171], v[116:119]
	v_mfma_f32_16x16x32_bf16 v[112:115], v[212:215], v[168:171], v[112:115]
	v_mfma_f32_16x16x32_bf16 v[100:103], v[204:207], v[176:179], v[100:103]
	v_mfma_f32_16x16x32_bf16 v[96:99], v[212:215], v[176:179], v[96:99]
	v_mfma_f32_16x16x32_bf16 v[84:87], v[204:207], v[184:187], v[84:87]
	v_mfma_f32_16x16x32_bf16 v[80:83], v[212:215], v[184:187], v[80:83]
	v_mfma_f32_16x16x32_bf16 v[68:71], v[204:207], v[192:195], v[68:71]
	v_mfma_f32_16x16x32_bf16 v[64:67], v[212:215], v[192:195], v[64:67]
	v_mfma_f32_16x16x32_bf16 v[116:119], v[208:211], v[172:175], v[116:119]
	v_mfma_f32_16x16x32_bf16 v[112:115], v[216:219], v[172:175], v[112:115]
	v_mfma_f32_16x16x32_bf16 v[100:103], v[208:211], v[180:183], v[100:103]
	v_mfma_f32_16x16x32_bf16 v[96:99], v[216:219], v[180:183], v[96:99]
	v_mfma_f32_16x16x32_bf16 v[84:87], v[208:211], v[188:191], v[84:87]
	v_mfma_f32_16x16x32_bf16 v[80:83], v[216:219], v[188:191], v[80:83]
	v_mfma_f32_16x16x32_bf16 v[68:71], v[208:211], v[196:199], v[68:71]
	v_mfma_f32_16x16x32_bf16 v[64:67], v[216:219], v[196:199], v[64:67]
	s_mov_b32 m0, s39
	v_lshl_add_u64 v[144:145], v[220:221], 0, s[0:1]
	s_barrier
	ds_read_b128 v[168:171], v150 offset:49152
	ds_read_b128 v[172:175], v150 offset:50176
	ds_read_b128 v[176:179], v150 offset:51200
	ds_read_b128 v[180:183], v150 offset:52224
	ds_read_b128 v[184:187], v150 offset:53248
	ds_read_b128 v[188:191], v150 offset:54272
	ds_read_b128 v[192:195], v150 offset:55296
	ds_read_b128 v[196:199], v150 offset:56320
	global_load_lds_dwordx4 v[144:145], off
	v_lshl_add_u64 v[144:145], v[222:223], 0, s[0:1]
	s_mov_b32 m0, s40
	s_nop 0
	global_load_lds_dwordx4 v[144:145], off
	s_barrier
	s_waitcnt lgkmcnt(0)
	s_waitcnt lgkmcnt(0)
	v_mfma_f32_16x16x32_bf16 v[60:63], v[152:155], v[168:171], v[60:63]
	v_mfma_f32_16x16x32_bf16 v[56:59], v[160:163], v[168:171], v[56:59]
	v_mfma_f32_16x16x32_bf16 v[44:47], v[152:155], v[176:179], v[44:47]
	v_mfma_f32_16x16x32_bf16 v[40:43], v[160:163], v[176:179], v[40:43]
	v_mfma_f32_16x16x32_bf16 v[28:31], v[152:155], v[184:187], v[28:31]
	v_mfma_f32_16x16x32_bf16 v[24:27], v[160:163], v[184:187], v[24:27]
	v_mfma_f32_16x16x32_bf16 v[12:15], v[152:155], v[192:195], v[12:15]
	v_mfma_f32_16x16x32_bf16 v[8:11], v[160:163], v[192:195], v[8:11]
	v_mfma_f32_16x16x32_bf16 v[60:63], v[156:159], v[172:175], v[60:63]
	v_mfma_f32_16x16x32_bf16 v[56:59], v[164:167], v[172:175], v[56:59]
	v_mfma_f32_16x16x32_bf16 v[44:47], v[156:159], v[180:183], v[44:47]
	v_mfma_f32_16x16x32_bf16 v[40:43], v[164:167], v[180:183], v[40:43]
	v_mfma_f32_16x16x32_bf16 v[28:31], v[156:159], v[188:191], v[28:31]
	v_mfma_f32_16x16x32_bf16 v[24:27], v[164:167], v[188:191], v[24:27]
	v_mfma_f32_16x16x32_bf16 v[12:15], v[156:159], v[196:199], v[12:15]
	v_mfma_f32_16x16x32_bf16 v[8:11], v[164:167], v[196:199], v[8:11]
	s_barrier
	s_add_u32 s24, s24, 0x20080
	s_addc_u32 s25, s25, 0
	s_add_i32 s26, s26, s31
	v_lshl_add_u64 v[144:145], s[24:25], 0, v[132:133]
	s_mov_b32 m0, s26
	s_nop 0
	global_load_lds_dwordx4 v[144:145], off
	v_lshl_add_u64 v[144:145], s[24:25], 0, v[128:129]
	s_add_i32 m0, s26, 0x2000
	s_nop 0
	global_load_lds_dwordx4 v[144:145], off
	s_waitcnt vmcnt(6)
	s_barrier
	v_mfma_f32_16x16x32_bf16 v[52:55], v[204:207], v[168:171], v[52:55]
	v_mfma_f32_16x16x32_bf16 v[48:51], v[212:215], v[168:171], v[48:51]
	v_mfma_f32_16x16x32_bf16 v[36:39], v[204:207], v[176:179], v[36:39]
	v_mfma_f32_16x16x32_bf16 v[32:35], v[212:215], v[176:179], v[32:35]
	v_mfma_f32_16x16x32_bf16 v[20:23], v[204:207], v[184:187], v[20:23]
	v_mfma_f32_16x16x32_bf16 v[16:19], v[212:215], v[184:187], v[16:19]
	v_mfma_f32_16x16x32_bf16 v[4:7], v[204:207], v[192:195], v[4:7]
	v_mfma_f32_16x16x32_bf16 v[0:3], v[212:215], v[192:195], v[0:3]
	v_mfma_f32_16x16x32_bf16 v[52:55], v[208:211], v[172:175], v[52:55]
	v_mfma_f32_16x16x32_bf16 v[48:51], v[216:219], v[172:175], v[48:51]
	v_mfma_f32_16x16x32_bf16 v[36:39], v[208:211], v[180:183], v[36:39]
	v_mfma_f32_16x16x32_bf16 v[32:35], v[216:219], v[180:183], v[32:35]
	v_mfma_f32_16x16x32_bf16 v[20:23], v[208:211], v[188:191], v[20:23]
	v_mfma_f32_16x16x32_bf16 v[16:19], v[216:219], v[188:191], v[16:19]
	v_mfma_f32_16x16x32_bf16 v[4:7], v[208:211], v[196:199], v[4:7]
	v_mfma_f32_16x16x32_bf16 v[0:3], v[216:219], v[196:199], v[0:3]
	s_add_i32 s52, s52, 2
	s_add_u32 s22, s22, 0x100
	s_addc_u32 s23, s23, 0
	s_add_u32 s50, s50, 0x100
	s_addc_u32 s51, s51, 0
	s_cmp_gt_u32 s52, 29
	s_barrier
	s_cbranch_scc0 .LBB0_1564
	v_readlane_b32 s100, v248, 63
	v_readlane_b32 s101, v247, 0
	v_and_b32_e32 v242, 15, v202
	v_bfe_u32 v243, v202, 4, 2
	v_bfe_u32 v244, v202, 6, 2
	v_lshrrev_b32_e32 v245, 8, v202
	v_and_b32_e32 v240, 7, v242
	v_lshl_add_u32 v240, v245, 6, v240
	v_lshl_add_u32 v240, s20, 8, v240
	v_lshlrev_b32_e32 v240, 14, v240
	v_lshrrev_b32_e32 v241, 3, v242
	v_lshlrev_b32_e32 v241, 6, v241
	v_lshl_add_u32 v241, v244, 7, v241
	v_lshl_add_u32 v241, v243, 4, v241
	v_add_u32_e32 v240, v240, v241
	s_lshl_b32 s98, s47, 9
	v_add_u32_e32 v240, s98, v240
	v_max_f32_e32 v124, 0, v124
	v_max_f32_e32 v125, 0, v125
	v_max_f32_e32 v126, 0, v126
	v_max_f32_e32 v127, 0, v127
	v_max_f32_e32 v120, 0, v120
	v_max_f32_e32 v121, 0, v121
	v_max_f32_e32 v122, 0, v122
	v_max_f32_e32 v123, 0, v123
	v_pk_mul_f32 v[124:125], v[124:125], v[124:125]
	v_pk_mul_f32 v[126:127], v[126:127], v[126:127]
	v_pk_mul_f32 v[120:121], v[120:121], v[120:121]
	v_pk_mul_f32 v[122:123], v[122:123], v[122:123]
	v_cvt_pk_bf16_f32 v228, v124, v125
	v_cvt_pk_bf16_f32 v229, v126, v127
	v_cvt_pk_bf16_f32 v230, v120, v121
	v_cvt_pk_bf16_f32 v231, v122, v123
	v_max_f32_e32 v116, 0, v116
	v_max_f32_e32 v117, 0, v117
	v_max_f32_e32 v118, 0, v118
	v_max_f32_e32 v119, 0, v119
	v_max_f32_e32 v112, 0, v112
	v_max_f32_e32 v113, 0, v113
	v_max_f32_e32 v114, 0, v114
	v_max_f32_e32 v115, 0, v115
	v_pk_mul_f32 v[116:117], v[116:117], v[116:117]
	v_pk_mul_f32 v[118:119], v[118:119], v[118:119]
	v_pk_mul_f32 v[112:113], v[112:113], v[112:113]
	v_pk_mul_f32 v[114:115], v[114:115], v[114:115]
	v_cvt_pk_bf16_f32 v232, v116, v117
	v_cvt_pk_bf16_f32 v233, v118, v119
	v_cvt_pk_bf16_f32 v234, v112, v113
	v_cvt_pk_bf16_f32 v235, v114, v115
	v_mov_b32_e32 v236, v228
	v_mov_b32_e32 v237, v229
	v_mov_b32_e32 v238, v230
	v_mov_b32_e32 v239, v231
	v_mov_b32_dpp v228, v232 row_ror:8 row_mask:0xf bank_mask:0xc
	v_mov_b32_dpp v229, v233 row_ror:8 row_mask:0xf bank_mask:0xc
	v_mov_b32_dpp v230, v234 row_ror:8 row_mask:0xf bank_mask:0xc
	v_mov_b32_dpp v231, v235 row_ror:8 row_mask:0xf bank_mask:0xc
	v_mov_b32_dpp v232, v236 row_ror:8 row_mask:0xf bank_mask:0x3
	v_mov_b32_dpp v233, v237 row_ror:8 row_mask:0xf bank_mask:0x3
	v_mov_b32_dpp v234, v238 row_ror:8 row_mask:0xf bank_mask:0x3
	v_mov_b32_dpp v235, v239 row_ror:8 row_mask:0xf bank_mask:0x3
	global_store_dwordx4 v240, v[228:231], s[100:101]
	s_add_u32 s100, s100, 0x20000
	s_addc_u32 s101, s101, 0
	global_store_dwordx4 v240, v[232:235], s[100:101]
	v_max_f32_e32 v108, 0, v108
	v_max_f32_e32 v109, 0, v109
	v_max_f32_e32 v110, 0, v110
	v_max_f32_e32 v111, 0, v111
	v_max_f32_e32 v104, 0, v104
	v_max_f32_e32 v105, 0, v105
	v_max_f32_e32 v106, 0, v106
	v_max_f32_e32 v107, 0, v107
	v_pk_mul_f32 v[108:109], v[108:109], v[108:109]
	v_pk_mul_f32 v[110:111], v[110:111], v[110:111]
	v_pk_mul_f32 v[104:105], v[104:105], v[104:105]
	v_pk_mul_f32 v[106:107], v[106:107], v[106:107]
	v_cvt_pk_bf16_f32 v228, v108, v109
	v_cvt_pk_bf16_f32 v229, v110, v111
	v_cvt_pk_bf16_f32 v230, v104, v105
	v_cvt_pk_bf16_f32 v231, v106, v107
	v_max_f32_e32 v100, 0, v100
	v_max_f32_e32 v101, 0, v101
	v_max_f32_e32 v102, 0, v102
	v_max_f32_e32 v103, 0, v103
	v_max_f32_e32 v96, 0, v96
	v_max_f32_e32 v97, 0, v97
	v_max_f32_e32 v98, 0, v98
	v_max_f32_e32 v99, 0, v99
	v_pk_mul_f32 v[100:101], v[100:101], v[100:101]
	v_pk_mul_f32 v[102:103], v[102:103], v[102:103]
	v_pk_mul_f32 v[96:97], v[96:97], v[96:97]
	v_pk_mul_f32 v[98:99], v[98:99], v[98:99]
	v_cvt_pk_bf16_f32 v232, v100, v101
	v_cvt_pk_bf16_f32 v233, v102, v103
	v_cvt_pk_bf16_f32 v234, v96, v97
	v_cvt_pk_bf16_f32 v235, v98, v99
	v_mov_b32_e32 v236, v228
	v_mov_b32_e32 v237, v229
	v_mov_b32_e32 v238, v230
	v_mov_b32_e32 v239, v231
	v_mov_b32_dpp v228, v232 row_ror:8 row_mask:0xf bank_mask:0xc
	v_mov_b32_dpp v229, v233 row_ror:8 row_mask:0xf bank_mask:0xc
	v_mov_b32_dpp v230, v234 row_ror:8 row_mask:0xf bank_mask:0xc
	v_mov_b32_dpp v231, v235 row_ror:8 row_mask:0xf bank_mask:0xc
	v_mov_b32_dpp v232, v236 row_ror:8 row_mask:0xf bank_mask:0x3
	v_mov_b32_dpp v233, v237 row_ror:8 row_mask:0xf bank_mask:0x3
	v_mov_b32_dpp v234, v238 row_ror:8 row_mask:0xf bank_mask:0x3
	v_mov_b32_dpp v235, v239 row_ror:8 row_mask:0xf bank_mask:0x3
	s_add_u32 s100, s100, 0x20000
	s_addc_u32 s101, s101, 0
	global_store_dwordx4 v240, v[228:231], s[100:101]
	s_add_u32 s100, s100, 0x20000
	s_addc_u32 s101, s101, 0
	global_store_dwordx4 v240, v[232:235], s[100:101]
	v_max_f32_e32 v92, 0, v92
	v_max_f32_e32 v93, 0, v93
	v_max_f32_e32 v94, 0, v94
	v_max_f32_e32 v95, 0, v95
	v_max_f32_e32 v88, 0, v88
	v_max_f32_e32 v89, 0, v89
	v_max_f32_e32 v90, 0, v90
	v_max_f32_e32 v91, 0, v91
	v_pk_mul_f32 v[92:93], v[92:93], v[92:93]
	v_pk_mul_f32 v[94:95], v[94:95], v[94:95]
	v_pk_mul_f32 v[88:89], v[88:89], v[88:89]
	v_pk_mul_f32 v[90:91], v[90:91], v[90:91]
	v_cvt_pk_bf16_f32 v228, v92, v93
	v_cvt_pk_bf16_f32 v229, v94, v95
	v_cvt_pk_bf16_f32 v230, v88, v89
	v_cvt_pk_bf16_f32 v231, v90, v91
	v_max_f32_e32 v84, 0, v84
	v_max_f32_e32 v85, 0, v85
	v_max_f32_e32 v86, 0, v86
	v_max_f32_e32 v87, 0, v87
	v_max_f32_e32 v80, 0, v80
	v_max_f32_e32 v81, 0, v81
	v_max_f32_e32 v82, 0, v82
	v_max_f32_e32 v83, 0, v83
	v_pk_mul_f32 v[84:85], v[84:85], v[84:85]
	v_pk_mul_f32 v[86:87], v[86:87], v[86:87]
	v_pk_mul_f32 v[80:81], v[80:81], v[80:81]
	v_pk_mul_f32 v[82:83], v[82:83], v[82:83]
	v_cvt_pk_bf16_f32 v232, v84, v85
	v_cvt_pk_bf16_f32 v233, v86, v87
	v_cvt_pk_bf16_f32 v234, v80, v81
	v_cvt_pk_bf16_f32 v235, v82, v83
	v_mov_b32_e32 v236, v228
	v_mov_b32_e32 v237, v229
	v_mov_b32_e32 v238, v230
	v_mov_b32_e32 v239, v231
	v_mov_b32_dpp v228, v232 row_ror:8 row_mask:0xf bank_mask:0xc
	v_mov_b32_dpp v229, v233 row_ror:8 row_mask:0xf bank_mask:0xc
	v_mov_b32_dpp v230, v234 row_ror:8 row_mask:0xf bank_mask:0xc
	v_mov_b32_dpp v231, v235 row_ror:8 row_mask:0xf bank_mask:0xc
	v_mov_b32_dpp v232, v236 row_ror:8 row_mask:0xf bank_mask:0x3
	v_mov_b32_dpp v233, v237 row_ror:8 row_mask:0xf bank_mask:0x3
	v_mov_b32_dpp v234, v238 row_ror:8 row_mask:0xf bank_mask:0x3
	v_mov_b32_dpp v235, v239 row_ror:8 row_mask:0xf bank_mask:0x3
	s_add_u32 s100, s100, 0x20000
	s_addc_u32 s101, s101, 0
	global_store_dwordx4 v240, v[228:231], s[100:101]
	s_add_u32 s100, s100, 0x20000
	s_addc_u32 s101, s101, 0
	global_store_dwordx4 v240, v[232:235], s[100:101]
	v_max_f32_e32 v76, 0, v76
	v_max_f32_e32 v77, 0, v77
	v_max_f32_e32 v78, 0, v78
	v_max_f32_e32 v79, 0, v79
	v_max_f32_e32 v72, 0, v72
	v_max_f32_e32 v73, 0, v73
	v_max_f32_e32 v74, 0, v74
	v_max_f32_e32 v75, 0, v75
	v_pk_mul_f32 v[76:77], v[76:77], v[76:77]
	v_pk_mul_f32 v[78:79], v[78:79], v[78:79]
	v_pk_mul_f32 v[72:73], v[72:73], v[72:73]
	v_pk_mul_f32 v[74:75], v[74:75], v[74:75]
	v_cvt_pk_bf16_f32 v228, v76, v77
	v_cvt_pk_bf16_f32 v229, v78, v79
	v_cvt_pk_bf16_f32 v230, v72, v73
	v_cvt_pk_bf16_f32 v231, v74, v75
	v_max_f32_e32 v68, 0, v68
	v_max_f32_e32 v69, 0, v69
	v_max_f32_e32 v70, 0, v70
	v_max_f32_e32 v71, 0, v71
	v_max_f32_e32 v64, 0, v64
	v_max_f32_e32 v65, 0, v65
	v_max_f32_e32 v66, 0, v66
	v_max_f32_e32 v67, 0, v67
	v_pk_mul_f32 v[68:69], v[68:69], v[68:69]
	v_pk_mul_f32 v[70:71], v[70:71], v[70:71]
	v_pk_mul_f32 v[64:65], v[64:65], v[64:65]
	v_pk_mul_f32 v[66:67], v[66:67], v[66:67]
	v_cvt_pk_bf16_f32 v232, v68, v69
	v_cvt_pk_bf16_f32 v233, v70, v71
	v_cvt_pk_bf16_f32 v234, v64, v65
	v_cvt_pk_bf16_f32 v235, v66, v67
	v_mov_b32_e32 v236, v228
	v_mov_b32_e32 v237, v229
	v_mov_b32_e32 v238, v230
	v_mov_b32_e32 v239, v231
	v_mov_b32_dpp v228, v232 row_ror:8 row_mask:0xf bank_mask:0xc
	v_mov_b32_dpp v229, v233 row_ror:8 row_mask:0xf bank_mask:0xc
	v_mov_b32_dpp v230, v234 row_ror:8 row_mask:0xf bank_mask:0xc
	v_mov_b32_dpp v231, v235 row_ror:8 row_mask:0xf bank_mask:0xc
	v_mov_b32_dpp v232, v236 row_ror:8 row_mask:0xf bank_mask:0x3
	v_mov_b32_dpp v233, v237 row_ror:8 row_mask:0xf bank_mask:0x3
	v_mov_b32_dpp v234, v238 row_ror:8 row_mask:0xf bank_mask:0x3
	v_mov_b32_dpp v235, v239 row_ror:8 row_mask:0xf bank_mask:0x3
	s_add_u32 s100, s100, 0x20000
	s_addc_u32 s101, s101, 0
	global_store_dwordx4 v240, v[228:231], s[100:101]
	s_add_u32 s100, s100, 0x20000
	s_addc_u32 s101, s101, 0
	global_store_dwordx4 v240, v[232:235], s[100:101]
	v_max_f32_e32 v60, 0, v60
	v_max_f32_e32 v61, 0, v61
	v_max_f32_e32 v62, 0, v62
	v_max_f32_e32 v63, 0, v63
	v_max_f32_e32 v56, 0, v56
	v_max_f32_e32 v57, 0, v57
	v_max_f32_e32 v58, 0, v58
	v_max_f32_e32 v59, 0, v59
	v_pk_mul_f32 v[60:61], v[60:61], v[60:61]
	v_pk_mul_f32 v[62:63], v[62:63], v[62:63]
	v_pk_mul_f32 v[56:57], v[56:57], v[56:57]
	v_pk_mul_f32 v[58:59], v[58:59], v[58:59]
	v_cvt_pk_bf16_f32 v228, v60, v61
	v_cvt_pk_bf16_f32 v229, v62, v63
	v_cvt_pk_bf16_f32 v230, v56, v57
	v_cvt_pk_bf16_f32 v231, v58, v59
	v_max_f32_e32 v52, 0, v52
	v_max_f32_e32 v53, 0, v53
	v_max_f32_e32 v54, 0, v54
	v_max_f32_e32 v55, 0, v55
	v_max_f32_e32 v48, 0, v48
	v_max_f32_e32 v49, 0, v49
	v_max_f32_e32 v50, 0, v50
	v_max_f32_e32 v51, 0, v51
	v_pk_mul_f32 v[52:53], v[52:53], v[52:53]
	v_pk_mul_f32 v[54:55], v[54:55], v[54:55]
	v_pk_mul_f32 v[48:49], v[48:49], v[48:49]
	v_pk_mul_f32 v[50:51], v[50:51], v[50:51]
	v_cvt_pk_bf16_f32 v232, v52, v53
	v_cvt_pk_bf16_f32 v233, v54, v55
	v_cvt_pk_bf16_f32 v234, v48, v49
	v_cvt_pk_bf16_f32 v235, v50, v51
	v_mov_b32_e32 v236, v228
	v_mov_b32_e32 v237, v229
	v_mov_b32_e32 v238, v230
	v_mov_b32_e32 v239, v231
	v_mov_b32_dpp v228, v232 row_ror:8 row_mask:0xf bank_mask:0xc
	v_mov_b32_dpp v229, v233 row_ror:8 row_mask:0xf bank_mask:0xc
	v_mov_b32_dpp v230, v234 row_ror:8 row_mask:0xf bank_mask:0xc
	v_mov_b32_dpp v231, v235 row_ror:8 row_mask:0xf bank_mask:0xc
	v_mov_b32_dpp v232, v236 row_ror:8 row_mask:0xf bank_mask:0x3
	v_mov_b32_dpp v233, v237 row_ror:8 row_mask:0xf bank_mask:0x3
	v_mov_b32_dpp v234, v238 row_ror:8 row_mask:0xf bank_mask:0x3
	v_mov_b32_dpp v235, v239 row_ror:8 row_mask:0xf bank_mask:0x3
	s_add_u32 s100, s100, 0x120000
	s_addc_u32 s101, s101, 0
	global_store_dwordx4 v240, v[228:231], s[100:101]
	s_add_u32 s100, s100, 0x20000
	s_addc_u32 s101, s101, 0
	global_store_dwordx4 v240, v[232:235], s[100:101]
	v_max_f32_e32 v44, 0, v44
	v_max_f32_e32 v45, 0, v45
	v_max_f32_e32 v46, 0, v46
	v_max_f32_e32 v47, 0, v47
	v_max_f32_e32 v40, 0, v40
	v_max_f32_e32 v41, 0, v41
	v_max_f32_e32 v42, 0, v42
	v_max_f32_e32 v43, 0, v43
	v_pk_mul_f32 v[44:45], v[44:45], v[44:45]
	v_pk_mul_f32 v[46:47], v[46:47], v[46:47]
	v_pk_mul_f32 v[40:41], v[40:41], v[40:41]
	v_pk_mul_f32 v[42:43], v[42:43], v[42:43]
	v_cvt_pk_bf16_f32 v228, v44, v45
	v_cvt_pk_bf16_f32 v229, v46, v47
	v_cvt_pk_bf16_f32 v230, v40, v41
	v_cvt_pk_bf16_f32 v231, v42, v43
	v_max_f32_e32 v36, 0, v36
	v_max_f32_e32 v37, 0, v37
	v_max_f32_e32 v38, 0, v38
	v_max_f32_e32 v39, 0, v39
	v_max_f32_e32 v32, 0, v32
	v_max_f32_e32 v33, 0, v33
	v_max_f32_e32 v34, 0, v34
	v_max_f32_e32 v35, 0, v35
	v_pk_mul_f32 v[36:37], v[36:37], v[36:37]
	v_pk_mul_f32 v[38:39], v[38:39], v[38:39]
	v_pk_mul_f32 v[32:33], v[32:33], v[32:33]
	v_pk_mul_f32 v[34:35], v[34:35], v[34:35]
	v_cvt_pk_bf16_f32 v232, v36, v37
	v_cvt_pk_bf16_f32 v233, v38, v39
	v_cvt_pk_bf16_f32 v234, v32, v33
	v_cvt_pk_bf16_f32 v235, v34, v35
	v_mov_b32_e32 v236, v228
	v_mov_b32_e32 v237, v229
	v_mov_b32_e32 v238, v230
	v_mov_b32_e32 v239, v231
	v_mov_b32_dpp v228, v232 row_ror:8 row_mask:0xf bank_mask:0xc
	v_mov_b32_dpp v229, v233 row_ror:8 row_mask:0xf bank_mask:0xc
	v_mov_b32_dpp v230, v234 row_ror:8 row_mask:0xf bank_mask:0xc
	v_mov_b32_dpp v231, v235 row_ror:8 row_mask:0xf bank_mask:0xc
	v_mov_b32_dpp v232, v236 row_ror:8 row_mask:0xf bank_mask:0x3
	v_mov_b32_dpp v233, v237 row_ror:8 row_mask:0xf bank_mask:0x3
	v_mov_b32_dpp v234, v238 row_ror:8 row_mask:0xf bank_mask:0x3
	v_mov_b32_dpp v235, v239 row_ror:8 row_mask:0xf bank_mask:0x3
	s_add_u32 s100, s100, 0x20000
	s_addc_u32 s101, s101, 0
	global_store_dwordx4 v240, v[228:231], s[100:101]
	s_add_u32 s100, s100, 0x20000
	s_addc_u32 s101, s101, 0
	global_store_dwordx4 v240, v[232:235], s[100:101]
	v_max_f32_e32 v28, 0, v28
	v_max_f32_e32 v29, 0, v29
	v_max_f32_e32 v30, 0, v30
	v_max_f32_e32 v31, 0, v31
	v_max_f32_e32 v24, 0, v24
	v_max_f32_e32 v25, 0, v25
	v_max_f32_e32 v26, 0, v26
	v_max_f32_e32 v27, 0, v27
	v_pk_mul_f32 v[28:29], v[28:29], v[28:29]
	v_pk_mul_f32 v[30:31], v[30:31], v[30:31]
	v_pk_mul_f32 v[24:25], v[24:25], v[24:25]
	v_pk_mul_f32 v[26:27], v[26:27], v[26:27]
	v_cvt_pk_bf16_f32 v228, v28, v29
	v_cvt_pk_bf16_f32 v229, v30, v31
	v_cvt_pk_bf16_f32 v230, v24, v25
	v_cvt_pk_bf16_f32 v231, v26, v27
	v_max_f32_e32 v20, 0, v20
	v_max_f32_e32 v21, 0, v21
	v_max_f32_e32 v22, 0, v22
	v_max_f32_e32 v23, 0, v23
	v_max_f32_e32 v16, 0, v16
	v_max_f32_e32 v17, 0, v17
	v_max_f32_e32 v18, 0, v18
	v_max_f32_e32 v19, 0, v19
	v_pk_mul_f32 v[20:21], v[20:21], v[20:21]
	v_pk_mul_f32 v[22:23], v[22:23], v[22:23]
	v_pk_mul_f32 v[16:17], v[16:17], v[16:17]
	v_pk_mul_f32 v[18:19], v[18:19], v[18:19]
	v_cvt_pk_bf16_f32 v232, v20, v21
	v_cvt_pk_bf16_f32 v233, v22, v23
	v_cvt_pk_bf16_f32 v234, v16, v17
	v_cvt_pk_bf16_f32 v235, v18, v19
	v_mov_b32_e32 v236, v228
	v_mov_b32_e32 v237, v229
	v_mov_b32_e32 v238, v230
	v_mov_b32_e32 v239, v231
	v_mov_b32_dpp v228, v232 row_ror:8 row_mask:0xf bank_mask:0xc
	v_mov_b32_dpp v229, v233 row_ror:8 row_mask:0xf bank_mask:0xc
	v_mov_b32_dpp v230, v234 row_ror:8 row_mask:0xf bank_mask:0xc
	v_mov_b32_dpp v231, v235 row_ror:8 row_mask:0xf bank_mask:0xc
	v_mov_b32_dpp v232, v236 row_ror:8 row_mask:0xf bank_mask:0x3
	v_mov_b32_dpp v233, v237 row_ror:8 row_mask:0xf bank_mask:0x3
	v_mov_b32_dpp v234, v238 row_ror:8 row_mask:0xf bank_mask:0x3
	v_mov_b32_dpp v235, v239 row_ror:8 row_mask:0xf bank_mask:0x3
	s_add_u32 s100, s100, 0x20000
	s_addc_u32 s101, s101, 0
	global_store_dwordx4 v240, v[228:231], s[100:101]
	s_add_u32 s100, s100, 0x20000
	s_addc_u32 s101, s101, 0
	global_store_dwordx4 v240, v[232:235], s[100:101]
	v_max_f32_e32 v12, 0, v12
	v_max_f32_e32 v13, 0, v13
	v_max_f32_e32 v14, 0, v14
	v_max_f32_e32 v15, 0, v15
	v_max_f32_e32 v8, 0, v8
	v_max_f32_e32 v9, 0, v9
	v_max_f32_e32 v10, 0, v10
	v_max_f32_e32 v11, 0, v11
	v_pk_mul_f32 v[12:13], v[12:13], v[12:13]
	v_pk_mul_f32 v[14:15], v[14:15], v[14:15]
	v_pk_mul_f32 v[8:9], v[8:9], v[8:9]
	v_pk_mul_f32 v[10:11], v[10:11], v[10:11]
	v_cvt_pk_bf16_f32 v228, v12, v13
	v_cvt_pk_bf16_f32 v229, v14, v15
	v_cvt_pk_bf16_f32 v230, v8, v9
	v_cvt_pk_bf16_f32 v231, v10, v11
	v_max_f32_e32 v4, 0, v4
	v_max_f32_e32 v5, 0, v5
	v_max_f32_e32 v6, 0, v6
	v_max_f32_e32 v7, 0, v7
	v_max_f32_e32 v0, 0, v0
	v_max_f32_e32 v1, 0, v1
	v_max_f32_e32 v2, 0, v2
	v_max_f32_e32 v3, 0, v3
	v_pk_mul_f32 v[4:5], v[4:5], v[4:5]
	v_pk_mul_f32 v[6:7], v[6:7], v[6:7]
	v_pk_mul_f32 v[0:1], v[0:1], v[0:1]
	v_pk_mul_f32 v[2:3], v[2:3], v[2:3]
	v_cvt_pk_bf16_f32 v232, v4, v5
	v_cvt_pk_bf16_f32 v233, v6, v7
	v_cvt_pk_bf16_f32 v234, v0, v1
	v_cvt_pk_bf16_f32 v235, v2, v3
	v_mov_b32_e32 v236, v228
	v_mov_b32_e32 v237, v229
	v_mov_b32_e32 v238, v230
	v_mov_b32_e32 v239, v231
	v_mov_b32_dpp v228, v232 row_ror:8 row_mask:0xf bank_mask:0xc
	v_mov_b32_dpp v229, v233 row_ror:8 row_mask:0xf bank_mask:0xc
	v_mov_b32_dpp v230, v234 row_ror:8 row_mask:0xf bank_mask:0xc
	v_mov_b32_dpp v231, v235 row_ror:8 row_mask:0xf bank_mask:0xc
	v_mov_b32_dpp v232, v236 row_ror:8 row_mask:0xf bank_mask:0x3
	v_mov_b32_dpp v233, v237 row_ror:8 row_mask:0xf bank_mask:0x3
	v_mov_b32_dpp v234, v238 row_ror:8 row_mask:0xf bank_mask:0x3
	v_mov_b32_dpp v235, v239 row_ror:8 row_mask:0xf bank_mask:0x3
	s_add_u32 s100, s100, 0x20000
	s_addc_u32 s101, s101, 0
	global_store_dwordx4 v240, v[228:231], s[100:101]
	s_add_u32 s100, s100, 0x20000
	s_addc_u32 s101, s101, 0
	global_store_dwordx4 v240, v[232:235], s[100:101]
	s_and_b64 vcc, exec, s[2:3]
	s_mov_b32 s47, s12
	s_mov_b32 s20, s14
	s_mov_b64 s[24:25], s[18:19]
	s_mov_b64 s[22:23], s[16:17]
	s_cbranch_vccz .LBB0_1561
	s_waitcnt vmcnt(0)
	s_cmpk_gt_u32 s28, 0xff
	s_cbranch_scc1 .LBB0_1568
	s_barrier

.Lprio_skip_14:
	v_readlane_b32 s0, v247, 12
	v_mov_b32_e32 v8, v202
	v_readlane_b32 s1, v247, 13
	s_waitcnt lgkmcnt(0)
	s_barrier
	s_and_b64 vcc, exec, s[0:1]
	v_readfirstlane_b32 s26, v8
	s_cbranch_vccz .LBB0_1635
	v_lshlrev_b32_e32 v0, 4, v8
	v_add_u32_e32 v1, 0x2000, v0
	v_ashrrev_i32_e32 v2, 31, v1
	v_lshrrev_b32_e32 v2, 22, v2
	v_add_u32_e32 v2, v1, v2
	v_ashrrev_i32_e32 v9, 10, v2
	v_mul_i32_i24_e32 v2, 0x400, v9
	v_sub_u32_e32 v1, v1, v2
	v_lshrrev_b32_e32 v2, 4, v1
	v_bitop3_b32 v1, v2, v1, 32 bitop3:0x6c
	v_ashrrev_i32_e32 v2, 31, v1
	v_lshrrev_b32_e32 v2, 26, v2
	v_add_u32_e32 v2, v1, v2
	v_lshlrev_b32_e32 v3, 3, v9
	v_ashrrev_i32_e32 v10, 6, v2
	v_and_b32_e32 v3, -16, v3
	s_add_u32 s27, s58, 0xc100000
	v_readlane_b32 s3, v248, 59
	v_readlane_b32 s4, v248, 60
	v_add_u32_e32 v3, v10, v3
	s_addc_u32 s28, s59, 0
	s_sub_i32 s4, s3, s4
	v_and_b32_e32 v4, 3, v10
	s_mov_b32 s3, 0x3ffe0
	v_lshrrev_b32_e32 v5, 2, v3
	v_lshlrev_b32_e32 v6, 1, v3
	v_and_b32_e32 v2, 0xc0, v2
	v_and_or_b32 v4, v3, s3, v4
	v_and_b32_e32 v5, 4, v5
	v_and_b32_e32 v6, 24, v6
	v_sub_u32_e32 v1, v1, v2
	v_mov_b32_e32 v2, 1
	v_or3_b32 v4, v4, v5, v6
	v_lshlrev_b32_e32 v5, 5, v9
	v_ashrrev_i16_sdwa v1, v2, sext(v1) dst_sel:DWORD dst_unused:UNUSED_PAD src0_sel:DWORD src1_sel:BYTE_0
	v_and_b32_e32 v5, 32, v5
	v_bfe_i32 v11, v1, 0, 16
	v_add_lshl_u32 v1, v5, v11, 1
	v_lshl_add_u32 v128, v4, 14, v1
	v_lshl_add_u32 v130, v3, 14, v1
	v_bfe_i32 v1, v8, 27, 1
	v_lshrrev_b32_e32 v1, 22, v1
	v_add_u32_e32 v1, v0, v1
	v_and_b32_e32 v1, 0xfffffc00, v1
	v_sub_u32_e32 v0, v0, v1
	v_lshrrev_b32_e32 v1, 4, v0
	v_ashrrev_i32_e32 v3, 31, v8
	v_bitop3_b32 v0, v1, v0, 32 bitop3:0x6c
	v_lshrrev_b32_e32 v3, 26, v3
	v_ashrrev_i32_e32 v1, 31, v0
	v_add_u32_e32 v3, v8, v3
	v_lshrrev_b32_e32 v1, 26, v1
	v_ashrrev_i32_e32 v13, 6, v3
	v_readlane_b32 s6, v248, 61
	v_add_u32_e32 v1, v0, v1
	v_lshlrev_b32_e32 v3, 3, v13
	v_readlane_b32 s7, v248, 62
	v_ashrrev_i32_e32 v12, 6, v1
	v_and_b32_e32 v3, -16, v3
	s_ashr_i32 s0, s26, 6
	v_readlane_b32 s1, v248, 58
	s_ashr_i32 s5, s4, 31
	s_ashr_i32 s7, s6, 31
	v_add_u32_e32 v3, v12, v3
	s_ashr_i32 s2, s26, 8
	s_lshl_b32 s29, s0, 10
	s_lshl_b32 s1, s1, 22
	s_lshl_b64 s[4:5], s[4:5], 7
	s_mov_b32 s52, s6
	s_lshl_b64 s[6:7], s[6:7], 22
	v_and_b32_e32 v4, 3, v12
	v_lshrrev_b32_e32 v5, 2, v3
	v_lshlrev_b32_e32 v6, 1, v3
	v_and_b32_e32 v1, 0xc0, v1
	v_and_or_b32 v4, v3, s3, v4
	v_and_b32_e32 v5, 4, v5
	v_and_b32_e32 v6, 24, v6
	v_sub_u32_e32 v0, v0, v1
	s_add_u32 s1, s27, s1
	v_or3_b32 v4, v4, v5, v6
	v_lshlrev_b32_e32 v5, 5, v13
	v_ashrrev_i16_sdwa v0, v2, sext(v0) dst_sel:DWORD dst_unused:UNUSED_PAD src0_sel:DWORD src1_sel:BYTE_0
	s_addc_u32 s3, s28, 0
	v_and_b32_e32 v5, 32, v5
	v_bfe_i32 v14, v0, 0, 16
	s_add_u32 s22, s1, s4
	v_add_lshl_u32 v0, v5, v14, 1
	s_addc_u32 s23, s3, s5
	s_add_i32 s30, s29, 0
	v_lshl_add_u32 v132, v4, 14, v0
	s_add_i32 m0, s30, 0x10000
	v_readlane_b32 s8, v248, 63
	v_mov_b32_e32 v230, s2
	v_lshlrev_b32_e32 v230, 19, v230
	v_add_u32_e32 v132, v132, v230
	v_add_u32_e32 v230, 0x100000, v230
	v_add_u32_e32 v128, v128, v230
	global_load_lds_dwordx4 v132, s[22:23]
	s_add_i32 m0, s30, 0x12000
	v_readlane_b32 s9, v247, 0
	s_add_u32 s1, s8, s6
	s_addc_u32 s3, s9, s7
	s_add_u32 s20, s1, s4
	v_lshl_add_u32 v134, v3, 14, v0
	global_load_lds_dwordx4 v128, s[22:23]
	s_addc_u32 s21, s3, s5
	s_mov_b32 m0, s30
	s_add_i32 s31, s30, 0x2000
	global_load_lds_dwordx4 v134, s[20:21]
	s_mov_b32 m0, s31
	s_add_u32 s4, s22, 0x80000
	global_load_lds_dwordx4 v130, s[20:21]
	s_addc_u32 s5, s23, 0
	s_add_i32 m0, s30, 0x14000
	v_mov_b32_e32 v133, 0
	global_load_lds_dwordx4 v132, s[4:5]
	s_add_i32 m0, s30, 0x16000
	v_mov_b32_e32 v129, v133
	global_load_lds_dwordx4 v128, s[4:5]
	s_add_u32 s4, s20, 0x200000
	s_addc_u32 s5, s21, 0
	s_add_i32 s34, s30, 0x4000
	s_mov_b32 m0, s34
	s_add_i32 s35, s30, 0x6000
	global_load_lds_dwordx4 v134, s[4:5]
	s_mov_b32 m0, s35
	v_mov_b32_e32 v135, v133
	global_load_lds_dwordx4 v130, s[4:5]
	v_mov_b32_e32 v131, v133
	s_mov_b32 s36, 0
	v_lshl_add_u64 v[6:7], s[22:23], 0, v[132:133]
	v_lshl_add_u64 v[4:5], s[22:23], 0, v[128:129]
	v_lshl_add_u64 v[2:3], s[20:21], 0, v[134:135]
	s_cmp_lg_u32 s2, 1
	v_lshl_add_u64 v[0:1], s[20:21], 0, v[130:131]
	s_cbranch_scc1 .LBB0_1624
	s_barrier

.LBB0_1631:
	ds_read_b128 v[146:149], v143
	ds_read_b128 v[150:153], v143 offset:1024
	ds_read_b128 v[154:157], v143 offset:2048
	ds_read_b128 v[158:161], v143 offset:3072
	s_add_i32 s51, s22, 2
	s_add_u32 s23, s20, 0xffe00080
	s_addc_u32 s24, s21, -1
	s_cmp_eq_u32 s48, s22
	s_cselect_b32 s22, s47, s49
	s_cselect_b32 s25, s11, s24
	s_cselect_b32 s24, s13, s23
	s_cselect_b32 s23, s46, s50
	v_lshl_add_u64 v[194:195], s[20:21], 0, v[136:137]
	s_add_i32 m0, s30, 0xc000
	ds_read_b128 v[162:165], v144
	ds_read_b128 v[166:169], v144 offset:1024
	ds_read_b128 v[170:173], v144 offset:2048
	ds_read_b128 v[174:177], v144 offset:3072
	ds_read_b128 v[178:181], v144 offset:4096
	ds_read_b128 v[182:185], v144 offset:5120
	ds_read_b128 v[186:189], v144 offset:6144
	ds_read_b128 v[190:193], v144 offset:7168
	global_load_lds_dwordx4 v[194:195], off
	v_lshl_add_u64 v[194:195], s[20:21], 0, v[138:139]
	s_add_i32 m0, s30, 0xe000
	s_nop 0
	global_load_lds_dwordx4 v[194:195], off
	s_waitcnt lgkmcnt(8)
	s_barrier
	s_waitcnt lgkmcnt(0)
	s_waitcnt lgkmcnt(0)
	v_mfma_f32_16x16x32_bf16 v[124:127], v[146:149], v[162:165], v[124:127]
	v_mfma_f32_16x16x32_bf16 v[120:123], v[154:157], v[162:165], v[120:123]
	v_mfma_f32_16x16x32_bf16 v[108:111], v[146:149], v[170:173], v[108:111]
	v_mfma_f32_16x16x32_bf16 v[104:107], v[154:157], v[170:173], v[104:107]
	v_mfma_f32_16x16x32_bf16 v[92:95], v[146:149], v[178:181], v[92:95]
	v_mfma_f32_16x16x32_bf16 v[88:91], v[154:157], v[178:181], v[88:91]
	v_mfma_f32_16x16x32_bf16 v[76:79], v[146:149], v[186:189], v[76:79]
	v_mfma_f32_16x16x32_bf16 v[72:75], v[154:157], v[186:189], v[72:75]
	v_mfma_f32_16x16x32_bf16 v[124:127], v[150:153], v[166:169], v[124:127]
	v_mfma_f32_16x16x32_bf16 v[120:123], v[158:161], v[166:169], v[120:123]
	v_mfma_f32_16x16x32_bf16 v[108:111], v[150:153], v[174:177], v[108:111]
	v_mfma_f32_16x16x32_bf16 v[104:107], v[158:161], v[174:177], v[104:107]
	v_mfma_f32_16x16x32_bf16 v[92:95], v[150:153], v[182:185], v[92:95]
	v_mfma_f32_16x16x32_bf16 v[88:91], v[158:161], v[182:185], v[88:91]
	v_mfma_f32_16x16x32_bf16 v[76:79], v[150:153], v[190:193], v[76:79]
	v_mfma_f32_16x16x32_bf16 v[72:75], v[158:161], v[190:193], v[72:75]
	s_barrier
	s_add_i32 s52, s39, s29
	v_lshl_add_u64 v[212:213], s[22:23], 0, v[132:133]
	s_mov_b32 m0, s52
	ds_read_b128 v[194:197], v145
	ds_read_b128 v[198:201], v145 offset:1024
	ds_read_b128 v[204:207], v145 offset:2048
	ds_read_b128 v[208:211], v145 offset:3072
	global_load_lds_dwordx4 v[212:213], off
	v_lshl_add_u64 v[214:215], s[22:23], 0, v[128:129]
	s_add_i32 m0, s52, 0x2000
	s_nop 0
	global_load_lds_dwordx4 v[214:215], off
	s_barrier
	s_waitcnt lgkmcnt(0)
	s_waitcnt lgkmcnt(0)
	v_mfma_f32_16x16x32_bf16 v[116:119], v[194:197], v[162:165], v[116:119]
	v_mfma_f32_16x16x32_bf16 v[112:115], v[204:207], v[162:165], v[112:115]
	v_mfma_f32_16x16x32_bf16 v[100:103], v[194:197], v[170:173], v[100:103]
	v_mfma_f32_16x16x32_bf16 v[96:99], v[204:207], v[170:173], v[96:99]
	v_mfma_f32_16x16x32_bf16 v[84:87], v[194:197], v[178:181], v[84:87]
	v_mfma_f32_16x16x32_bf16 v[80:83], v[204:207], v[178:181], v[80:83]
	v_mfma_f32_16x16x32_bf16 v[68:71], v[194:197], v[186:189], v[68:71]
	v_mfma_f32_16x16x32_bf16 v[64:67], v[204:207], v[186:189], v[64:67]
	v_mfma_f32_16x16x32_bf16 v[116:119], v[198:201], v[166:169], v[116:119]
	v_mfma_f32_16x16x32_bf16 v[112:115], v[208:211], v[166:169], v[112:115]
	v_mfma_f32_16x16x32_bf16 v[100:103], v[198:201], v[174:177], v[100:103]
	v_mfma_f32_16x16x32_bf16 v[96:99], v[208:211], v[174:177], v[96:99]
	v_mfma_f32_16x16x32_bf16 v[84:87], v[198:201], v[182:185], v[84:87]
	v_mfma_f32_16x16x32_bf16 v[80:83], v[208:211], v[182:185], v[80:83]
	v_mfma_f32_16x16x32_bf16 v[68:71], v[198:201], v[190:193], v[68:71]
	v_mfma_f32_16x16x32_bf16 v[64:67], v[208:211], v[190:193], v[64:67]
	s_mov_b32 m0, s30
	v_lshl_add_u64 v[216:217], s[24:25], 0, v[134:135]
	s_barrier
	ds_read_b128 v[162:165], v144 offset:16384
	ds_read_b128 v[166:169], v144 offset:17408
	ds_read_b128 v[170:173], v144 offset:18432
	ds_read_b128 v[174:177], v144 offset:19456
	ds_read_b128 v[178:181], v144 offset:20480
	ds_read_b128 v[182:185], v144 offset:21504
	ds_read_b128 v[186:189], v144 offset:22528
	ds_read_b128 v[190:193], v144 offset:23552
	global_load_lds_dwordx4 v[216:217], off
	v_lshl_add_u64 v[218:219], s[24:25], 0, v[130:131]
	s_mov_b32 m0, s31
	s_nop 0
	global_load_lds_dwordx4 v[218:219], off
	s_barrier
	s_waitcnt lgkmcnt(0)
	s_waitcnt lgkmcnt(0)
	v_mfma_f32_16x16x32_bf16 v[60:63], v[146:149], v[162:165], v[60:63]
	v_mfma_f32_16x16x32_bf16 v[56:59], v[154:157], v[162:165], v[56:59]
	v_mfma_f32_16x16x32_bf16 v[44:47], v[146:149], v[170:173], v[44:47]
	v_mfma_f32_16x16x32_bf16 v[40:43], v[154:157], v[170:173], v[40:43]
	v_mfma_f32_16x16x32_bf16 v[28:31], v[146:149], v[178:181], v[28:31]
	v_mfma_f32_16x16x32_bf16 v[24:27], v[154:157], v[178:181], v[24:27]
	v_mfma_f32_16x16x32_bf16 v[12:15], v[146:149], v[186:189], v[12:15]
	v_mfma_f32_16x16x32_bf16 v[8:11], v[154:157], v[186:189], v[8:11]
	v_mfma_f32_16x16x32_bf16 v[60:63], v[150:153], v[166:169], v[60:63]
	v_mfma_f32_16x16x32_bf16 v[56:59], v[158:161], v[166:169], v[56:59]
	v_mfma_f32_16x16x32_bf16 v[44:47], v[150:153], v[174:177], v[44:47]
	v_mfma_f32_16x16x32_bf16 v[40:43], v[158:161], v[174:177], v[40:43]
	v_mfma_f32_16x16x32_bf16 v[28:31], v[150:153], v[182:185], v[28:31]
	v_mfma_f32_16x16x32_bf16 v[24:27], v[158:161], v[182:185], v[24:27]
	v_mfma_f32_16x16x32_bf16 v[12:15], v[150:153], v[190:193], v[12:15]
	v_mfma_f32_16x16x32_bf16 v[8:11], v[158:161], v[190:193], v[8:11]
	s_barrier
	s_add_u32 s52, s22, 0x80000
	s_addc_u32 s53, s23, 0
	s_add_i32 s54, s40, s29
	v_lshl_add_u64 v[146:147], s[52:53], 0, v[132:133]
	s_mov_b32 m0, s54
	s_nop 0
	global_load_lds_dwordx4 v[146:147], off
	v_lshl_add_u64 v[146:147], s[52:53], 0, v[128:129]
	s_add_i32 m0, s54, 0x2000
	s_nop 0
	global_load_lds_dwordx4 v[146:147], off
	s_waitcnt vmcnt(6)
	s_barrier
	v_mfma_f32_16x16x32_bf16 v[52:55], v[194:197], v[162:165], v[52:55]
	v_mfma_f32_16x16x32_bf16 v[48:51], v[204:207], v[162:165], v[48:51]
	v_mfma_f32_16x16x32_bf16 v[36:39], v[194:197], v[170:173], v[36:39]
	v_mfma_f32_16x16x32_bf16 v[32:35], v[204:207], v[170:173], v[32:35]
	v_mfma_f32_16x16x32_bf16 v[20:23], v[194:197], v[178:181], v[20:23]
	v_mfma_f32_16x16x32_bf16 v[16:19], v[204:207], v[178:181], v[16:19]
	v_mfma_f32_16x16x32_bf16 v[4:7], v[194:197], v[186:189], v[4:7]
	v_mfma_f32_16x16x32_bf16 v[0:3], v[204:207], v[186:189], v[0:3]
	v_mfma_f32_16x16x32_bf16 v[52:55], v[198:201], v[166:169], v[52:55]
	v_mfma_f32_16x16x32_bf16 v[48:51], v[208:211], v[166:169], v[48:51]
	v_mfma_f32_16x16x32_bf16 v[36:39], v[198:201], v[174:177], v[36:39]
	v_mfma_f32_16x16x32_bf16 v[32:35], v[208:211], v[174:177], v[32:35]
	v_mfma_f32_16x16x32_bf16 v[20:23], v[198:201], v[182:185], v[20:23]
	v_mfma_f32_16x16x32_bf16 v[16:19], v[208:211], v[182:185], v[16:19]
	v_mfma_f32_16x16x32_bf16 v[4:7], v[198:201], v[190:193], v[4:7]
	v_mfma_f32_16x16x32_bf16 v[0:3], v[208:211], v[190:193], v[0:3]
	s_add_i32 s52, 0, 0x18000
	v_add_u32_e32 v158, s52, v141
	s_barrier
	ds_read_b128 v[146:149], v158
	ds_read_b128 v[150:153], v158 offset:1024
	ds_read_b128 v[154:157], v158 offset:2048
	ds_read_b128 v[158:161], v158 offset:3072
	s_add_u32 s24, s24, 0x200000
	s_addc_u32 s25, s25, 0
	s_mov_b32 m0, s34
	v_lshl_add_u64 v[194:195], s[24:25], 0, v[134:135]
	ds_read_b128 v[162:165], v144 offset:32768
	ds_read_b128 v[166:169], v144 offset:33792
	ds_read_b128 v[170:173], v144 offset:34816
	ds_read_b128 v[174:177], v144 offset:35840
	ds_read_b128 v[178:181], v144 offset:36864
	ds_read_b128 v[182:185], v144 offset:37888
	ds_read_b128 v[186:189], v144 offset:38912
	ds_read_b128 v[190:193], v144 offset:39936
	global_load_lds_dwordx4 v[194:195], off
	v_lshl_add_u64 v[194:195], s[24:25], 0, v[130:131]
	s_mov_b32 m0, s35
	s_nop 0
	global_load_lds_dwordx4 v[194:195], off
	s_waitcnt lgkmcnt(8)
	s_barrier
	s_waitcnt lgkmcnt(0)
	s_waitcnt lgkmcnt(0)
	v_mfma_f32_16x16x32_bf16 v[124:127], v[146:149], v[162:165], v[124:127]
	v_mfma_f32_16x16x32_bf16 v[120:123], v[154:157], v[162:165], v[120:123]
	v_mfma_f32_16x16x32_bf16 v[108:111], v[146:149], v[170:173], v[108:111]
	v_mfma_f32_16x16x32_bf16 v[104:107], v[154:157], v[170:173], v[104:107]
	v_mfma_f32_16x16x32_bf16 v[92:95], v[146:149], v[178:181], v[92:95]
	v_mfma_f32_16x16x32_bf16 v[88:91], v[154:157], v[178:181], v[88:91]
	v_mfma_f32_16x16x32_bf16 v[76:79], v[146:149], v[186:189], v[76:79]
	v_mfma_f32_16x16x32_bf16 v[72:75], v[154:157], v[186:189], v[72:75]
	v_mfma_f32_16x16x32_bf16 v[124:127], v[150:153], v[166:169], v[124:127]
	v_mfma_f32_16x16x32_bf16 v[120:123], v[158:161], v[166:169], v[120:123]
	v_mfma_f32_16x16x32_bf16 v[108:111], v[150:153], v[174:177], v[108:111]
	v_mfma_f32_16x16x32_bf16 v[104:107], v[158:161], v[174:177], v[104:107]
	v_mfma_f32_16x16x32_bf16 v[92:95], v[150:153], v[182:185], v[92:95]
	v_mfma_f32_16x16x32_bf16 v[88:91], v[158:161], v[182:185], v[88:91]
	v_mfma_f32_16x16x32_bf16 v[76:79], v[150:153], v[190:193], v[76:79]
	v_mfma_f32_16x16x32_bf16 v[72:75], v[158:161], v[190:193], v[72:75]
	s_barrier
	s_add_i32 s24, 0, 0x1c000
	s_add_i32 s25, s52, s29
	v_add_u32_e32 v208, s24, v141
	v_lshl_add_u64 v[212:213], v[212:213], 0, s[0:1]
	s_mov_b32 m0, s25
	ds_read_b128 v[194:197], v208
	ds_read_b128 v[198:201], v208 offset:1024
	ds_read_b128 v[204:207], v208 offset:2048
	ds_read_b128 v[208:211], v208 offset:3072
	global_load_lds_dwordx4 v[212:213], off
	v_lshl_add_u64 v[212:213], v[214:215], 0, s[0:1]
	s_add_i32 m0, s25, 0x2000
	s_nop 0
	global_load_lds_dwordx4 v[212:213], off
	s_barrier
	s_waitcnt lgkmcnt(0)
	s_waitcnt lgkmcnt(0)
	v_mfma_f32_16x16x32_bf16 v[116:119], v[194:197], v[162:165], v[116:119]
	v_mfma_f32_16x16x32_bf16 v[112:115], v[204:207], v[162:165], v[112:115]
	v_mfma_f32_16x16x32_bf16 v[100:103], v[194:197], v[170:173], v[100:103]
	v_mfma_f32_16x16x32_bf16 v[96:99], v[204:207], v[170:173], v[96:99]
	v_mfma_f32_16x16x32_bf16 v[84:87], v[194:197], v[178:181], v[84:87]
	v_mfma_f32_16x16x32_bf16 v[80:83], v[204:207], v[178:181], v[80:83]
	v_mfma_f32_16x16x32_bf16 v[68:71], v[194:197], v[186:189], v[68:71]
	v_mfma_f32_16x16x32_bf16 v[64:67], v[204:207], v[186:189], v[64:67]
	v_mfma_f32_16x16x32_bf16 v[116:119], v[198:201], v[166:169], v[116:119]
	v_mfma_f32_16x16x32_bf16 v[112:115], v[208:211], v[166:169], v[112:115]
	v_mfma_f32_16x16x32_bf16 v[100:103], v[198:201], v[174:177], v[100:103]
	v_mfma_f32_16x16x32_bf16 v[96:99], v[208:211], v[174:177], v[96:99]
	v_mfma_f32_16x16x32_bf16 v[84:87], v[198:201], v[182:185], v[84:87]
	v_mfma_f32_16x16x32_bf16 v[80:83], v[208:211], v[182:185], v[80:83]
	v_mfma_f32_16x16x32_bf16 v[68:71], v[198:201], v[190:193], v[68:71]
	v_mfma_f32_16x16x32_bf16 v[64:67], v[208:211], v[190:193], v[64:67]
	s_mov_b32 m0, s37
	v_lshl_add_u64 v[212:213], v[216:217], 0, s[0:1]
	s_barrier
	ds_read_b128 v[162:165], v144 offset:49152
	ds_read_b128 v[166:169], v144 offset:50176
	ds_read_b128 v[170:173], v144 offset:51200
	ds_read_b128 v[174:177], v144 offset:52224
	ds_read_b128 v[178:181], v144 offset:53248
	ds_read_b128 v[182:185], v144 offset:54272
	ds_read_b128 v[186:189], v144 offset:55296
	ds_read_b128 v[190:193], v144 offset:56320
	global_load_lds_dwordx4 v[212:213], off
	v_lshl_add_u64 v[212:213], v[218:219], 0, s[0:1]
	s_mov_b32 m0, s38
	s_nop 0
	global_load_lds_dwordx4 v[212:213], off
	s_barrier
	s_waitcnt lgkmcnt(0)
	s_waitcnt lgkmcnt(0)
	v_mfma_f32_16x16x32_bf16 v[60:63], v[146:149], v[162:165], v[60:63]
	v_mfma_f32_16x16x32_bf16 v[56:59], v[154:157], v[162:165], v[56:59]
	v_mfma_f32_16x16x32_bf16 v[44:47], v[146:149], v[170:173], v[44:47]
	v_mfma_f32_16x16x32_bf16 v[40:43], v[154:157], v[170:173], v[40:43]
	v_mfma_f32_16x16x32_bf16 v[28:31], v[146:149], v[178:181], v[28:31]
	v_mfma_f32_16x16x32_bf16 v[24:27], v[154:157], v[178:181], v[24:27]
	v_mfma_f32_16x16x32_bf16 v[12:15], v[146:149], v[186:189], v[12:15]
	v_mfma_f32_16x16x32_bf16 v[8:11], v[154:157], v[186:189], v[8:11]
	v_mfma_f32_16x16x32_bf16 v[60:63], v[150:153], v[166:169], v[60:63]
	v_mfma_f32_16x16x32_bf16 v[56:59], v[158:161], v[166:169], v[56:59]
	v_mfma_f32_16x16x32_bf16 v[44:47], v[150:153], v[174:177], v[44:47]
	v_mfma_f32_16x16x32_bf16 v[40:43], v[158:161], v[174:177], v[40:43]
	v_mfma_f32_16x16x32_bf16 v[28:31], v[150:153], v[182:185], v[28:31]
	v_mfma_f32_16x16x32_bf16 v[24:27], v[158:161], v[182:185], v[24:27]
	v_mfma_f32_16x16x32_bf16 v[12:15], v[150:153], v[190:193], v[12:15]
	v_mfma_f32_16x16x32_bf16 v[8:11], v[158:161], v[190:193], v[8:11]
	s_barrier
	s_add_u32 s22, s22, 0x80080
	s_addc_u32 s23, s23, 0
	s_add_i32 s24, s24, s29
	v_lshl_add_u64 v[146:147], s[22:23], 0, v[132:133]
	s_mov_b32 m0, s24
	s_nop 0
	global_load_lds_dwordx4 v[146:147], off
	v_lshl_add_u64 v[146:147], s[22:23], 0, v[128:129]
	s_add_i32 m0, s24, 0x2000
	s_nop 0
	global_load_lds_dwordx4 v[146:147], off
	s_waitcnt vmcnt(6)
	s_barrier
	v_mfma_f32_16x16x32_bf16 v[52:55], v[194:197], v[162:165], v[52:55]
	v_mfma_f32_16x16x32_bf16 v[48:51], v[204:207], v[162:165], v[48:51]
	v_mfma_f32_16x16x32_bf16 v[36:39], v[194:197], v[170:173], v[36:39]
	v_mfma_f32_16x16x32_bf16 v[32:35], v[204:207], v[170:173], v[32:35]
	v_mfma_f32_16x16x32_bf16 v[20:23], v[194:197], v[178:181], v[20:23]
	v_mfma_f32_16x16x32_bf16 v[16:19], v[204:207], v[178:181], v[16:19]
	v_mfma_f32_16x16x32_bf16 v[4:7], v[194:197], v[186:189], v[4:7]
	v_mfma_f32_16x16x32_bf16 v[0:3], v[204:207], v[186:189], v[0:3]
	v_mfma_f32_16x16x32_bf16 v[52:55], v[198:201], v[166:169], v[52:55]
	v_mfma_f32_16x16x32_bf16 v[48:51], v[208:211], v[166:169], v[48:51]
	v_mfma_f32_16x16x32_bf16 v[36:39], v[198:201], v[174:177], v[36:39]
	v_mfma_f32_16x16x32_bf16 v[32:35], v[208:211], v[174:177], v[32:35]
	v_mfma_f32_16x16x32_bf16 v[20:23], v[198:201], v[182:185], v[20:23]
	v_mfma_f32_16x16x32_bf16 v[16:19], v[208:211], v[182:185], v[16:19]
	v_mfma_f32_16x16x32_bf16 v[4:7], v[198:201], v[190:193], v[4:7]
	v_mfma_f32_16x16x32_bf16 v[0:3], v[208:211], v[190:193], v[0:3]
	s_add_u32 s20, s20, 0x100
	s_addc_u32 s21, s21, 0
	s_add_u32 s49, s49, 0x100
	s_addc_u32 s50, s50, 0
	s_cmp_ge_i32 s51, s33
	s_mov_b32 s22, s51
	s_barrier
	s_cbranch_scc0 .LBB0_1631
	s_branch .LBB0_1626

.LBB0_1687:
	s_or_b64 exec, exec, s[0:1]
	s_setprio 0
	s_waitcnt lgkmcnt(0)
	v_mov_b32_e32 v0, v202
	s_barrier
	v_readlane_b32 s8, v247, 6
	v_ashrrev_i32_e32 v32, 6, v202
	s_movk_i32 s12, 0x2400
	v_add_u32_e32 v97, s8, v32
	v_cmp_gt_i32_e32 vcc, s12, v97
	v_readlane_b32 s9, v247, 7
	s_and_saveexec_b64 s[0:1], vcc
	s_xor_b64 s[0:1], exec, s[0:1]
	s_cbranch_execz .LBB0_1726
	v_and_b32_e32 v96, 63, v0
	v_readlane_b32 s0, v248, 0
	v_or_b32_e32 v34, 0x100, v96
	v_or_b32_e32 v36, 0x140, v96
	v_or_b32_e32 v38, 0x180, v96
	v_or_b32_e32 v40, 0x1c0, v96
	v_lshlrev_b32_e32 v98, 4, v96
	v_readlane_b32 s6, v248, 6
	v_readlane_b32 s7, v248, 7
	v_lshlrev_b32_e32 v33, 4, v40
	v_lshlrev_b32_e32 v35, 4, v38
	v_lshlrev_b32_e32 v37, 4, v36
	v_lshlrev_b32_e32 v39, 4, v34
	s_nop 0
	global_load_dwordx4 v[0:3], v98, s[6:7] offset:3072
	global_load_dwordx4 v[4:7], v98, s[6:7] offset:2048
	global_load_dwordx4 v[8:11], v98, s[6:7] offset:1024
	global_load_dwordx4 v[12:15], v98, s[6:7]
	global_load_dwordx4 v[16:19], v33, s[6:7]
	global_load_dwordx4 v[20:23], v35, s[6:7]
	global_load_dwordx4 v[24:27], v37, s[6:7]
	global_load_dwordx4 v[28:31], v39, s[6:7]
	v_mbcnt_hi_u32_b32 v33, -1, v203
	v_and_b32_e32 v35, 64, v33
	v_add_u32_e32 v35, 64, v35
	v_xor_b32_e32 v37, 1, v33
	v_cmp_lt_i32_e32 vcc, v37, v35
	v_readlane_b32 s1, v248, 1
	v_mov_b32_e32 v99, 0
	v_cndmask_b32_e32 v37, v33, v37, vcc
	v_lshlrev_b32_e32 v184, 2, v37
	v_xor_b32_e32 v37, 2, v33
	v_cmp_lt_i32_e32 vcc, v37, v35
	v_readlane_b32 s0, v248, 50
	v_lshlrev_b32_e32 v42, 3, v96
	v_cndmask_b32_e32 v37, v33, v37, vcc
	v_lshlrev_b32_e32 v185, 2, v37
	v_xor_b32_e32 v37, 4, v33
	v_cmp_lt_i32_e32 vcc, v37, v35
	v_mov_b32_e32 v43, v99
	v_readlane_b32 s1, v248, 51
	v_cndmask_b32_e32 v37, v33, v37, vcc
	v_lshlrev_b32_e32 v186, 2, v37
	v_xor_b32_e32 v37, 8, v33
	v_cmp_lt_i32_e32 vcc, v37, v35
	v_lshl_add_u64 v[102:103], s[0:1], 0, v[42:43]
	s_ashr_i32 s9, s8, 31
	v_cndmask_b32_e32 v37, v33, v37, vcc
	v_lshlrev_b32_e32 v187, 2, v37
	v_xor_b32_e32 v37, 16, v33
	v_cmp_lt_i32_e32 vcc, v37, v35
	v_readlane_b32 s0, v248, 52
	v_readlane_b32 s1, v248, 53
	v_cndmask_b32_e32 v37, v33, v37, vcc
	v_lshlrev_b32_e32 v188, 2, v37
	v_xor_b32_e32 v37, 32, v33
	v_cmp_lt_i32_e32 vcc, v37, v35
	v_readlane_b32 s2, v248, 2
	v_readlane_b32 s3, v248, 3
	v_cndmask_b32_e32 v33, v33, v37, vcc
	v_lshlrev_b32_e32 v189, 2, v33
	v_ashrrev_i32_e32 v33, 31, v32
	v_lshl_add_u64 v[32:33], v[32:33], 0, s[8:9]
	v_readlane_b32 s4, v248, 4
	v_readlane_b32 s5, v248, 5
	v_lshlrev_b64 v[104:105], 12, v[32:33]
	s_ashr_i32 s1, s0, 31
	v_lshlrev_b64 v[106:107], 13, v[32:33]
	v_lshl_add_u64 v[100:101], s[56:57], 0, v[98:99]
	v_or_b32_e32 v104, v104, v42
	s_lshl_b64 s[2:3], s[0:1], 12
	v_or_b32_e32 v106, v106, v98
	s_mov_b32 s20, s0
	s_lshl_b64 s[4:5], s[0:1], 13
	s_mov_b64 s[6:7], 0
	s_mov_b32 s13, 0xe100000
	s_mov_b32 s14, 0x3c280000
	s_mov_b32 s15, 0x38e38e39
	v_lshlrev_b32_e32 v98, 4, v34
	v_lshlrev_b32_e32 v108, 4, v36
	v_lshlrev_b32_e32 v110, 4, v38
	v_lshlrev_b32_e32 v112, 4, v40
	v_mov_b32_e32 v190, 0x358637bd
	s_mov_b32 s16, 0x800000
	s_movk_i32 s17, 0x1000
	s_movk_i32 s18, 0x23ff
	s_branch .LBB0_1690
